# remove the duplicate s_waitcnt lgkmcnt(0) hipcc placed right after each hand-placed lgkmcnt(0) before the MFMA bursts in the GEMM K loops (102 sites)
# speedup vs baseline: 1.0405x; 1.0053x over previous
.LBB0_410:
	v_add_u32_e32 v168, s93, v167
	ds_read_b128 v[172:175], v168
	ds_read_b128 v[176:179], v168 offset:1024
	ds_read_b128 v[180:183], v168 offset:2048
	ds_read_b128 v[184:187], v168 offset:3072
	v_add_u32_e32 v169, 0xc000, v152
	v_lshl_add_u64 v[194:195], s[76:77], 0, v[142:143]
	v_readfirstlane_b32 s3, v169
	v_lshl_add_u64 v[170:171], v[194:195], 0, s[46:47]
	s_mov_b32 m0, s3
	ds_read_b128 v[188:191], v156
	ds_read_b128 v[196:199], v156 offset:1024
	ds_read_b128 v[200:203], v155
	ds_read_b128 v[204:207], v155 offset:1024
	ds_read_b128 v[208:211], v154
	ds_read_b128 v[212:215], v154 offset:1024
	ds_read_b128 v[216:219], v153
	ds_read_b128 v[220:223], v153 offset:1024
	global_load_lds_dwordx4 v[170:171], off
	v_add_u32_e32 v170, 0xe000, v152
	v_lshl_add_u64 v[240:241], s[76:77], 0, v[144:145]
	v_readfirstlane_b32 s3, v170
	v_lshl_add_u64 v[224:225], v[240:241], 0, s[46:47]
	s_mov_b32 m0, s3
	s_nop 0
	global_load_lds_dwordx4 v[224:225], off
	s_waitcnt lgkmcnt(8)
	s_barrier
	s_waitcnt lgkmcnt(0)
	s_setprio 1
	v_mfma_f32_16x16x32_bf16 v[124:127], v[188:191], v[172:175], v[124:127]
	v_mfma_f32_16x16x32_bf16 v[120:123], v[188:191], v[180:183], v[120:123]
	v_mfma_f32_16x16x32_bf16 v[116:119], v[200:203], v[172:175], v[116:119]
	v_mfma_f32_16x16x32_bf16 v[112:115], v[200:203], v[180:183], v[112:115]
	v_mfma_f32_16x16x32_bf16 v[108:111], v[208:211], v[172:175], v[108:111]
	v_mfma_f32_16x16x32_bf16 v[104:107], v[208:211], v[180:183], v[104:107]
	v_mfma_f32_16x16x32_bf16 v[100:103], v[216:219], v[172:175], v[100:103]
	v_mfma_f32_16x16x32_bf16 v[96:99], v[216:219], v[180:183], v[96:99]
	v_mfma_f32_16x16x32_bf16 v[124:127], v[196:199], v[176:179], v[124:127]
	v_mfma_f32_16x16x32_bf16 v[120:123], v[196:199], v[184:187], v[120:123]
	v_mfma_f32_16x16x32_bf16 v[116:119], v[204:207], v[176:179], v[116:119]
	v_mfma_f32_16x16x32_bf16 v[112:115], v[204:207], v[184:187], v[112:115]
	v_mfma_f32_16x16x32_bf16 v[108:111], v[212:215], v[176:179], v[108:111]
	v_mfma_f32_16x16x32_bf16 v[104:107], v[212:215], v[184:187], v[104:107]
	v_mfma_f32_16x16x32_bf16 v[100:103], v[220:223], v[176:179], v[100:103]
	v_mfma_f32_16x16x32_bf16 v[96:99], v[220:223], v[184:187], v[96:99]
	s_setprio 0
	s_barrier
	v_lshl_add_u64 v[244:245], s[76:77], 0, v[134:135]
	v_readfirstlane_b32 s3, v151
	v_add_u32_e32 v193, 0x2000, v151
	v_add_u32_e32 v171, s12, v167
	v_lshl_add_u64 v[242:243], v[244:245], 0, s[48:49]
	s_mov_b32 m0, s3
	v_lshl_add_u64 v[246:247], s[76:77], 0, v[136:137]
	v_readfirstlane_b32 s3, v193
	ds_read_b128 v[224:227], v171
	ds_read_b128 v[228:231], v171 offset:1024
	ds_read_b128 v[232:235], v171 offset:2048
	ds_read_b128 v[236:239], v171 offset:3072
	global_load_lds_dwordx4 v[242:243], off
	v_lshl_add_u64 v[242:243], v[246:247], 0, s[48:49]
	s_mov_b32 m0, s3
	s_nop 0
	global_load_lds_dwordx4 v[242:243], off
	s_barrier
	s_waitcnt lgkmcnt(0)
	s_setprio 1
	v_mfma_f32_16x16x32_bf16 v[92:95], v[188:191], v[224:227], v[92:95]
	v_mfma_f32_16x16x32_bf16 v[88:91], v[188:191], v[232:235], v[88:91]
	v_mfma_f32_16x16x32_bf16 v[84:87], v[200:203], v[224:227], v[84:87]
	v_mfma_f32_16x16x32_bf16 v[80:83], v[200:203], v[232:235], v[80:83]
	v_mfma_f32_16x16x32_bf16 v[76:79], v[208:211], v[224:227], v[76:79]
	v_mfma_f32_16x16x32_bf16 v[72:75], v[208:211], v[232:235], v[72:75]
	v_mfma_f32_16x16x32_bf16 v[68:71], v[216:219], v[224:227], v[68:71]
	v_mfma_f32_16x16x32_bf16 v[64:67], v[216:219], v[232:235], v[64:67]
	v_mfma_f32_16x16x32_bf16 v[92:95], v[196:199], v[228:231], v[92:95]
	v_mfma_f32_16x16x32_bf16 v[88:91], v[196:199], v[236:239], v[88:91]
	v_mfma_f32_16x16x32_bf16 v[84:87], v[204:207], v[228:231], v[84:87]
	v_mfma_f32_16x16x32_bf16 v[80:83], v[204:207], v[236:239], v[80:83]
	v_mfma_f32_16x16x32_bf16 v[76:79], v[212:215], v[228:231], v[76:79]
	v_mfma_f32_16x16x32_bf16 v[72:75], v[212:215], v[236:239], v[72:75]
	v_mfma_f32_16x16x32_bf16 v[68:71], v[220:223], v[228:231], v[68:71]
	v_mfma_f32_16x16x32_bf16 v[64:67], v[220:223], v[236:239], v[64:67]
	s_setprio 0
	v_lshl_add_u64 v[248:249], s[76:77], 0, v[138:139]
	v_readfirstlane_b32 s3, v152
	v_lshl_add_u64 v[242:243], v[248:249], 0, s[50:51]
	s_mov_b32 m0, s3
	v_lshl_add_u64 v[250:251], s[76:77], 0, v[140:141]
	v_readfirstlane_b32 s3, v157
	s_barrier
	ds_read_b128 v[188:191], v156 offset:16384
	ds_read_b128 v[196:199], v156 offset:17408
	ds_read_b128 v[200:203], v155 offset:16384
	ds_read_b128 v[204:207], v155 offset:17408
	ds_read_b128 v[208:211], v154 offset:16384
	ds_read_b128 v[212:215], v154 offset:17408
	ds_read_b128 v[216:219], v153 offset:16384
	ds_read_b128 v[220:223], v153 offset:17408
	global_load_lds_dwordx4 v[242:243], off
	v_lshl_add_u64 v[242:243], v[250:251], 0, s[50:51]
	s_mov_b32 m0, s3
	s_nop 0
	global_load_lds_dwordx4 v[242:243], off
	s_barrier
	s_waitcnt lgkmcnt(0)
	s_setprio 1
	v_mfma_f32_16x16x32_bf16 v[60:63], v[188:191], v[172:175], v[60:63]
	v_mfma_f32_16x16x32_bf16 v[56:59], v[188:191], v[180:183], v[56:59]
	v_mfma_f32_16x16x32_bf16 v[52:55], v[200:203], v[172:175], v[52:55]
	v_mfma_f32_16x16x32_bf16 v[48:51], v[200:203], v[180:183], v[48:51]
	v_mfma_f32_16x16x32_bf16 v[44:47], v[208:211], v[172:175], v[44:47]
	v_mfma_f32_16x16x32_bf16 v[40:43], v[208:211], v[180:183], v[40:43]
	v_mfma_f32_16x16x32_bf16 v[36:39], v[216:219], v[172:175], v[36:39]
	v_mfma_f32_16x16x32_bf16 v[32:35], v[216:219], v[180:183], v[32:35]
	v_mfma_f32_16x16x32_bf16 v[60:63], v[196:199], v[176:179], v[60:63]
	v_mfma_f32_16x16x32_bf16 v[56:59], v[196:199], v[184:187], v[56:59]
	v_mfma_f32_16x16x32_bf16 v[52:55], v[204:207], v[176:179], v[52:55]
	v_mfma_f32_16x16x32_bf16 v[48:51], v[204:207], v[184:187], v[48:51]
	v_mfma_f32_16x16x32_bf16 v[44:47], v[212:215], v[176:179], v[44:47]
	v_mfma_f32_16x16x32_bf16 v[40:43], v[212:215], v[184:187], v[40:43]
	v_mfma_f32_16x16x32_bf16 v[36:39], v[220:223], v[176:179], v[36:39]
	v_mfma_f32_16x16x32_bf16 v[32:35], v[220:223], v[184:187], v[32:35]
	s_setprio 0
	s_barrier
	v_readfirstlane_b32 s3, v158
	v_add_u32_e32 v174, 0x2000, v158
	v_lshl_add_u64 v[172:173], v[244:245], 0, s[52:53]
	s_mov_b32 m0, s3
	v_readfirstlane_b32 s3, v174
	global_load_lds_dwordx4 v[172:173], off
	v_lshl_add_u64 v[172:173], v[246:247], 0, s[52:53]
	s_mov_b32 m0, s3
	s_nop 0
	global_load_lds_dwordx4 v[172:173], off
	s_waitcnt vmcnt(6)
	s_barrier
	s_setprio 1
	v_mfma_f32_16x16x32_bf16 v[28:31], v[188:191], v[224:227], v[28:31]
	v_mfma_f32_16x16x32_bf16 v[24:27], v[188:191], v[232:235], v[24:27]
	v_mfma_f32_16x16x32_bf16 v[20:23], v[200:203], v[224:227], v[20:23]
	v_mfma_f32_16x16x32_bf16 v[16:19], v[200:203], v[232:235], v[16:19]
	v_mfma_f32_16x16x32_bf16 v[12:15], v[208:211], v[224:227], v[12:15]
	v_mfma_f32_16x16x32_bf16 v[8:11], v[208:211], v[232:235], v[8:11]
	v_mfma_f32_16x16x32_bf16 v[4:7], v[216:219], v[224:227], v[4:7]
	v_mfma_f32_16x16x32_bf16 v[0:3], v[216:219], v[232:235], v[0:3]
	v_mfma_f32_16x16x32_bf16 v[28:31], v[196:199], v[228:231], v[28:31]
	v_mfma_f32_16x16x32_bf16 v[24:27], v[196:199], v[236:239], v[24:27]
	v_mfma_f32_16x16x32_bf16 v[20:23], v[204:207], v[228:231], v[20:23]
	v_mfma_f32_16x16x32_bf16 v[16:19], v[204:207], v[236:239], v[16:19]
	v_mfma_f32_16x16x32_bf16 v[12:15], v[212:215], v[228:231], v[12:15]
	v_mfma_f32_16x16x32_bf16 v[8:11], v[212:215], v[236:239], v[8:11]
	v_mfma_f32_16x16x32_bf16 v[4:7], v[220:223], v[228:231], v[4:7]
	v_mfma_f32_16x16x32_bf16 v[0:3], v[220:223], v[236:239], v[0:3]
	s_setprio 0
	v_add_u32_e32 v172, s13, v167
	s_barrier
	ds_read_b128 v[174:177], v172
	ds_read_b128 v[178:181], v172 offset:1024
	ds_read_b128 v[182:185], v172 offset:2048
	ds_read_b128 v[186:189], v172 offset:3072
	v_readfirstlane_b32 s3, v159
	v_lshl_add_u64 v[190:191], v[194:195], 0, s[50:51]
	s_mov_b32 m0, s3
	v_readfirstlane_b32 s3, v160
	ds_read_b128 v[196:199], v156 offset:32768
	ds_read_b128 v[200:203], v156 offset:33792
	ds_read_b128 v[204:207], v155 offset:32768
	ds_read_b128 v[208:211], v155 offset:33792
	ds_read_b128 v[212:215], v154 offset:32768
	ds_read_b128 v[216:219], v154 offset:33792
	ds_read_b128 v[220:223], v153 offset:32768
	ds_read_b128 v[224:227], v153 offset:33792
	global_load_lds_dwordx4 v[190:191], off
	v_lshl_add_u64 v[190:191], v[240:241], 0, s[50:51]
	s_mov_b32 m0, s3
	s_nop 0
	global_load_lds_dwordx4 v[190:191], off
	s_waitcnt lgkmcnt(8)
	s_barrier
	s_waitcnt lgkmcnt(0)
	s_setprio 1
	v_mfma_f32_16x16x32_bf16 v[124:127], v[196:199], v[174:177], v[124:127]
	v_mfma_f32_16x16x32_bf16 v[120:123], v[196:199], v[182:185], v[120:123]
	v_mfma_f32_16x16x32_bf16 v[116:119], v[204:207], v[174:177], v[116:119]
	v_mfma_f32_16x16x32_bf16 v[112:115], v[204:207], v[182:185], v[112:115]
	v_mfma_f32_16x16x32_bf16 v[108:111], v[212:215], v[174:177], v[108:111]
	v_mfma_f32_16x16x32_bf16 v[104:107], v[212:215], v[182:185], v[104:107]
	v_mfma_f32_16x16x32_bf16 v[100:103], v[220:223], v[174:177], v[100:103]
	v_mfma_f32_16x16x32_bf16 v[96:99], v[220:223], v[182:185], v[96:99]
	v_mfma_f32_16x16x32_bf16 v[124:127], v[200:203], v[178:181], v[124:127]
	v_mfma_f32_16x16x32_bf16 v[120:123], v[200:203], v[186:189], v[120:123]
	v_mfma_f32_16x16x32_bf16 v[116:119], v[208:211], v[178:181], v[116:119]
	v_mfma_f32_16x16x32_bf16 v[112:115], v[208:211], v[186:189], v[112:115]
	v_mfma_f32_16x16x32_bf16 v[108:111], v[216:219], v[178:181], v[108:111]
	v_mfma_f32_16x16x32_bf16 v[104:107], v[216:219], v[186:189], v[104:107]
	v_mfma_f32_16x16x32_bf16 v[100:103], v[224:227], v[178:181], v[100:103]
	v_mfma_f32_16x16x32_bf16 v[96:99], v[224:227], v[186:189], v[96:99]
	s_setprio 0
	s_barrier
	v_readfirstlane_b32 s3, v161
	v_add_u32_e32 v173, s25, v167
	v_lshl_add_u64 v[190:191], v[244:245], 0, s[54:55]
	s_mov_b32 m0, s3
	v_readfirstlane_b32 s3, v162
	ds_read_b128 v[228:231], v173
	ds_read_b128 v[232:235], v173 offset:1024
	ds_read_b128 v[236:239], v173 offset:2048
	ds_read_b128 v[240:243], v173 offset:3072
	global_load_lds_dwordx4 v[190:191], off
	v_lshl_add_u64 v[190:191], v[246:247], 0, s[54:55]
	s_mov_b32 m0, s3
	s_nop 0
	global_load_lds_dwordx4 v[190:191], off
	s_barrier
	s_waitcnt lgkmcnt(0)
	s_setprio 1
	v_mfma_f32_16x16x32_bf16 v[92:95], v[196:199], v[228:231], v[92:95]
	v_mfma_f32_16x16x32_bf16 v[88:91], v[196:199], v[236:239], v[88:91]
	v_mfma_f32_16x16x32_bf16 v[84:87], v[204:207], v[228:231], v[84:87]
	v_mfma_f32_16x16x32_bf16 v[80:83], v[204:207], v[236:239], v[80:83]
	v_mfma_f32_16x16x32_bf16 v[76:79], v[212:215], v[228:231], v[76:79]
	v_mfma_f32_16x16x32_bf16 v[72:75], v[212:215], v[236:239], v[72:75]
	v_mfma_f32_16x16x32_bf16 v[68:71], v[220:223], v[228:231], v[68:71]
	v_mfma_f32_16x16x32_bf16 v[64:67], v[220:223], v[236:239], v[64:67]
	v_mfma_f32_16x16x32_bf16 v[92:95], v[200:203], v[232:235], v[92:95]
	v_mfma_f32_16x16x32_bf16 v[88:91], v[200:203], v[240:243], v[88:91]
	v_mfma_f32_16x16x32_bf16 v[84:87], v[208:211], v[232:235], v[84:87]
	v_mfma_f32_16x16x32_bf16 v[80:83], v[208:211], v[240:243], v[80:83]
	v_mfma_f32_16x16x32_bf16 v[76:79], v[216:219], v[232:235], v[76:79]
	v_mfma_f32_16x16x32_bf16 v[72:75], v[216:219], v[240:243], v[72:75]
	v_mfma_f32_16x16x32_bf16 v[68:71], v[224:227], v[232:235], v[68:71]
	v_mfma_f32_16x16x32_bf16 v[64:67], v[224:227], v[240:243], v[64:67]
	s_setprio 0
	v_readfirstlane_b32 s3, v163
	v_lshl_add_u64 v[190:191], v[248:249], 0, s[56:57]
	s_mov_b32 m0, s3
	v_readfirstlane_b32 s3, v164
	s_barrier
	ds_read_b128 v[196:199], v156 offset:49152
	ds_read_b128 v[200:203], v156 offset:50176
	ds_read_b128 v[204:207], v155 offset:49152
	ds_read_b128 v[208:211], v155 offset:50176
	ds_read_b128 v[212:215], v154 offset:49152
	ds_read_b128 v[216:219], v154 offset:50176
	ds_read_b128 v[220:223], v153 offset:49152
	ds_read_b128 v[224:227], v153 offset:50176
	global_load_lds_dwordx4 v[190:191], off
	v_lshl_add_u64 v[190:191], v[250:251], 0, s[56:57]
	s_mov_b32 m0, s3
	s_nop 0
	global_load_lds_dwordx4 v[190:191], off
	s_barrier
	s_waitcnt lgkmcnt(0)
	s_setprio 1
	v_mfma_f32_16x16x32_bf16 v[60:63], v[196:199], v[174:177], v[60:63]
	v_mfma_f32_16x16x32_bf16 v[56:59], v[196:199], v[182:185], v[56:59]
	v_mfma_f32_16x16x32_bf16 v[52:55], v[204:207], v[174:177], v[52:55]
	v_mfma_f32_16x16x32_bf16 v[48:51], v[204:207], v[182:185], v[48:51]
	v_mfma_f32_16x16x32_bf16 v[44:47], v[212:215], v[174:177], v[44:47]
	v_mfma_f32_16x16x32_bf16 v[40:43], v[212:215], v[182:185], v[40:43]
	v_mfma_f32_16x16x32_bf16 v[36:39], v[220:223], v[174:177], v[36:39]
	v_mfma_f32_16x16x32_bf16 v[32:35], v[220:223], v[182:185], v[32:35]
	v_mfma_f32_16x16x32_bf16 v[60:63], v[200:203], v[178:181], v[60:63]
	v_mfma_f32_16x16x32_bf16 v[56:59], v[200:203], v[186:189], v[56:59]
	v_mfma_f32_16x16x32_bf16 v[52:55], v[208:211], v[178:181], v[52:55]
	v_mfma_f32_16x16x32_bf16 v[48:51], v[208:211], v[186:189], v[48:51]
	v_mfma_f32_16x16x32_bf16 v[44:47], v[216:219], v[178:181], v[44:47]
	v_mfma_f32_16x16x32_bf16 v[40:43], v[216:219], v[186:189], v[40:43]
	v_mfma_f32_16x16x32_bf16 v[36:39], v[224:227], v[178:181], v[36:39]
	v_mfma_f32_16x16x32_bf16 v[32:35], v[224:227], v[186:189], v[32:35]
	s_setprio 0
	s_barrier
	v_readfirstlane_b32 s3, v165
	v_lshl_add_u64 v[174:175], v[244:245], 0, s[58:59]
	s_mov_b32 m0, s3
	v_readfirstlane_b32 s3, v166
	global_load_lds_dwordx4 v[174:175], off
	v_lshl_add_u64 v[174:175], v[246:247], 0, s[58:59]
	s_mov_b32 m0, s3
	s_nop 0
	global_load_lds_dwordx4 v[174:175], off
	s_waitcnt vmcnt(6)
	s_barrier
	s_setprio 1
	v_mfma_f32_16x16x32_bf16 v[28:31], v[196:199], v[228:231], v[28:31]
	v_mfma_f32_16x16x32_bf16 v[24:27], v[196:199], v[236:239], v[24:27]
	v_mfma_f32_16x16x32_bf16 v[20:23], v[204:207], v[228:231], v[20:23]
	v_mfma_f32_16x16x32_bf16 v[16:19], v[204:207], v[236:239], v[16:19]
	v_mfma_f32_16x16x32_bf16 v[12:15], v[212:215], v[228:231], v[12:15]
	v_mfma_f32_16x16x32_bf16 v[8:11], v[212:215], v[236:239], v[8:11]
	v_mfma_f32_16x16x32_bf16 v[4:7], v[220:223], v[228:231], v[4:7]
	v_mfma_f32_16x16x32_bf16 v[0:3], v[220:223], v[236:239], v[0:3]
	v_mfma_f32_16x16x32_bf16 v[28:31], v[200:203], v[232:235], v[28:31]
	v_mfma_f32_16x16x32_bf16 v[24:27], v[200:203], v[240:243], v[24:27]
	v_mfma_f32_16x16x32_bf16 v[20:23], v[208:211], v[232:235], v[20:23]
	v_mfma_f32_16x16x32_bf16 v[16:19], v[208:211], v[240:243], v[16:19]
	v_mfma_f32_16x16x32_bf16 v[12:15], v[216:219], v[232:235], v[12:15]
	v_mfma_f32_16x16x32_bf16 v[8:11], v[216:219], v[240:243], v[8:11]
	v_mfma_f32_16x16x32_bf16 v[4:7], v[224:227], v[232:235], v[4:7]
	v_mfma_f32_16x16x32_bf16 v[0:3], v[224:227], v[240:243], v[0:3]
	s_setprio 0
	s_add_i32 s2, s2, 2
	v_lshl_add_u64 v[134:135], v[134:135], 0, s[60:61]
	v_lshl_add_u64 v[136:137], v[136:137], 0, s[60:61]
	v_lshl_add_u64 v[138:139], v[138:139], 0, s[60:61]
	v_lshl_add_u64 v[140:141], v[140:141], 0, s[60:61]
	v_lshl_add_u64 v[142:143], v[142:143], 0, s[60:61]
	s_cmp_lt_u32 s2, 28
	v_lshl_add_u64 v[144:145], v[144:145], 0, s[60:61]
	s_barrier
	s_cbranch_scc1 .LBB0_410
	v_readfirstlane_b32 s2, v169
	v_lshl_add_u64 v[130:131], v[130:131], 0, s[62:63]
	s_mov_b32 m0, s2
	v_readfirstlane_b32 s2, v170
	ds_read_b128 v[134:137], v168
	ds_read_b128 v[138:141], v168 offset:1024
	ds_read_b128 v[142:145], v168 offset:2048
	ds_read_b128 v[158:161], v168 offset:3072
	ds_read_b128 v[162:165], v156
	ds_read_b128 v[174:177], v156 offset:1024
	ds_read_b128 v[178:181], v155
	ds_read_b128 v[182:185], v155 offset:1024
	ds_read_b128 v[186:189], v154
	ds_read_b128 v[196:199], v154 offset:1024
	ds_read_b128 v[200:203], v153
	ds_read_b128 v[204:207], v153 offset:1024
	global_load_lds_dwordx4 v[130:131], off
	v_lshl_add_u64 v[130:131], v[132:133], 0, s[62:63]
	s_mov_b32 m0, s2
	s_nop 0
	global_load_lds_dwordx4 v[130:131], off
	s_barrier
	s_waitcnt lgkmcnt(0)
	s_setprio 1
	v_mfma_f32_16x16x32_bf16 v[124:127], v[162:165], v[134:137], v[124:127]
	v_mfma_f32_16x16x32_bf16 v[120:123], v[162:165], v[142:145], v[120:123]
	v_mfma_f32_16x16x32_bf16 v[116:119], v[178:181], v[134:137], v[116:119]
	v_mfma_f32_16x16x32_bf16 v[112:115], v[178:181], v[142:145], v[112:115]
	v_mfma_f32_16x16x32_bf16 v[108:111], v[186:189], v[134:137], v[108:111]
	v_mfma_f32_16x16x32_bf16 v[104:107], v[186:189], v[142:145], v[104:107]
	v_mfma_f32_16x16x32_bf16 v[100:103], v[200:203], v[134:137], v[100:103]
	v_mfma_f32_16x16x32_bf16 v[96:99], v[200:203], v[142:145], v[96:99]
	v_mfma_f32_16x16x32_bf16 v[124:127], v[174:177], v[138:141], v[124:127]
	v_mfma_f32_16x16x32_bf16 v[120:123], v[174:177], v[158:161], v[120:123]
	v_mfma_f32_16x16x32_bf16 v[116:119], v[182:185], v[138:141], v[116:119]
	v_mfma_f32_16x16x32_bf16 v[112:115], v[182:185], v[158:161], v[112:115]
	v_mfma_f32_16x16x32_bf16 v[108:111], v[196:199], v[138:141], v[108:111]
	v_mfma_f32_16x16x32_bf16 v[104:107], v[196:199], v[158:161], v[104:107]
	v_mfma_f32_16x16x32_bf16 v[100:103], v[204:207], v[138:141], v[100:103]
	v_mfma_f32_16x16x32_bf16 v[96:99], v[204:207], v[158:161], v[96:99]
	s_setprio 0
	s_barrier
	ds_read_b128 v[130:133], v171
	ds_read_b128 v[166:169], v171 offset:1024
	ds_read_b128 v[208:211], v171 offset:2048
	ds_read_b128 v[212:215], v171 offset:3072
	s_barrier
	s_waitcnt lgkmcnt(0)
	s_setprio 1
	v_mfma_f32_16x16x32_bf16 v[92:95], v[162:165], v[130:133], v[92:95]
	v_mfma_f32_16x16x32_bf16 v[88:91], v[162:165], v[208:211], v[88:91]
	v_mfma_f32_16x16x32_bf16 v[84:87], v[178:181], v[130:133], v[84:87]
	v_mfma_f32_16x16x32_bf16 v[80:83], v[178:181], v[208:211], v[80:83]
	v_mfma_f32_16x16x32_bf16 v[76:79], v[186:189], v[130:133], v[76:79]
	v_mfma_f32_16x16x32_bf16 v[72:75], v[186:189], v[208:211], v[72:75]
	v_mfma_f32_16x16x32_bf16 v[68:71], v[200:203], v[130:133], v[68:71]
	v_mfma_f32_16x16x32_bf16 v[64:67], v[200:203], v[208:211], v[64:67]
	v_mfma_f32_16x16x32_bf16 v[92:95], v[174:177], v[166:169], v[92:95]
	v_mfma_f32_16x16x32_bf16 v[88:91], v[174:177], v[212:215], v[88:91]
	v_mfma_f32_16x16x32_bf16 v[84:87], v[182:185], v[166:169], v[84:87]
	v_mfma_f32_16x16x32_bf16 v[80:83], v[182:185], v[212:215], v[80:83]
	v_mfma_f32_16x16x32_bf16 v[76:79], v[196:199], v[166:169], v[76:79]
	v_mfma_f32_16x16x32_bf16 v[72:75], v[196:199], v[212:215], v[72:75]
	v_mfma_f32_16x16x32_bf16 v[68:71], v[204:207], v[166:169], v[68:71]
	v_mfma_f32_16x16x32_bf16 v[64:67], v[204:207], v[212:215], v[64:67]
	s_setprio 0
	s_barrier
	ds_read_b128 v[162:165], v156 offset:16384
	ds_read_b128 v[174:177], v156 offset:17408
	ds_read_b128 v[178:181], v155 offset:16384
	ds_read_b128 v[182:185], v155 offset:17408
	ds_read_b128 v[186:189], v154 offset:16384
	ds_read_b128 v[196:199], v154 offset:17408
	ds_read_b128 v[200:203], v153 offset:16384
	ds_read_b128 v[204:207], v153 offset:17408
	s_waitcnt vmcnt(4)
	s_barrier
	s_waitcnt lgkmcnt(0)
	s_setprio 1
	v_mfma_f32_16x16x32_bf16 v[60:63], v[162:165], v[134:137], v[60:63]
	v_mfma_f32_16x16x32_bf16 v[56:59], v[162:165], v[142:145], v[56:59]
	v_mfma_f32_16x16x32_bf16 v[52:55], v[178:181], v[134:137], v[52:55]
	v_mfma_f32_16x16x32_bf16 v[48:51], v[178:181], v[142:145], v[48:51]
	v_mfma_f32_16x16x32_bf16 v[44:47], v[186:189], v[134:137], v[44:47]
	v_mfma_f32_16x16x32_bf16 v[40:43], v[186:189], v[142:145], v[40:43]
	v_mfma_f32_16x16x32_bf16 v[36:39], v[200:203], v[134:137], v[36:39]
	v_mfma_f32_16x16x32_bf16 v[32:35], v[200:203], v[142:145], v[32:35]
	v_mfma_f32_16x16x32_bf16 v[60:63], v[174:177], v[138:141], v[60:63]
	v_mfma_f32_16x16x32_bf16 v[56:59], v[174:177], v[158:161], v[56:59]
	v_mfma_f32_16x16x32_bf16 v[52:55], v[182:185], v[138:141], v[52:55]
	v_mfma_f32_16x16x32_bf16 v[48:51], v[182:185], v[158:161], v[48:51]
	v_mfma_f32_16x16x32_bf16 v[44:47], v[196:199], v[138:141], v[44:47]
	v_mfma_f32_16x16x32_bf16 v[40:43], v[196:199], v[158:161], v[40:43]
	v_mfma_f32_16x16x32_bf16 v[36:39], v[204:207], v[138:141], v[36:39]
	v_mfma_f32_16x16x32_bf16 v[32:35], v[204:207], v[158:161], v[32:35]
	s_setprio 0
	s_setprio 1
	v_mfma_f32_16x16x32_bf16 v[28:31], v[162:165], v[130:133], v[28:31]
	v_mfma_f32_16x16x32_bf16 v[24:27], v[162:165], v[208:211], v[24:27]
	v_mfma_f32_16x16x32_bf16 v[20:23], v[178:181], v[130:133], v[20:23]
	v_mfma_f32_16x16x32_bf16 v[16:19], v[178:181], v[208:211], v[16:19]
	v_mfma_f32_16x16x32_bf16 v[12:15], v[186:189], v[130:133], v[12:15]
	v_mfma_f32_16x16x32_bf16 v[8:11], v[186:189], v[208:211], v[8:11]
	v_mfma_f32_16x16x32_bf16 v[4:7], v[200:203], v[130:133], v[4:7]
	v_mfma_f32_16x16x32_bf16 v[0:3], v[200:203], v[208:211], v[0:3]
	v_mfma_f32_16x16x32_bf16 v[28:31], v[174:177], v[166:169], v[28:31]
	v_mfma_f32_16x16x32_bf16 v[24:27], v[174:177], v[212:215], v[24:27]
	v_mfma_f32_16x16x32_bf16 v[20:23], v[182:185], v[166:169], v[20:23]
	v_mfma_f32_16x16x32_bf16 v[16:19], v[182:185], v[212:215], v[16:19]
	v_mfma_f32_16x16x32_bf16 v[12:15], v[196:199], v[166:169], v[12:15]
	v_mfma_f32_16x16x32_bf16 v[8:11], v[196:199], v[212:215], v[8:11]
	v_mfma_f32_16x16x32_bf16 v[4:7], v[204:207], v[166:169], v[4:7]
	v_mfma_f32_16x16x32_bf16 v[0:3], v[204:207], v[212:215], v[0:3]
	s_setprio 0
	s_barrier
	ds_read_b128 v[130:133], v172
	ds_read_b128 v[134:137], v172 offset:1024
	ds_read_b128 v[138:141], v172 offset:2048
	ds_read_b128 v[142:145], v172 offset:3072
	ds_read_b128 v[158:161], v156 offset:32768
	ds_read_b128 v[162:165], v156 offset:33792
	ds_read_b128 v[166:169], v155 offset:32768
	ds_read_b128 v[174:177], v155 offset:33792
	ds_read_b128 v[178:181], v154 offset:32768
	ds_read_b128 v[182:185], v154 offset:33792
	ds_read_b128 v[186:189], v153 offset:32768
	ds_read_b128 v[196:199], v153 offset:33792
	s_waitcnt vmcnt(2)
	s_barrier
	s_waitcnt lgkmcnt(0)
	s_setprio 1
	v_mfma_f32_16x16x32_bf16 v[124:127], v[158:161], v[130:133], v[124:127]
	v_mfma_f32_16x16x32_bf16 v[120:123], v[158:161], v[138:141], v[120:123]
	v_mfma_f32_16x16x32_bf16 v[116:119], v[166:169], v[130:133], v[116:119]
	v_mfma_f32_16x16x32_bf16 v[112:115], v[166:169], v[138:141], v[112:115]
	v_mfma_f32_16x16x32_bf16 v[108:111], v[178:181], v[130:133], v[108:111]
	v_mfma_f32_16x16x32_bf16 v[104:107], v[178:181], v[138:141], v[104:107]
	v_mfma_f32_16x16x32_bf16 v[100:103], v[186:189], v[130:133], v[100:103]
	v_mfma_f32_16x16x32_bf16 v[96:99], v[186:189], v[138:141], v[96:99]
	v_mfma_f32_16x16x32_bf16 v[124:127], v[162:165], v[134:137], v[124:127]
	v_mfma_f32_16x16x32_bf16 v[120:123], v[162:165], v[142:145], v[120:123]
	v_mfma_f32_16x16x32_bf16 v[116:119], v[174:177], v[134:137], v[116:119]
	v_mfma_f32_16x16x32_bf16 v[112:115], v[174:177], v[142:145], v[112:115]
	v_mfma_f32_16x16x32_bf16 v[108:111], v[182:185], v[134:137], v[108:111]
	v_mfma_f32_16x16x32_bf16 v[104:107], v[182:185], v[142:145], v[104:107]
	v_mfma_f32_16x16x32_bf16 v[100:103], v[196:199], v[134:137], v[100:103]
	v_mfma_f32_16x16x32_bf16 v[96:99], v[196:199], v[142:145], v[96:99]
	s_setprio 0
	s_barrier
	ds_read_b128 v[200:203], v173
	ds_read_b128 v[204:207], v173 offset:1024
	ds_read_b128 v[208:211], v173 offset:2048
	ds_read_b128 v[170:173], v173 offset:3072
	s_waitcnt vmcnt(0)
	s_barrier
	s_waitcnt lgkmcnt(0)
	s_setprio 1
	v_mfma_f32_16x16x32_bf16 v[92:95], v[158:161], v[200:203], v[92:95]
	v_mfma_f32_16x16x32_bf16 v[88:91], v[158:161], v[208:211], v[88:91]
	v_mfma_f32_16x16x32_bf16 v[84:87], v[166:169], v[200:203], v[84:87]
	v_mfma_f32_16x16x32_bf16 v[80:83], v[166:169], v[208:211], v[80:83]
	v_mfma_f32_16x16x32_bf16 v[76:79], v[178:181], v[200:203], v[76:79]
	v_mfma_f32_16x16x32_bf16 v[72:75], v[178:181], v[208:211], v[72:75]
	v_mfma_f32_16x16x32_bf16 v[68:71], v[186:189], v[200:203], v[68:71]
	v_mfma_f32_16x16x32_bf16 v[64:67], v[186:189], v[208:211], v[64:67]
	v_mfma_f32_16x16x32_bf16 v[92:95], v[162:165], v[204:207], v[92:95]
	v_mfma_f32_16x16x32_bf16 v[88:91], v[162:165], v[170:173], v[88:91]
	v_mfma_f32_16x16x32_bf16 v[84:87], v[174:177], v[204:207], v[84:87]
	v_mfma_f32_16x16x32_bf16 v[80:83], v[174:177], v[170:173], v[80:83]
	v_mfma_f32_16x16x32_bf16 v[76:79], v[182:185], v[204:207], v[76:79]
	v_mfma_f32_16x16x32_bf16 v[72:75], v[182:185], v[170:173], v[72:75]
	v_mfma_f32_16x16x32_bf16 v[68:71], v[196:199], v[204:207], v[68:71]
	v_mfma_f32_16x16x32_bf16 v[64:67], v[196:199], v[170:173], v[64:67]
	s_setprio 0
	s_barrier
	ds_read_b128 v[158:161], v156 offset:49152
	ds_read_b128 v[162:165], v156 offset:50176
	ds_read_b128 v[166:169], v155 offset:49152
	ds_read_b128 v[174:177], v155 offset:50176
	ds_read_b128 v[178:181], v154 offset:49152
	ds_read_b128 v[154:157], v154 offset:50176
	ds_read_b128 v[182:185], v153 offset:49152
	ds_read_b128 v[186:189], v153 offset:50176
	s_barrier
	s_waitcnt lgkmcnt(0)
	s_setprio 1
	v_mfma_f32_16x16x32_bf16 v[60:63], v[158:161], v[130:133], v[60:63]
	v_mfma_f32_16x16x32_bf16 v[56:59], v[158:161], v[138:141], v[56:59]
	v_mfma_f32_16x16x32_bf16 v[52:55], v[166:169], v[130:133], v[52:55]
	v_mfma_f32_16x16x32_bf16 v[48:51], v[166:169], v[138:141], v[48:51]
	v_mfma_f32_16x16x32_bf16 v[44:47], v[178:181], v[130:133], v[44:47]
	v_mfma_f32_16x16x32_bf16 v[40:43], v[178:181], v[138:141], v[40:43]
	v_mfma_f32_16x16x32_bf16 v[36:39], v[182:185], v[130:133], v[36:39]
	v_mfma_f32_16x16x32_bf16 v[32:35], v[182:185], v[138:141], v[32:35]
	v_mfma_f32_16x16x32_bf16 v[60:63], v[162:165], v[134:137], v[60:63]
	v_mfma_f32_16x16x32_bf16 v[56:59], v[162:165], v[142:145], v[56:59]
	v_mfma_f32_16x16x32_bf16 v[52:55], v[174:177], v[134:137], v[52:55]
	v_mfma_f32_16x16x32_bf16 v[48:51], v[174:177], v[142:145], v[48:51]
	v_mfma_f32_16x16x32_bf16 v[44:47], v[154:157], v[134:137], v[44:47]
	v_mfma_f32_16x16x32_bf16 v[40:43], v[154:157], v[142:145], v[40:43]
	v_mfma_f32_16x16x32_bf16 v[36:39], v[186:189], v[134:137], v[36:39]
	v_mfma_f32_16x16x32_bf16 v[32:35], v[186:189], v[142:145], v[32:35]
	s_setprio 0
	s_setprio 1
	v_mfma_f32_16x16x32_bf16 v[28:31], v[158:161], v[200:203], v[28:31]
	v_mfma_f32_16x16x32_bf16 v[24:27], v[158:161], v[208:211], v[24:27]
	v_mfma_f32_16x16x32_bf16 v[20:23], v[166:169], v[200:203], v[20:23]
	v_mfma_f32_16x16x32_bf16 v[16:19], v[166:169], v[208:211], v[16:19]
	v_mfma_f32_16x16x32_bf16 v[12:15], v[178:181], v[200:203], v[12:15]
	v_mfma_f32_16x16x32_bf16 v[8:11], v[178:181], v[208:211], v[8:11]
	v_mfma_f32_16x16x32_bf16 v[4:7], v[182:185], v[200:203], v[4:7]
	v_mfma_f32_16x16x32_bf16 v[0:3], v[182:185], v[208:211], v[0:3]
	v_mfma_f32_16x16x32_bf16 v[28:31], v[162:165], v[204:207], v[28:31]
	v_mfma_f32_16x16x32_bf16 v[24:27], v[162:165], v[170:173], v[24:27]
	v_mfma_f32_16x16x32_bf16 v[20:23], v[174:177], v[204:207], v[20:23]
	v_mfma_f32_16x16x32_bf16 v[16:19], v[174:177], v[170:173], v[16:19]
	v_mfma_f32_16x16x32_bf16 v[12:15], v[154:157], v[204:207], v[12:15]
	v_mfma_f32_16x16x32_bf16 v[8:11], v[154:157], v[170:173], v[8:11]
	v_mfma_f32_16x16x32_bf16 v[4:7], v[186:189], v[204:207], v[4:7]
	v_mfma_f32_16x16x32_bf16 v[0:3], v[186:189], v[170:173], v[0:3]
	s_setprio 0
	v_readlane_b32 s2, v253, 16
	v_readlane_b32 s3, v253, 17
	s_andn2_b64 vcc, exec, s[2:3]
	s_barrier
	s_cbranch_vccnz .LBB0_413
	s_barrier

.LBB0_546:
	v_add_u32_e32 v168, s93, v167
	ds_read_b128 v[172:175], v168
	ds_read_b128 v[176:179], v168 offset:1024
	ds_read_b128 v[180:183], v168 offset:2048
	ds_read_b128 v[184:187], v168 offset:3072
	v_add_u32_e32 v169, 0xc000, v156
	v_lshl_add_u64 v[240:241], s[76:77], 0, v[142:143]
	v_readfirstlane_b32 s2, v169
	v_lshl_add_u64 v[170:171], v[240:241], 0, s[66:67]
	s_mov_b32 m0, s2
	ds_read_b128 v[188:191], v155
	ds_read_b128 v[196:199], v155 offset:1024
	ds_read_b128 v[200:203], v154
	ds_read_b128 v[204:207], v154 offset:1024
	ds_read_b128 v[208:211], v153
	ds_read_b128 v[212:215], v153 offset:1024
	ds_read_b128 v[216:219], v152
	ds_read_b128 v[220:223], v152 offset:1024
	global_load_lds_dwordx4 v[170:171], off
	v_add_u32_e32 v170, 0xe000, v156
	v_lshl_add_u64 v[242:243], s[76:77], 0, v[144:145]
	v_readfirstlane_b32 s2, v170
	v_lshl_add_u64 v[224:225], v[242:243], 0, s[66:67]
	s_mov_b32 m0, s2
	s_nop 0
	global_load_lds_dwordx4 v[224:225], off
	s_waitcnt lgkmcnt(8)
	s_barrier
	s_waitcnt lgkmcnt(0)
	s_setprio 1
	v_mfma_f32_16x16x32_bf16 v[124:127], v[172:175], v[188:191], v[124:127]
	v_mfma_f32_16x16x32_bf16 v[120:123], v[180:183], v[188:191], v[120:123]
	v_mfma_f32_16x16x32_bf16 v[116:119], v[172:175], v[200:203], v[116:119]
	v_mfma_f32_16x16x32_bf16 v[112:115], v[180:183], v[200:203], v[112:115]
	v_mfma_f32_16x16x32_bf16 v[108:111], v[172:175], v[208:211], v[108:111]
	v_mfma_f32_16x16x32_bf16 v[104:107], v[180:183], v[208:211], v[104:107]
	v_mfma_f32_16x16x32_bf16 v[100:103], v[172:175], v[216:219], v[100:103]
	v_mfma_f32_16x16x32_bf16 v[96:99], v[180:183], v[216:219], v[96:99]
	v_mfma_f32_16x16x32_bf16 v[124:127], v[176:179], v[196:199], v[124:127]
	v_mfma_f32_16x16x32_bf16 v[120:123], v[184:187], v[196:199], v[120:123]
	v_mfma_f32_16x16x32_bf16 v[116:119], v[176:179], v[204:207], v[116:119]
	v_mfma_f32_16x16x32_bf16 v[112:115], v[184:187], v[204:207], v[112:115]
	v_mfma_f32_16x16x32_bf16 v[108:111], v[176:179], v[212:215], v[108:111]
	v_mfma_f32_16x16x32_bf16 v[104:107], v[184:187], v[212:215], v[104:107]
	v_mfma_f32_16x16x32_bf16 v[100:103], v[176:179], v[220:223], v[100:103]
	v_mfma_f32_16x16x32_bf16 v[96:99], v[184:187], v[220:223], v[96:99]
	s_setprio 0
	s_barrier
	v_lshl_add_u64 v[244:245], s[76:77], 0, v[134:135]
	v_readfirstlane_b32 s2, v151
	v_add_u32_e32 v171, s12, v167
	v_lshl_add_u64 v[246:247], v[244:245], 0, s[60:61]
	s_mov_b32 m0, s2
	v_add_u32_e32 v193, 0x2000, v151
	ds_read_b128 v[224:227], v171
	ds_read_b128 v[228:231], v171 offset:1024
	ds_read_b128 v[232:235], v171 offset:2048
	ds_read_b128 v[236:239], v171 offset:3072
	global_load_lds_dwordx4 v[246:247], off
	v_lshl_add_u64 v[246:247], s[76:77], 0, v[136:137]
	v_readfirstlane_b32 s2, v193
	v_lshl_add_u64 v[248:249], v[246:247], 0, s[60:61]
	s_mov_b32 m0, s2
	s_nop 0
	global_load_lds_dwordx4 v[248:249], off
	s_barrier
	s_waitcnt lgkmcnt(0)
	s_setprio 1
	v_mfma_f32_16x16x32_bf16 v[92:95], v[224:227], v[188:191], v[92:95]
	v_mfma_f32_16x16x32_bf16 v[88:91], v[232:235], v[188:191], v[88:91]
	v_mfma_f32_16x16x32_bf16 v[84:87], v[224:227], v[200:203], v[84:87]
	v_mfma_f32_16x16x32_bf16 v[80:83], v[232:235], v[200:203], v[80:83]
	v_mfma_f32_16x16x32_bf16 v[76:79], v[224:227], v[208:211], v[76:79]
	v_mfma_f32_16x16x32_bf16 v[72:75], v[232:235], v[208:211], v[72:75]
	v_mfma_f32_16x16x32_bf16 v[68:71], v[224:227], v[216:219], v[68:71]
	v_mfma_f32_16x16x32_bf16 v[64:67], v[232:235], v[216:219], v[64:67]
	v_mfma_f32_16x16x32_bf16 v[92:95], v[228:231], v[196:199], v[92:95]
	v_mfma_f32_16x16x32_bf16 v[88:91], v[236:239], v[196:199], v[88:91]
	v_mfma_f32_16x16x32_bf16 v[84:87], v[228:231], v[204:207], v[84:87]
	v_mfma_f32_16x16x32_bf16 v[80:83], v[236:239], v[204:207], v[80:83]
	v_mfma_f32_16x16x32_bf16 v[76:79], v[228:231], v[212:215], v[76:79]
	v_mfma_f32_16x16x32_bf16 v[72:75], v[236:239], v[212:215], v[72:75]
	v_mfma_f32_16x16x32_bf16 v[68:71], v[228:231], v[220:223], v[68:71]
	v_mfma_f32_16x16x32_bf16 v[64:67], v[236:239], v[220:223], v[64:67]
	s_setprio 0
	v_lshl_add_u64 v[248:249], s[76:77], 0, v[138:139]
	v_readfirstlane_b32 s2, v156
	v_lshl_add_u64 v[250:251], v[248:249], 0, s[68:69]
	s_mov_b32 m0, s2
	s_barrier
	ds_read_b128 v[188:191], v155 offset:16384
	ds_read_b128 v[196:199], v155 offset:17408
	ds_read_b128 v[200:203], v154 offset:16384
	ds_read_b128 v[204:207], v154 offset:17408
	ds_read_b128 v[208:211], v153 offset:16384
	ds_read_b128 v[212:215], v153 offset:17408
	ds_read_b128 v[216:219], v152 offset:16384
	ds_read_b128 v[220:223], v152 offset:17408
	global_load_lds_dwordx4 v[250:251], off
	v_lshl_add_u64 v[250:251], s[76:77], 0, v[140:141]
	v_readfirstlane_b32 s2, v157
	v_lshl_add_u64 v[194:195], v[250:251], 0, s[68:69]
	s_mov_b32 m0, s2
	s_nop 0
	global_load_lds_dwordx4 v[194:195], off
	s_barrier
	s_waitcnt lgkmcnt(0)
	s_setprio 1
	v_mfma_f32_16x16x32_bf16 v[60:63], v[172:175], v[188:191], v[60:63]
	v_mfma_f32_16x16x32_bf16 v[56:59], v[180:183], v[188:191], v[56:59]
	v_mfma_f32_16x16x32_bf16 v[52:55], v[172:175], v[200:203], v[52:55]
	v_mfma_f32_16x16x32_bf16 v[48:51], v[180:183], v[200:203], v[48:51]
	v_mfma_f32_16x16x32_bf16 v[44:47], v[172:175], v[208:211], v[44:47]
	v_mfma_f32_16x16x32_bf16 v[40:43], v[180:183], v[208:211], v[40:43]
	v_mfma_f32_16x16x32_bf16 v[36:39], v[172:175], v[216:219], v[36:39]
	v_mfma_f32_16x16x32_bf16 v[32:35], v[180:183], v[216:219], v[32:35]
	v_mfma_f32_16x16x32_bf16 v[60:63], v[176:179], v[196:199], v[60:63]
	v_mfma_f32_16x16x32_bf16 v[56:59], v[184:187], v[196:199], v[56:59]
	v_mfma_f32_16x16x32_bf16 v[52:55], v[176:179], v[204:207], v[52:55]
	v_mfma_f32_16x16x32_bf16 v[48:51], v[184:187], v[204:207], v[48:51]
	v_mfma_f32_16x16x32_bf16 v[44:47], v[176:179], v[212:215], v[44:47]
	v_mfma_f32_16x16x32_bf16 v[40:43], v[184:187], v[212:215], v[40:43]
	v_mfma_f32_16x16x32_bf16 v[36:39], v[176:179], v[220:223], v[36:39]
	v_mfma_f32_16x16x32_bf16 v[32:35], v[184:187], v[220:223], v[32:35]
	s_setprio 0
	s_barrier
	v_readfirstlane_b32 s2, v158
	v_add_u32_e32 v174, 0x2000, v158
	v_lshl_add_u64 v[172:173], v[244:245], 0, s[70:71]
	s_mov_b32 m0, s2
	v_readfirstlane_b32 s2, v174
	global_load_lds_dwordx4 v[172:173], off
	v_lshl_add_u64 v[172:173], v[246:247], 0, s[70:71]
	s_mov_b32 m0, s2
	s_nop 0
	global_load_lds_dwordx4 v[172:173], off
	s_waitcnt vmcnt(6)
	s_barrier
	s_setprio 1
	v_mfma_f32_16x16x32_bf16 v[28:31], v[224:227], v[188:191], v[28:31]
	v_mfma_f32_16x16x32_bf16 v[24:27], v[232:235], v[188:191], v[24:27]
	v_mfma_f32_16x16x32_bf16 v[20:23], v[224:227], v[200:203], v[20:23]
	v_mfma_f32_16x16x32_bf16 v[16:19], v[232:235], v[200:203], v[16:19]
	v_mfma_f32_16x16x32_bf16 v[12:15], v[224:227], v[208:211], v[12:15]
	v_mfma_f32_16x16x32_bf16 v[8:11], v[232:235], v[208:211], v[8:11]
	v_mfma_f32_16x16x32_bf16 v[4:7], v[224:227], v[216:219], v[4:7]
	v_mfma_f32_16x16x32_bf16 v[0:3], v[232:235], v[216:219], v[0:3]
	v_mfma_f32_16x16x32_bf16 v[28:31], v[228:231], v[196:199], v[28:31]
	v_mfma_f32_16x16x32_bf16 v[24:27], v[236:239], v[196:199], v[24:27]
	v_mfma_f32_16x16x32_bf16 v[20:23], v[228:231], v[204:207], v[20:23]
	v_mfma_f32_16x16x32_bf16 v[16:19], v[236:239], v[204:207], v[16:19]
	v_mfma_f32_16x16x32_bf16 v[12:15], v[228:231], v[212:215], v[12:15]
	v_mfma_f32_16x16x32_bf16 v[8:11], v[236:239], v[212:215], v[8:11]
	v_mfma_f32_16x16x32_bf16 v[4:7], v[228:231], v[220:223], v[4:7]
	v_mfma_f32_16x16x32_bf16 v[0:3], v[236:239], v[220:223], v[0:3]
	s_setprio 0
	v_add_u32_e32 v172, s13, v167
	s_barrier
	ds_read_b128 v[174:177], v172
	ds_read_b128 v[178:181], v172 offset:1024
	ds_read_b128 v[182:185], v172 offset:2048
	ds_read_b128 v[186:189], v172 offset:3072
	v_readfirstlane_b32 s2, v159
	v_lshl_add_u64 v[190:191], v[240:241], 0, s[68:69]
	s_mov_b32 m0, s2
	v_readfirstlane_b32 s2, v160
	ds_read_b128 v[196:199], v155 offset:32768
	ds_read_b128 v[200:203], v155 offset:33792
	ds_read_b128 v[204:207], v154 offset:32768
	ds_read_b128 v[208:211], v154 offset:33792
	ds_read_b128 v[212:215], v153 offset:32768
	ds_read_b128 v[216:219], v153 offset:33792
	ds_read_b128 v[220:223], v152 offset:32768
	ds_read_b128 v[224:227], v152 offset:33792
	global_load_lds_dwordx4 v[190:191], off
	v_lshl_add_u64 v[190:191], v[242:243], 0, s[68:69]
	s_mov_b32 m0, s2
	s_nop 0
	global_load_lds_dwordx4 v[190:191], off
	s_waitcnt lgkmcnt(8)
	s_barrier
	s_waitcnt lgkmcnt(0)
	s_setprio 1
	v_mfma_f32_16x16x32_bf16 v[124:127], v[174:177], v[196:199], v[124:127]
	v_mfma_f32_16x16x32_bf16 v[120:123], v[182:185], v[196:199], v[120:123]
	v_mfma_f32_16x16x32_bf16 v[116:119], v[174:177], v[204:207], v[116:119]
	v_mfma_f32_16x16x32_bf16 v[112:115], v[182:185], v[204:207], v[112:115]
	v_mfma_f32_16x16x32_bf16 v[108:111], v[174:177], v[212:215], v[108:111]
	v_mfma_f32_16x16x32_bf16 v[104:107], v[182:185], v[212:215], v[104:107]
	v_mfma_f32_16x16x32_bf16 v[100:103], v[174:177], v[220:223], v[100:103]
	v_mfma_f32_16x16x32_bf16 v[96:99], v[182:185], v[220:223], v[96:99]
	v_mfma_f32_16x16x32_bf16 v[124:127], v[178:181], v[200:203], v[124:127]
	v_mfma_f32_16x16x32_bf16 v[120:123], v[186:189], v[200:203], v[120:123]
	v_mfma_f32_16x16x32_bf16 v[116:119], v[178:181], v[208:211], v[116:119]
	v_mfma_f32_16x16x32_bf16 v[112:115], v[186:189], v[208:211], v[112:115]
	v_mfma_f32_16x16x32_bf16 v[108:111], v[178:181], v[216:219], v[108:111]
	v_mfma_f32_16x16x32_bf16 v[104:107], v[186:189], v[216:219], v[104:107]
	v_mfma_f32_16x16x32_bf16 v[100:103], v[178:181], v[224:227], v[100:103]
	v_mfma_f32_16x16x32_bf16 v[96:99], v[186:189], v[224:227], v[96:99]
	s_setprio 0
	s_barrier
	v_readfirstlane_b32 s2, v161
	v_add_u32_e32 v173, s25, v167
	v_lshl_add_u64 v[190:191], v[244:245], 0, s[72:73]
	s_mov_b32 m0, s2
	v_readfirstlane_b32 s2, v162
	ds_read_b128 v[228:231], v173
	ds_read_b128 v[232:235], v173 offset:1024
	ds_read_b128 v[236:239], v173 offset:2048
	ds_read_b128 v[240:243], v173 offset:3072
	global_load_lds_dwordx4 v[190:191], off
	v_lshl_add_u64 v[190:191], v[246:247], 0, s[72:73]
	s_mov_b32 m0, s2
	s_nop 0
	global_load_lds_dwordx4 v[190:191], off
	s_barrier
	s_waitcnt lgkmcnt(0)
	s_setprio 1
	v_mfma_f32_16x16x32_bf16 v[92:95], v[228:231], v[196:199], v[92:95]
	v_mfma_f32_16x16x32_bf16 v[88:91], v[236:239], v[196:199], v[88:91]
	v_mfma_f32_16x16x32_bf16 v[84:87], v[228:231], v[204:207], v[84:87]
	v_mfma_f32_16x16x32_bf16 v[80:83], v[236:239], v[204:207], v[80:83]
	v_mfma_f32_16x16x32_bf16 v[76:79], v[228:231], v[212:215], v[76:79]
	v_mfma_f32_16x16x32_bf16 v[72:75], v[236:239], v[212:215], v[72:75]
	v_mfma_f32_16x16x32_bf16 v[68:71], v[228:231], v[220:223], v[68:71]
	v_mfma_f32_16x16x32_bf16 v[64:67], v[236:239], v[220:223], v[64:67]
	v_mfma_f32_16x16x32_bf16 v[92:95], v[232:235], v[200:203], v[92:95]
	v_mfma_f32_16x16x32_bf16 v[88:91], v[240:243], v[200:203], v[88:91]
	v_mfma_f32_16x16x32_bf16 v[84:87], v[232:235], v[208:211], v[84:87]
	v_mfma_f32_16x16x32_bf16 v[80:83], v[240:243], v[208:211], v[80:83]
	v_mfma_f32_16x16x32_bf16 v[76:79], v[232:235], v[216:219], v[76:79]
	v_mfma_f32_16x16x32_bf16 v[72:75], v[240:243], v[216:219], v[72:75]
	v_mfma_f32_16x16x32_bf16 v[68:71], v[232:235], v[224:227], v[68:71]
	v_mfma_f32_16x16x32_bf16 v[64:67], v[240:243], v[224:227], v[64:67]
	s_setprio 0
	v_readfirstlane_b32 s2, v163
	v_lshl_add_u64 v[190:191], v[248:249], 0, s[74:75]
	s_mov_b32 m0, s2
	v_readfirstlane_b32 s2, v164
	s_barrier
	ds_read_b128 v[196:199], v155 offset:49152
	ds_read_b128 v[200:203], v155 offset:50176
	ds_read_b128 v[204:207], v154 offset:49152
	ds_read_b128 v[208:211], v154 offset:50176
	ds_read_b128 v[212:215], v153 offset:49152
	ds_read_b128 v[216:219], v153 offset:50176
	ds_read_b128 v[220:223], v152 offset:49152
	ds_read_b128 v[224:227], v152 offset:50176
	global_load_lds_dwordx4 v[190:191], off
	v_lshl_add_u64 v[190:191], v[250:251], 0, s[74:75]
	s_mov_b32 m0, s2
	s_nop 0
	global_load_lds_dwordx4 v[190:191], off
	s_barrier
	s_waitcnt lgkmcnt(0)
	s_setprio 1
	v_mfma_f32_16x16x32_bf16 v[60:63], v[174:177], v[196:199], v[60:63]
	v_mfma_f32_16x16x32_bf16 v[56:59], v[182:185], v[196:199], v[56:59]
	v_mfma_f32_16x16x32_bf16 v[52:55], v[174:177], v[204:207], v[52:55]
	v_mfma_f32_16x16x32_bf16 v[48:51], v[182:185], v[204:207], v[48:51]
	v_mfma_f32_16x16x32_bf16 v[44:47], v[174:177], v[212:215], v[44:47]
	v_mfma_f32_16x16x32_bf16 v[40:43], v[182:185], v[212:215], v[40:43]
	v_mfma_f32_16x16x32_bf16 v[36:39], v[174:177], v[220:223], v[36:39]
	v_mfma_f32_16x16x32_bf16 v[32:35], v[182:185], v[220:223], v[32:35]
	v_mfma_f32_16x16x32_bf16 v[60:63], v[178:181], v[200:203], v[60:63]
	v_mfma_f32_16x16x32_bf16 v[56:59], v[186:189], v[200:203], v[56:59]
	v_mfma_f32_16x16x32_bf16 v[52:55], v[178:181], v[208:211], v[52:55]
	v_mfma_f32_16x16x32_bf16 v[48:51], v[186:189], v[208:211], v[48:51]
	v_mfma_f32_16x16x32_bf16 v[44:47], v[178:181], v[216:219], v[44:47]
	v_mfma_f32_16x16x32_bf16 v[40:43], v[186:189], v[216:219], v[40:43]
	v_mfma_f32_16x16x32_bf16 v[36:39], v[178:181], v[224:227], v[36:39]
	v_mfma_f32_16x16x32_bf16 v[32:35], v[186:189], v[224:227], v[32:35]
	s_setprio 0
	s_barrier
	v_readfirstlane_b32 s2, v165
	v_lshl_add_u64 v[174:175], v[244:245], 0, s[8:9]
	s_mov_b32 m0, s2
	v_readfirstlane_b32 s2, v166
	global_load_lds_dwordx4 v[174:175], off
	v_lshl_add_u64 v[174:175], v[246:247], 0, s[8:9]
	s_mov_b32 m0, s2
	s_nop 0
	global_load_lds_dwordx4 v[174:175], off
	s_waitcnt vmcnt(6)
	s_barrier
	s_setprio 1
	v_mfma_f32_16x16x32_bf16 v[28:31], v[228:231], v[196:199], v[28:31]
	v_mfma_f32_16x16x32_bf16 v[24:27], v[236:239], v[196:199], v[24:27]
	v_mfma_f32_16x16x32_bf16 v[20:23], v[228:231], v[204:207], v[20:23]
	v_mfma_f32_16x16x32_bf16 v[16:19], v[236:239], v[204:207], v[16:19]
	v_mfma_f32_16x16x32_bf16 v[12:15], v[228:231], v[212:215], v[12:15]
	v_mfma_f32_16x16x32_bf16 v[8:11], v[236:239], v[212:215], v[8:11]
	v_mfma_f32_16x16x32_bf16 v[4:7], v[228:231], v[220:223], v[4:7]
	v_mfma_f32_16x16x32_bf16 v[0:3], v[236:239], v[220:223], v[0:3]
	v_mfma_f32_16x16x32_bf16 v[28:31], v[232:235], v[200:203], v[28:31]
	v_mfma_f32_16x16x32_bf16 v[24:27], v[240:243], v[200:203], v[24:27]
	v_mfma_f32_16x16x32_bf16 v[20:23], v[232:235], v[208:211], v[20:23]
	v_mfma_f32_16x16x32_bf16 v[16:19], v[240:243], v[208:211], v[16:19]
	v_mfma_f32_16x16x32_bf16 v[12:15], v[232:235], v[216:219], v[12:15]
	v_mfma_f32_16x16x32_bf16 v[8:11], v[240:243], v[216:219], v[8:11]
	v_mfma_f32_16x16x32_bf16 v[4:7], v[232:235], v[224:227], v[4:7]
	v_mfma_f32_16x16x32_bf16 v[0:3], v[240:243], v[224:227], v[0:3]
	s_setprio 0
	s_add_i32 s1, s1, 2
	v_lshl_add_u64 v[134:135], v[134:135], 0, s[60:61]
	v_lshl_add_u64 v[136:137], v[136:137], 0, s[60:61]
	v_lshl_add_u64 v[138:139], v[138:139], 0, s[60:61]
	v_lshl_add_u64 v[140:141], v[140:141], 0, s[60:61]
	v_lshl_add_u64 v[142:143], v[142:143], 0, s[60:61]
	s_cmp_lt_u32 s1, 28
	v_lshl_add_u64 v[144:145], v[144:145], 0, s[60:61]
	s_barrier
	s_cbranch_scc1 .LBB0_546
	v_readfirstlane_b32 s1, v169
	v_lshl_add_u64 v[130:131], v[130:131], 0, s[62:63]
	s_mov_b32 m0, s1
	v_readfirstlane_b32 s1, v170
	ds_read_b128 v[134:137], v168
	ds_read_b128 v[138:141], v168 offset:1024
	ds_read_b128 v[142:145], v168 offset:2048
	ds_read_b128 v[156:159], v168 offset:3072
	ds_read_b128 v[160:163], v155
	ds_read_b128 v[164:167], v155 offset:1024
	ds_read_b128 v[174:177], v154
	ds_read_b128 v[178:181], v154 offset:1024
	ds_read_b128 v[182:185], v153
	ds_read_b128 v[186:189], v153 offset:1024
	ds_read_b128 v[196:199], v152
	ds_read_b128 v[200:203], v152 offset:1024
	global_load_lds_dwordx4 v[130:131], off
	v_lshl_add_u64 v[130:131], v[132:133], 0, s[62:63]
	s_mov_b32 m0, s1
	s_nop 0
	global_load_lds_dwordx4 v[130:131], off
	s_barrier
	s_waitcnt lgkmcnt(0)
	s_setprio 1
	v_mfma_f32_16x16x32_bf16 v[124:127], v[134:137], v[160:163], v[124:127]
	v_mfma_f32_16x16x32_bf16 v[116:119], v[134:137], v[174:177], v[116:119]
	v_mfma_f32_16x16x32_bf16 v[108:111], v[134:137], v[182:185], v[108:111]
	v_mfma_f32_16x16x32_bf16 v[100:103], v[134:137], v[196:199], v[100:103]
	v_mfma_f32_16x16x32_bf16 v[124:127], v[138:141], v[164:167], v[124:127]
	v_mfma_f32_16x16x32_bf16 v[120:123], v[142:145], v[160:163], v[120:123]
	v_mfma_f32_16x16x32_bf16 v[116:119], v[138:141], v[178:181], v[116:119]
	v_mfma_f32_16x16x32_bf16 v[112:115], v[142:145], v[174:177], v[112:115]
	v_mfma_f32_16x16x32_bf16 v[108:111], v[138:141], v[186:189], v[108:111]
	v_mfma_f32_16x16x32_bf16 v[104:107], v[142:145], v[182:185], v[104:107]
	v_mfma_f32_16x16x32_bf16 v[100:103], v[138:141], v[200:203], v[100:103]
	v_mfma_f32_16x16x32_bf16 v[96:99], v[142:145], v[196:199], v[96:99]
	v_mfma_f32_16x16x32_bf16 v[130:133], v[156:159], v[164:167], v[120:123]
	v_mfma_f32_16x16x32_bf16 v[204:207], v[156:159], v[178:181], v[112:115]
	v_mfma_f32_16x16x32_bf16 v[208:211], v[156:159], v[186:189], v[104:107]
	v_mfma_f32_16x16x32_bf16 v[212:215], v[156:159], v[200:203], v[96:99]
	s_setprio 0
	s_barrier
	s_nop 1
	ds_read_b128 v[96:99], v171
	ds_read_b128 v[104:107], v171 offset:1024
	ds_read_b128 v[112:115], v171 offset:2048
	ds_read_b128 v[120:123], v171 offset:3072
	s_barrier
	s_waitcnt lgkmcnt(0)
	s_setprio 1
	v_mfma_f32_16x16x32_bf16 v[92:95], v[96:99], v[160:163], v[92:95]
	v_mfma_f32_16x16x32_bf16 v[84:87], v[96:99], v[174:177], v[84:87]
	v_mfma_f32_16x16x32_bf16 v[76:79], v[96:99], v[182:185], v[76:79]
	v_mfma_f32_16x16x32_bf16 v[68:71], v[96:99], v[196:199], v[68:71]
	v_mfma_f32_16x16x32_bf16 v[64:67], v[112:115], v[196:199], v[64:67]
	v_mfma_f32_16x16x32_bf16 v[92:95], v[104:107], v[164:167], v[92:95]
	v_mfma_f32_16x16x32_bf16 v[88:91], v[112:115], v[160:163], v[88:91]
	v_mfma_f32_16x16x32_bf16 v[84:87], v[104:107], v[178:181], v[84:87]
	v_mfma_f32_16x16x32_bf16 v[80:83], v[112:115], v[174:177], v[80:83]
	v_mfma_f32_16x16x32_bf16 v[76:79], v[104:107], v[186:189], v[76:79]
	v_mfma_f32_16x16x32_bf16 v[72:75], v[112:115], v[182:185], v[72:75]
	v_mfma_f32_16x16x32_bf16 v[68:71], v[104:107], v[200:203], v[68:71]
	v_mfma_f32_16x16x32_bf16 v[64:67], v[120:123], v[200:203], v[64:67]
	v_mfma_f32_16x16x32_bf16 v[160:163], v[120:123], v[164:167], v[88:91]
	v_mfma_f32_16x16x32_bf16 v[164:167], v[120:123], v[178:181], v[80:83]
	v_mfma_f32_16x16x32_bf16 v[168:171], v[120:123], v[186:189], v[72:75]
	s_setprio 0
	s_barrier
	s_nop 0
	ds_read_b128 v[72:75], v155 offset:16384
	ds_read_b128 v[80:83], v155 offset:17408
	ds_read_b128 v[88:91], v154 offset:16384
	ds_read_b128 v[174:177], v154 offset:17408
	ds_read_b128 v[178:181], v153 offset:16384
	ds_read_b128 v[182:185], v153 offset:17408
	ds_read_b128 v[186:189], v152 offset:16384
	ds_read_b128 v[196:199], v152 offset:17408
	s_waitcnt vmcnt(4)
	s_barrier
	s_waitcnt lgkmcnt(0)
	s_setprio 1
	v_mfma_f32_16x16x32_bf16 v[52:55], v[134:137], v[88:91], v[52:55]
	v_mfma_f32_16x16x32_bf16 v[44:47], v[134:137], v[178:181], v[44:47]
	v_mfma_f32_16x16x32_bf16 v[36:39], v[134:137], v[186:189], v[36:39]
	v_mfma_f32_16x16x32_bf16 v[60:63], v[134:137], v[72:75], v[60:63]
	v_mfma_f32_16x16x32_bf16 v[56:59], v[142:145], v[72:75], v[56:59]
	v_mfma_f32_16x16x32_bf16 v[52:55], v[138:141], v[174:177], v[52:55]
	v_mfma_f32_16x16x32_bf16 v[48:51], v[142:145], v[88:91], v[48:51]
	v_mfma_f32_16x16x32_bf16 v[44:47], v[138:141], v[182:185], v[44:47]
	v_mfma_f32_16x16x32_bf16 v[40:43], v[142:145], v[178:181], v[40:43]
	v_mfma_f32_16x16x32_bf16 v[36:39], v[138:141], v[196:199], v[36:39]
	v_mfma_f32_16x16x32_bf16 v[32:35], v[142:145], v[186:189], v[32:35]
	v_mfma_f32_16x16x32_bf16 v[200:203], v[138:141], v[80:83], v[60:63]
	v_mfma_f32_16x16x32_bf16 v[216:219], v[156:159], v[80:83], v[56:59]
	v_mfma_f32_16x16x32_bf16 v[220:223], v[156:159], v[174:177], v[48:51]
	v_mfma_f32_16x16x32_bf16 v[224:227], v[156:159], v[182:185], v[40:43]
	v_mfma_f32_16x16x32_bf16 v[134:137], v[156:159], v[196:199], v[32:35]
	s_setprio 0
	s_setprio 1
	v_mfma_f32_16x16x32_bf16 v[28:31], v[96:99], v[72:75], v[28:31]
	v_mfma_f32_16x16x32_bf16 v[20:23], v[96:99], v[88:91], v[20:23]
	v_mfma_f32_16x16x32_bf16 v[12:15], v[96:99], v[178:181], v[12:15]
	v_mfma_f32_16x16x32_bf16 v[4:7], v[96:99], v[186:189], v[4:7]
	v_mfma_f32_16x16x32_bf16 v[28:31], v[104:107], v[80:83], v[28:31]
	v_mfma_f32_16x16x32_bf16 v[24:27], v[112:115], v[72:75], v[24:27]
	v_mfma_f32_16x16x32_bf16 v[20:23], v[104:107], v[174:177], v[20:23]
	v_mfma_f32_16x16x32_bf16 v[16:19], v[112:115], v[88:91], v[16:19]
	v_mfma_f32_16x16x32_bf16 v[12:15], v[104:107], v[182:185], v[12:15]
	v_mfma_f32_16x16x32_bf16 v[8:11], v[112:115], v[178:181], v[8:11]
	v_mfma_f32_16x16x32_bf16 v[4:7], v[104:107], v[196:199], v[4:7]
	v_mfma_f32_16x16x32_bf16 v[0:3], v[112:115], v[186:189], v[0:3]
	v_mfma_f32_16x16x32_bf16 v[138:141], v[120:123], v[80:83], v[24:27]
	v_mfma_f32_16x16x32_bf16 v[142:145], v[120:123], v[174:177], v[16:19]
	v_mfma_f32_16x16x32_bf16 v[156:159], v[120:123], v[182:185], v[8:11]
	v_mfma_f32_16x16x32_bf16 v[174:177], v[120:123], v[196:199], v[0:3]
	s_setprio 0
	s_barrier
	s_nop 1
	ds_read_b128 v[0:3], v172
	ds_read_b128 v[8:11], v172 offset:1024
	ds_read_b128 v[16:19], v172 offset:2048
	ds_read_b128 v[24:27], v172 offset:3072
	ds_read_b128 v[32:35], v155 offset:32768
	ds_read_b128 v[40:43], v155 offset:33792
	ds_read_b128 v[48:51], v154 offset:32768
	ds_read_b128 v[56:59], v154 offset:33792
	ds_read_b128 v[60:63], v153 offset:32768
	ds_read_b128 v[178:181], v153 offset:33792
	ds_read_b128 v[182:185], v152 offset:32768
	ds_read_b128 v[186:189], v152 offset:33792
	s_waitcnt vmcnt(2)
	s_barrier
	s_waitcnt lgkmcnt(0)
	s_setprio 1
	v_mfma_f32_16x16x32_bf16 v[72:75], v[0:3], v[32:35], v[124:127]
	v_mfma_f32_16x16x32_bf16 v[120:123], v[8:11], v[40:43], v[72:75]
	v_mfma_f32_16x16x32_bf16 v[72:75], v[16:19], v[32:35], v[130:133]
	v_mfma_f32_16x16x32_bf16 v[124:127], v[24:27], v[40:43], v[72:75]
	v_mfma_f32_16x16x32_bf16 v[72:75], v[0:3], v[48:51], v[116:119]
	v_mfma_f32_16x16x32_bf16 v[112:115], v[8:11], v[56:59], v[72:75]
	v_mfma_f32_16x16x32_bf16 v[72:75], v[16:19], v[48:51], v[204:207]
	v_mfma_f32_16x16x32_bf16 v[116:119], v[24:27], v[56:59], v[72:75]
	v_mfma_f32_16x16x32_bf16 v[72:75], v[0:3], v[60:63], v[108:111]
	v_mfma_f32_16x16x32_bf16 v[104:107], v[8:11], v[178:181], v[72:75]
	v_mfma_f32_16x16x32_bf16 v[72:75], v[16:19], v[60:63], v[208:211]
	v_mfma_f32_16x16x32_bf16 v[108:111], v[24:27], v[178:181], v[72:75]
	v_mfma_f32_16x16x32_bf16 v[72:75], v[0:3], v[182:185], v[100:103]
	v_mfma_f32_16x16x32_bf16 v[96:99], v[8:11], v[186:189], v[72:75]
	v_mfma_f32_16x16x32_bf16 v[72:75], v[16:19], v[182:185], v[212:215]
	v_mfma_f32_16x16x32_bf16 v[100:103], v[24:27], v[186:189], v[72:75]
	s_setprio 0
	s_barrier
	ds_read_b128 v[130:133], v173
	ds_read_b128 v[196:199], v173 offset:1024
	ds_read_b128 v[204:207], v173 offset:2048
	ds_read_b128 v[208:211], v173 offset:3072
	s_waitcnt vmcnt(0)
	s_barrier
	s_waitcnt lgkmcnt(0)
	s_setprio 1
	v_mfma_f32_16x16x32_bf16 v[72:75], v[130:133], v[32:35], v[92:95]
	v_mfma_f32_16x16x32_bf16 v[32:35], v[204:207], v[32:35], v[160:163]
	v_mfma_f32_16x16x32_bf16 v[92:95], v[208:211], v[40:43], v[32:35]
	v_mfma_f32_16x16x32_bf16 v[32:35], v[130:133], v[48:51], v[84:87]
	v_mfma_f32_16x16x32_bf16 v[80:83], v[196:199], v[56:59], v[32:35]
	v_mfma_f32_16x16x32_bf16 v[32:35], v[204:207], v[48:51], v[164:167]
	v_mfma_f32_16x16x32_bf16 v[84:87], v[208:211], v[56:59], v[32:35]
	v_mfma_f32_16x16x32_bf16 v[32:35], v[130:133], v[60:63], v[76:79]
	v_mfma_f32_16x16x32_bf16 v[88:91], v[196:199], v[40:43], v[72:75]
	v_mfma_f32_16x16x32_bf16 v[72:75], v[196:199], v[178:181], v[32:35]
	v_mfma_f32_16x16x32_bf16 v[32:35], v[204:207], v[60:63], v[168:171]
	v_mfma_f32_16x16x32_bf16 v[76:79], v[208:211], v[178:181], v[32:35]
	v_mfma_f32_16x16x32_bf16 v[32:35], v[130:133], v[182:185], v[68:71]
	v_mfma_f32_16x16x32_bf16 v[56:59], v[196:199], v[186:189], v[32:35]
	v_mfma_f32_16x16x32_bf16 v[32:35], v[204:207], v[182:185], v[64:67]
	v_mfma_f32_16x16x32_bf16 v[60:63], v[208:211], v[186:189], v[32:35]
	s_setprio 0
	s_barrier
	ds_read_b128 v[160:163], v155 offset:49152
	ds_read_b128 v[164:167], v155 offset:50176
	ds_read_b128 v[168:171], v154 offset:49152
	ds_read_b128 v[178:181], v154 offset:50176
	ds_read_b128 v[182:185], v153 offset:49152
	ds_read_b128 v[186:189], v153 offset:50176
	ds_read_b128 v[212:215], v152 offset:49152
	ds_read_b128 v[152:155], v152 offset:50176
	s_barrier
	s_waitcnt lgkmcnt(0)
	s_setprio 1
	v_mfma_f32_16x16x32_bf16 v[32:35], v[0:3], v[160:163], v[200:203]
	v_mfma_f32_16x16x32_bf16 v[64:67], v[8:11], v[164:167], v[32:35]
	v_mfma_f32_16x16x32_bf16 v[32:35], v[16:19], v[160:163], v[216:219]
	v_mfma_f32_16x16x32_bf16 v[68:71], v[24:27], v[164:167], v[32:35]
	v_mfma_f32_16x16x32_bf16 v[32:35], v[0:3], v[168:171], v[52:55]
	v_mfma_f32_16x16x32_bf16 v[48:51], v[8:11], v[178:181], v[32:35]
	v_mfma_f32_16x16x32_bf16 v[32:35], v[16:19], v[168:171], v[220:223]
	v_mfma_f32_16x16x32_bf16 v[52:55], v[24:27], v[178:181], v[32:35]
	v_mfma_f32_16x16x32_bf16 v[32:35], v[0:3], v[182:185], v[44:47]
	v_mfma_f32_16x16x32_bf16 v[40:43], v[8:11], v[186:189], v[32:35]
	v_mfma_f32_16x16x32_bf16 v[32:35], v[16:19], v[182:185], v[224:227]
	v_mfma_f32_16x16x32_bf16 v[0:3], v[0:3], v[212:215], v[36:39]
	v_mfma_f32_16x16x32_bf16 v[44:47], v[24:27], v[186:189], v[32:35]
	v_mfma_f32_16x16x32_bf16 v[32:35], v[8:11], v[152:155], v[0:3]
	v_mfma_f32_16x16x32_bf16 v[0:3], v[16:19], v[212:215], v[134:137]
	v_mfma_f32_16x16x32_bf16 v[36:39], v[24:27], v[152:155], v[0:3]
	s_setprio 0
	s_setprio 1
	v_mfma_f32_16x16x32_bf16 v[0:3], v[130:133], v[160:163], v[28:31]
	v_mfma_f32_16x16x32_bf16 v[24:27], v[196:199], v[164:167], v[0:3]
	v_mfma_f32_16x16x32_bf16 v[0:3], v[204:207], v[160:163], v[138:141]
	v_mfma_f32_16x16x32_bf16 v[28:31], v[208:211], v[164:167], v[0:3]
	v_mfma_f32_16x16x32_bf16 v[0:3], v[130:133], v[168:171], v[20:23]
	v_mfma_f32_16x16x32_bf16 v[16:19], v[196:199], v[178:181], v[0:3]
	v_mfma_f32_16x16x32_bf16 v[0:3], v[204:207], v[168:171], v[142:145]
	v_mfma_f32_16x16x32_bf16 v[20:23], v[208:211], v[178:181], v[0:3]
	v_mfma_f32_16x16x32_bf16 v[0:3], v[130:133], v[182:185], v[12:15]
	v_mfma_f32_16x16x32_bf16 v[8:11], v[196:199], v[186:189], v[0:3]
	v_mfma_f32_16x16x32_bf16 v[0:3], v[204:207], v[182:185], v[156:159]
	v_mfma_f32_16x16x32_bf16 v[12:15], v[208:211], v[186:189], v[0:3]
	v_mfma_f32_16x16x32_bf16 v[0:3], v[130:133], v[212:215], v[4:7]
	v_mfma_f32_16x16x32_bf16 v[4:7], v[204:207], v[212:215], v[174:177]
	v_mfma_f32_16x16x32_bf16 v[0:3], v[196:199], v[152:155], v[0:3]
	v_mfma_f32_16x16x32_bf16 v[4:7], v[208:211], v[152:155], v[4:7]
	s_setprio 0
	v_readlane_b32 s2, v253, 16
	v_readlane_b32 s3, v253, 17
	s_andn2_b64 vcc, exec, s[2:3]
	s_barrier
	s_cbranch_vccnz .LBB0_404
	s_barrier
	s_branch .LBB0_404

.LBB0_605:
	v_add_u32_e32 v164, s26, v163
	ds_read_b128 v[168:171], v164
	ds_read_b128 v[172:175], v164 offset:1024
	ds_read_b128 v[176:179], v164 offset:2048
	ds_read_b128 v[180:183], v164 offset:3072
	v_add_u32_e32 v165, 0xc000, v149
	v_lshl_add_u64 v[194:195], s[76:77], 0, v[140:141]
	v_readfirstlane_b32 s24, v165
	v_lshl_add_u64 v[166:167], v[194:195], 0, s[2:3]
	s_mov_b32 m0, s24
	ds_read_b128 v[184:187], v152
	ds_read_b128 v[188:191], v152 offset:1024
	ds_read_b128 v[196:199], v151
	ds_read_b128 v[200:203], v151 offset:1024
	ds_read_b128 v[204:207], v150
	ds_read_b128 v[208:211], v150 offset:1024
	ds_read_b128 v[212:215], v148
	ds_read_b128 v[216:219], v148 offset:1024
	global_load_lds_dwordx4 v[166:167], off
	v_add_u32_e32 v166, 0xe000, v149
	v_lshl_add_u64 v[236:237], s[76:77], 0, v[142:143]
	v_readfirstlane_b32 s24, v166
	v_lshl_add_u64 v[192:193], v[236:237], 0, s[2:3]
	s_mov_b32 m0, s24
	s_nop 0
	global_load_lds_dwordx4 v[192:193], off
	s_waitcnt lgkmcnt(8)
	s_barrier
	s_waitcnt lgkmcnt(0)
	s_setprio 1
	v_mfma_f32_16x16x32_bf16 v[124:127], v[168:171], v[184:187], v[124:127]
	v_mfma_f32_16x16x32_bf16 v[120:123], v[176:179], v[184:187], v[120:123]
	v_mfma_f32_16x16x32_bf16 v[116:119], v[168:171], v[196:199], v[116:119]
	v_mfma_f32_16x16x32_bf16 v[112:115], v[176:179], v[196:199], v[112:115]
	v_mfma_f32_16x16x32_bf16 v[108:111], v[168:171], v[204:207], v[108:111]
	v_mfma_f32_16x16x32_bf16 v[104:107], v[176:179], v[204:207], v[104:107]
	v_mfma_f32_16x16x32_bf16 v[100:103], v[168:171], v[212:215], v[100:103]
	v_mfma_f32_16x16x32_bf16 v[96:99], v[176:179], v[212:215], v[96:99]
	v_mfma_f32_16x16x32_bf16 v[124:127], v[172:175], v[188:191], v[124:127]
	v_mfma_f32_16x16x32_bf16 v[120:123], v[180:183], v[188:191], v[120:123]
	v_mfma_f32_16x16x32_bf16 v[116:119], v[172:175], v[200:203], v[116:119]
	v_mfma_f32_16x16x32_bf16 v[112:115], v[180:183], v[200:203], v[112:115]
	v_mfma_f32_16x16x32_bf16 v[108:111], v[172:175], v[208:211], v[108:111]
	v_mfma_f32_16x16x32_bf16 v[104:107], v[180:183], v[208:211], v[104:107]
	v_mfma_f32_16x16x32_bf16 v[100:103], v[172:175], v[216:219], v[100:103]
	v_mfma_f32_16x16x32_bf16 v[96:99], v[180:183], v[216:219], v[96:99]
	s_setprio 0
	s_barrier
	v_lshl_add_u64 v[238:239], s[76:77], 0, v[132:133]
	v_readfirstlane_b32 s24, v147
	v_add_u32_e32 v242, 0x2000, v147
	v_add_u32_e32 v167, s36, v163
	v_lshl_add_u64 v[192:193], v[238:239], 0, s[66:67]
	s_mov_b32 m0, s24
	v_lshl_add_u64 v[240:241], s[76:77], 0, v[134:135]
	v_readfirstlane_b32 s24, v242
	ds_read_b128 v[220:223], v167
	ds_read_b128 v[224:227], v167 offset:1024
	ds_read_b128 v[228:231], v167 offset:2048
	ds_read_b128 v[232:235], v167 offset:3072
	global_load_lds_dwordx4 v[192:193], off
	v_lshl_add_u64 v[192:193], v[240:241], 0, s[66:67]
	s_mov_b32 m0, s24
	s_nop 0
	global_load_lds_dwordx4 v[192:193], off
	s_barrier
	s_waitcnt lgkmcnt(0)
	s_setprio 1
	v_mfma_f32_16x16x32_bf16 v[92:95], v[220:223], v[184:187], v[92:95]
	v_mfma_f32_16x16x32_bf16 v[88:91], v[228:231], v[184:187], v[88:91]
	v_mfma_f32_16x16x32_bf16 v[84:87], v[220:223], v[196:199], v[84:87]
	v_mfma_f32_16x16x32_bf16 v[80:83], v[228:231], v[196:199], v[80:83]
	v_mfma_f32_16x16x32_bf16 v[76:79], v[220:223], v[204:207], v[76:79]
	v_mfma_f32_16x16x32_bf16 v[72:75], v[228:231], v[204:207], v[72:75]
	v_mfma_f32_16x16x32_bf16 v[68:71], v[220:223], v[212:215], v[68:71]
	v_mfma_f32_16x16x32_bf16 v[64:67], v[228:231], v[212:215], v[64:67]
	v_mfma_f32_16x16x32_bf16 v[92:95], v[224:227], v[188:191], v[92:95]
	v_mfma_f32_16x16x32_bf16 v[88:91], v[232:235], v[188:191], v[88:91]
	v_mfma_f32_16x16x32_bf16 v[84:87], v[224:227], v[200:203], v[84:87]
	v_mfma_f32_16x16x32_bf16 v[80:83], v[232:235], v[200:203], v[80:83]
	v_mfma_f32_16x16x32_bf16 v[76:79], v[224:227], v[208:211], v[76:79]
	v_mfma_f32_16x16x32_bf16 v[72:75], v[232:235], v[208:211], v[72:75]
	v_mfma_f32_16x16x32_bf16 v[68:71], v[224:227], v[216:219], v[68:71]
	v_mfma_f32_16x16x32_bf16 v[64:67], v[232:235], v[216:219], v[64:67]
	s_setprio 0
	v_lshl_add_u64 v[242:243], s[76:77], 0, v[136:137]
	v_readfirstlane_b32 s24, v149
	v_lshl_add_u64 v[192:193], v[242:243], 0, s[68:69]
	s_mov_b32 m0, s24
	v_lshl_add_u64 v[244:245], s[76:77], 0, v[138:139]
	v_readfirstlane_b32 s24, v153
	s_barrier
	ds_read_b128 v[184:187], v152 offset:16384
	ds_read_b128 v[188:191], v152 offset:17408
	ds_read_b128 v[196:199], v151 offset:16384
	ds_read_b128 v[200:203], v151 offset:17408
	ds_read_b128 v[204:207], v150 offset:16384
	ds_read_b128 v[208:211], v150 offset:17408
	ds_read_b128 v[212:215], v148 offset:16384
	ds_read_b128 v[216:219], v148 offset:17408
	global_load_lds_dwordx4 v[192:193], off
	v_lshl_add_u64 v[192:193], v[244:245], 0, s[68:69]
	s_mov_b32 m0, s24
	s_nop 0
	global_load_lds_dwordx4 v[192:193], off
	s_barrier
	s_waitcnt lgkmcnt(0)
	s_setprio 1
	v_mfma_f32_16x16x32_bf16 v[60:63], v[168:171], v[184:187], v[60:63]
	v_mfma_f32_16x16x32_bf16 v[56:59], v[176:179], v[184:187], v[56:59]
	v_mfma_f32_16x16x32_bf16 v[52:55], v[168:171], v[196:199], v[52:55]
	v_mfma_f32_16x16x32_bf16 v[48:51], v[176:179], v[196:199], v[48:51]
	v_mfma_f32_16x16x32_bf16 v[44:47], v[168:171], v[204:207], v[44:47]
	v_mfma_f32_16x16x32_bf16 v[40:43], v[176:179], v[204:207], v[40:43]
	v_mfma_f32_16x16x32_bf16 v[36:39], v[168:171], v[212:215], v[36:39]
	v_mfma_f32_16x16x32_bf16 v[32:35], v[176:179], v[212:215], v[32:35]
	v_mfma_f32_16x16x32_bf16 v[60:63], v[172:175], v[188:191], v[60:63]
	v_mfma_f32_16x16x32_bf16 v[56:59], v[180:183], v[188:191], v[56:59]
	v_mfma_f32_16x16x32_bf16 v[52:55], v[172:175], v[200:203], v[52:55]
	v_mfma_f32_16x16x32_bf16 v[48:51], v[180:183], v[200:203], v[48:51]
	v_mfma_f32_16x16x32_bf16 v[44:47], v[172:175], v[208:211], v[44:47]
	v_mfma_f32_16x16x32_bf16 v[40:43], v[180:183], v[208:211], v[40:43]
	v_mfma_f32_16x16x32_bf16 v[36:39], v[172:175], v[216:219], v[36:39]
	v_mfma_f32_16x16x32_bf16 v[32:35], v[180:183], v[216:219], v[32:35]
	s_setprio 0
	s_barrier
	v_readfirstlane_b32 s24, v154
	v_add_u32_e32 v170, 0x2000, v154
	v_lshl_add_u64 v[168:169], v[238:239], 0, s[70:71]
	s_mov_b32 m0, s24
	v_readfirstlane_b32 s24, v170
	global_load_lds_dwordx4 v[168:169], off
	v_lshl_add_u64 v[168:169], v[240:241], 0, s[70:71]
	s_mov_b32 m0, s24
	s_nop 0
	global_load_lds_dwordx4 v[168:169], off
	s_waitcnt vmcnt(6)
	s_barrier
	s_setprio 1
	v_mfma_f32_16x16x32_bf16 v[28:31], v[220:223], v[184:187], v[28:31]
	v_mfma_f32_16x16x32_bf16 v[24:27], v[228:231], v[184:187], v[24:27]
	v_mfma_f32_16x16x32_bf16 v[20:23], v[220:223], v[196:199], v[20:23]
	v_mfma_f32_16x16x32_bf16 v[16:19], v[228:231], v[196:199], v[16:19]
	v_mfma_f32_16x16x32_bf16 v[12:15], v[220:223], v[204:207], v[12:15]
	v_mfma_f32_16x16x32_bf16 v[8:11], v[228:231], v[204:207], v[8:11]
	v_mfma_f32_16x16x32_bf16 v[4:7], v[220:223], v[212:215], v[4:7]
	v_mfma_f32_16x16x32_bf16 v[0:3], v[228:231], v[212:215], v[0:3]
	v_mfma_f32_16x16x32_bf16 v[28:31], v[224:227], v[188:191], v[28:31]
	v_mfma_f32_16x16x32_bf16 v[24:27], v[232:235], v[188:191], v[24:27]
	v_mfma_f32_16x16x32_bf16 v[20:23], v[224:227], v[200:203], v[20:23]
	v_mfma_f32_16x16x32_bf16 v[16:19], v[232:235], v[200:203], v[16:19]
	v_mfma_f32_16x16x32_bf16 v[12:15], v[224:227], v[208:211], v[12:15]
	v_mfma_f32_16x16x32_bf16 v[8:11], v[232:235], v[208:211], v[8:11]
	v_mfma_f32_16x16x32_bf16 v[4:7], v[224:227], v[216:219], v[4:7]
	v_mfma_f32_16x16x32_bf16 v[0:3], v[232:235], v[216:219], v[0:3]
	s_setprio 0
	v_add_u32_e32 v168, s37, v163
	s_barrier
	ds_read_b128 v[170:173], v168
	ds_read_b128 v[174:177], v168 offset:1024
	ds_read_b128 v[178:181], v168 offset:2048
	ds_read_b128 v[182:185], v168 offset:3072
	v_readfirstlane_b32 s24, v155
	v_lshl_add_u64 v[194:195], v[194:195], 0, s[68:69]
	s_mov_b32 m0, s24
	v_readfirstlane_b32 s24, v156
	ds_read_b128 v[186:189], v152 offset:32768
	ds_read_b128 v[190:193], v152 offset:33792
	ds_read_b128 v[196:199], v151 offset:32768
	ds_read_b128 v[200:203], v151 offset:33792
	ds_read_b128 v[204:207], v150 offset:32768
	ds_read_b128 v[208:211], v150 offset:33792
	ds_read_b128 v[212:215], v148 offset:32768
	ds_read_b128 v[216:219], v148 offset:33792
	global_load_lds_dwordx4 v[194:195], off
	v_lshl_add_u64 v[194:195], v[236:237], 0, s[68:69]
	s_mov_b32 m0, s24
	s_nop 0
	global_load_lds_dwordx4 v[194:195], off
	s_waitcnt lgkmcnt(8)
	s_barrier
	s_waitcnt lgkmcnt(0)
	s_setprio 1
	v_mfma_f32_16x16x32_bf16 v[124:127], v[170:173], v[186:189], v[124:127]
	v_mfma_f32_16x16x32_bf16 v[120:123], v[178:181], v[186:189], v[120:123]
	v_mfma_f32_16x16x32_bf16 v[116:119], v[170:173], v[196:199], v[116:119]
	v_mfma_f32_16x16x32_bf16 v[112:115], v[178:181], v[196:199], v[112:115]
	v_mfma_f32_16x16x32_bf16 v[108:111], v[170:173], v[204:207], v[108:111]
	v_mfma_f32_16x16x32_bf16 v[104:107], v[178:181], v[204:207], v[104:107]
	v_mfma_f32_16x16x32_bf16 v[100:103], v[170:173], v[212:215], v[100:103]
	v_mfma_f32_16x16x32_bf16 v[96:99], v[178:181], v[212:215], v[96:99]
	v_mfma_f32_16x16x32_bf16 v[124:127], v[174:177], v[190:193], v[124:127]
	v_mfma_f32_16x16x32_bf16 v[120:123], v[182:185], v[190:193], v[120:123]
	v_mfma_f32_16x16x32_bf16 v[116:119], v[174:177], v[200:203], v[116:119]
	v_mfma_f32_16x16x32_bf16 v[112:115], v[182:185], v[200:203], v[112:115]
	v_mfma_f32_16x16x32_bf16 v[108:111], v[174:177], v[208:211], v[108:111]
	v_mfma_f32_16x16x32_bf16 v[104:107], v[182:185], v[208:211], v[104:107]
	v_mfma_f32_16x16x32_bf16 v[100:103], v[174:177], v[216:219], v[100:103]
	v_mfma_f32_16x16x32_bf16 v[96:99], v[182:185], v[216:219], v[96:99]
	s_setprio 0
	s_barrier
	v_readfirstlane_b32 s24, v157
	v_add_u32_e32 v169, s50, v163
	v_lshl_add_u64 v[194:195], v[238:239], 0, s[72:73]
	s_mov_b32 m0, s24
	v_readfirstlane_b32 s24, v158
	ds_read_b128 v[220:223], v169
	ds_read_b128 v[224:227], v169 offset:1024
	ds_read_b128 v[228:231], v169 offset:2048
	ds_read_b128 v[232:235], v169 offset:3072
	global_load_lds_dwordx4 v[194:195], off
	v_lshl_add_u64 v[194:195], v[240:241], 0, s[72:73]
	s_mov_b32 m0, s24
	s_nop 0
	global_load_lds_dwordx4 v[194:195], off
	s_barrier
	s_waitcnt lgkmcnt(0)
	s_setprio 1
	v_mfma_f32_16x16x32_bf16 v[92:95], v[220:223], v[186:189], v[92:95]
	v_mfma_f32_16x16x32_bf16 v[88:91], v[228:231], v[186:189], v[88:91]
	v_mfma_f32_16x16x32_bf16 v[84:87], v[220:223], v[196:199], v[84:87]
	v_mfma_f32_16x16x32_bf16 v[80:83], v[228:231], v[196:199], v[80:83]
	v_mfma_f32_16x16x32_bf16 v[76:79], v[220:223], v[204:207], v[76:79]
	v_mfma_f32_16x16x32_bf16 v[72:75], v[228:231], v[204:207], v[72:75]
	v_mfma_f32_16x16x32_bf16 v[68:71], v[220:223], v[212:215], v[68:71]
	v_mfma_f32_16x16x32_bf16 v[64:67], v[228:231], v[212:215], v[64:67]
	v_mfma_f32_16x16x32_bf16 v[92:95], v[224:227], v[190:193], v[92:95]
	v_mfma_f32_16x16x32_bf16 v[88:91], v[232:235], v[190:193], v[88:91]
	v_mfma_f32_16x16x32_bf16 v[84:87], v[224:227], v[200:203], v[84:87]
	v_mfma_f32_16x16x32_bf16 v[80:83], v[232:235], v[200:203], v[80:83]
	v_mfma_f32_16x16x32_bf16 v[76:79], v[224:227], v[208:211], v[76:79]
	v_mfma_f32_16x16x32_bf16 v[72:75], v[232:235], v[208:211], v[72:75]
	v_mfma_f32_16x16x32_bf16 v[68:71], v[224:227], v[216:219], v[68:71]
	v_mfma_f32_16x16x32_bf16 v[64:67], v[232:235], v[216:219], v[64:67]
	s_setprio 0
	v_readfirstlane_b32 s24, v159
	v_lshl_add_u64 v[194:195], v[242:243], 0, s[40:41]
	s_mov_b32 m0, s24
	v_readfirstlane_b32 s24, v160
	s_barrier
	ds_read_b128 v[186:189], v152 offset:49152
	ds_read_b128 v[190:193], v152 offset:50176
	ds_read_b128 v[196:199], v151 offset:49152
	ds_read_b128 v[200:203], v151 offset:50176
	ds_read_b128 v[204:207], v150 offset:49152
	ds_read_b128 v[208:211], v150 offset:50176
	ds_read_b128 v[212:215], v148 offset:49152
	ds_read_b128 v[216:219], v148 offset:50176
	global_load_lds_dwordx4 v[194:195], off
	v_lshl_add_u64 v[194:195], v[244:245], 0, s[40:41]
	s_mov_b32 m0, s24
	s_nop 0
	global_load_lds_dwordx4 v[194:195], off
	s_barrier
	s_waitcnt lgkmcnt(0)
	s_setprio 1
	v_mfma_f32_16x16x32_bf16 v[60:63], v[170:173], v[186:189], v[60:63]
	v_mfma_f32_16x16x32_bf16 v[56:59], v[178:181], v[186:189], v[56:59]
	v_mfma_f32_16x16x32_bf16 v[52:55], v[170:173], v[196:199], v[52:55]
	v_mfma_f32_16x16x32_bf16 v[48:51], v[178:181], v[196:199], v[48:51]
	v_mfma_f32_16x16x32_bf16 v[44:47], v[170:173], v[204:207], v[44:47]
	v_mfma_f32_16x16x32_bf16 v[40:43], v[178:181], v[204:207], v[40:43]
	v_mfma_f32_16x16x32_bf16 v[36:39], v[170:173], v[212:215], v[36:39]
	v_mfma_f32_16x16x32_bf16 v[32:35], v[178:181], v[212:215], v[32:35]
	v_mfma_f32_16x16x32_bf16 v[60:63], v[174:177], v[190:193], v[60:63]
	v_mfma_f32_16x16x32_bf16 v[56:59], v[182:185], v[190:193], v[56:59]
	v_mfma_f32_16x16x32_bf16 v[52:55], v[174:177], v[200:203], v[52:55]
	v_mfma_f32_16x16x32_bf16 v[48:51], v[182:185], v[200:203], v[48:51]
	v_mfma_f32_16x16x32_bf16 v[44:47], v[174:177], v[208:211], v[44:47]
	v_mfma_f32_16x16x32_bf16 v[40:43], v[182:185], v[208:211], v[40:43]
	v_mfma_f32_16x16x32_bf16 v[36:39], v[174:177], v[216:219], v[36:39]
	v_mfma_f32_16x16x32_bf16 v[32:35], v[182:185], v[216:219], v[32:35]
	s_setprio 0
	s_barrier
	v_readfirstlane_b32 s24, v161
	v_lshl_add_u64 v[170:171], v[238:239], 0, s[42:43]
	s_mov_b32 m0, s24
	v_readfirstlane_b32 s24, v162
	global_load_lds_dwordx4 v[170:171], off
	v_lshl_add_u64 v[170:171], v[240:241], 0, s[42:43]
	s_mov_b32 m0, s24
	s_nop 0
	global_load_lds_dwordx4 v[170:171], off
	s_waitcnt vmcnt(6)
	s_barrier
	s_setprio 1
	v_mfma_f32_16x16x32_bf16 v[28:31], v[220:223], v[186:189], v[28:31]
	v_mfma_f32_16x16x32_bf16 v[24:27], v[228:231], v[186:189], v[24:27]
	v_mfma_f32_16x16x32_bf16 v[20:23], v[220:223], v[196:199], v[20:23]
	v_mfma_f32_16x16x32_bf16 v[16:19], v[228:231], v[196:199], v[16:19]
	v_mfma_f32_16x16x32_bf16 v[12:15], v[220:223], v[204:207], v[12:15]
	v_mfma_f32_16x16x32_bf16 v[8:11], v[228:231], v[204:207], v[8:11]
	v_mfma_f32_16x16x32_bf16 v[4:7], v[220:223], v[212:215], v[4:7]
	v_mfma_f32_16x16x32_bf16 v[0:3], v[228:231], v[212:215], v[0:3]
	v_mfma_f32_16x16x32_bf16 v[28:31], v[224:227], v[190:193], v[28:31]
	v_mfma_f32_16x16x32_bf16 v[24:27], v[232:235], v[190:193], v[24:27]
	v_mfma_f32_16x16x32_bf16 v[20:23], v[224:227], v[200:203], v[20:23]
	v_mfma_f32_16x16x32_bf16 v[16:19], v[232:235], v[200:203], v[16:19]
	v_mfma_f32_16x16x32_bf16 v[12:15], v[224:227], v[208:211], v[12:15]
	v_mfma_f32_16x16x32_bf16 v[8:11], v[232:235], v[208:211], v[8:11]
	v_mfma_f32_16x16x32_bf16 v[4:7], v[224:227], v[216:219], v[4:7]
	v_mfma_f32_16x16x32_bf16 v[0:3], v[232:235], v[216:219], v[0:3]
	s_setprio 0
	s_add_i32 s49, s49, 2
	v_lshl_add_u64 v[132:133], v[132:133], 0, s[44:45]
	v_lshl_add_u64 v[134:135], v[134:135], 0, s[44:45]
	v_lshl_add_u64 v[136:137], v[136:137], 0, s[44:45]
	v_lshl_add_u64 v[138:139], v[138:139], 0, s[44:45]
	v_lshl_add_u64 v[140:141], v[140:141], 0, s[44:45]
	s_cmp_lt_u32 s49, 28
	v_lshl_add_u64 v[142:143], v[142:143], 0, s[44:45]
	s_barrier
	s_cbranch_scc1 .LBB0_605
	v_readfirstlane_b32 s24, v165
	v_lshl_add_u64 v[128:129], v[128:129], 0, s[46:47]
	s_mov_b32 m0, s24
	v_readfirstlane_b32 s24, v166
	ds_read_b128 v[132:135], v164
	ds_read_b128 v[136:139], v164 offset:1024
	ds_read_b128 v[140:143], v164 offset:2048
	ds_read_b128 v[154:157], v164 offset:3072
	ds_read_b128 v[158:161], v152
	ds_read_b128 v[170:173], v152 offset:1024
	ds_read_b128 v[174:177], v151
	ds_read_b128 v[178:181], v151 offset:1024
	ds_read_b128 v[182:185], v150
	ds_read_b128 v[186:189], v150 offset:1024
	ds_read_b128 v[190:193], v148
	ds_read_b128 v[196:199], v148 offset:1024
	global_load_lds_dwordx4 v[128:129], off
	v_lshl_add_u64 v[128:129], v[130:131], 0, s[46:47]
	s_mov_b32 m0, s24
	s_nop 0
	global_load_lds_dwordx4 v[128:129], off
	s_barrier
	s_waitcnt lgkmcnt(0)
	s_setprio 1
	v_mfma_f32_16x16x32_bf16 v[124:127], v[132:135], v[158:161], v[124:127]
	v_mfma_f32_16x16x32_bf16 v[120:123], v[140:143], v[158:161], v[120:123]
	v_mfma_f32_16x16x32_bf16 v[116:119], v[132:135], v[174:177], v[116:119]
	v_mfma_f32_16x16x32_bf16 v[112:115], v[140:143], v[174:177], v[112:115]
	v_mfma_f32_16x16x32_bf16 v[108:111], v[132:135], v[182:185], v[108:111]
	v_mfma_f32_16x16x32_bf16 v[104:107], v[140:143], v[182:185], v[104:107]
	v_mfma_f32_16x16x32_bf16 v[100:103], v[132:135], v[190:193], v[100:103]
	v_mfma_f32_16x16x32_bf16 v[96:99], v[140:143], v[190:193], v[96:99]
	v_mfma_f32_16x16x32_bf16 v[124:127], v[136:139], v[170:173], v[124:127]
	v_mfma_f32_16x16x32_bf16 v[120:123], v[154:157], v[170:173], v[120:123]
	v_mfma_f32_16x16x32_bf16 v[116:119], v[136:139], v[178:181], v[116:119]
	v_mfma_f32_16x16x32_bf16 v[112:115], v[154:157], v[178:181], v[112:115]
	v_mfma_f32_16x16x32_bf16 v[108:111], v[136:139], v[186:189], v[108:111]
	v_mfma_f32_16x16x32_bf16 v[104:107], v[154:157], v[186:189], v[104:107]
	v_mfma_f32_16x16x32_bf16 v[100:103], v[136:139], v[196:199], v[100:103]
	v_mfma_f32_16x16x32_bf16 v[96:99], v[154:157], v[196:199], v[96:99]
	s_setprio 0
	s_barrier
	ds_read_b128 v[128:131], v167
	ds_read_b128 v[162:165], v167 offset:1024
	ds_read_b128 v[200:203], v167 offset:2048
	ds_read_b128 v[204:207], v167 offset:3072
	s_barrier
	s_waitcnt lgkmcnt(0)
	s_setprio 1
	v_mfma_f32_16x16x32_bf16 v[88:91], v[200:203], v[158:161], v[88:91]
	v_mfma_f32_16x16x32_bf16 v[84:87], v[128:131], v[174:177], v[84:87]
	v_mfma_f32_16x16x32_bf16 v[80:83], v[200:203], v[174:177], v[80:83]
	v_mfma_f32_16x16x32_bf16 v[76:79], v[128:131], v[182:185], v[76:79]
	v_mfma_f32_16x16x32_bf16 v[72:75], v[200:203], v[182:185], v[72:75]
	v_mfma_f32_16x16x32_bf16 v[68:71], v[128:131], v[190:193], v[68:71]
	v_mfma_f32_16x16x32_bf16 v[64:67], v[200:203], v[190:193], v[64:67]
	v_mfma_f32_16x16x32_bf16 v[92:95], v[128:131], v[158:161], v[92:95]
	v_mfma_f32_16x16x32_bf16 v[88:91], v[204:207], v[170:173], v[88:91]
	v_mfma_f32_16x16x32_bf16 v[84:87], v[162:165], v[178:181], v[84:87]
	v_mfma_f32_16x16x32_bf16 v[80:83], v[204:207], v[178:181], v[80:83]
	v_mfma_f32_16x16x32_bf16 v[76:79], v[162:165], v[186:189], v[76:79]
	v_mfma_f32_16x16x32_bf16 v[72:75], v[204:207], v[186:189], v[72:75]
	v_mfma_f32_16x16x32_bf16 v[68:71], v[162:165], v[196:199], v[68:71]
	v_mfma_f32_16x16x32_bf16 v[64:67], v[204:207], v[196:199], v[64:67]
	v_mfma_f32_16x16x32_bf16 v[208:211], v[162:165], v[170:173], v[92:95]
	s_setprio 0
	s_barrier
	s_nop 0
	ds_read_b128 v[92:95], v152 offset:16384
	ds_read_b128 v[158:161], v152 offset:17408
	ds_read_b128 v[170:173], v151 offset:16384
	ds_read_b128 v[174:177], v151 offset:17408
	ds_read_b128 v[178:181], v150 offset:16384
	ds_read_b128 v[182:185], v150 offset:17408
	ds_read_b128 v[186:189], v148 offset:16384
	ds_read_b128 v[190:193], v148 offset:17408
	s_waitcnt vmcnt(4)
	s_barrier
	s_waitcnt lgkmcnt(0)
	s_setprio 1
	v_mfma_f32_16x16x32_bf16 v[56:59], v[140:143], v[92:95], v[56:59]
	v_mfma_f32_16x16x32_bf16 v[52:55], v[132:135], v[170:173], v[52:55]
	v_mfma_f32_16x16x32_bf16 v[48:51], v[140:143], v[170:173], v[48:51]
	v_mfma_f32_16x16x32_bf16 v[44:47], v[132:135], v[178:181], v[44:47]
	v_mfma_f32_16x16x32_bf16 v[40:43], v[140:143], v[178:181], v[40:43]
	v_mfma_f32_16x16x32_bf16 v[36:39], v[132:135], v[186:189], v[36:39]
	v_mfma_f32_16x16x32_bf16 v[32:35], v[140:143], v[186:189], v[32:35]
	v_mfma_f32_16x16x32_bf16 v[60:63], v[132:135], v[92:95], v[60:63]
	v_mfma_f32_16x16x32_bf16 v[56:59], v[154:157], v[158:161], v[56:59]
	v_mfma_f32_16x16x32_bf16 v[52:55], v[136:139], v[174:177], v[52:55]
	v_mfma_f32_16x16x32_bf16 v[48:51], v[154:157], v[174:177], v[48:51]
	v_mfma_f32_16x16x32_bf16 v[44:47], v[136:139], v[182:185], v[44:47]
	v_mfma_f32_16x16x32_bf16 v[40:43], v[154:157], v[182:185], v[40:43]
	v_mfma_f32_16x16x32_bf16 v[36:39], v[136:139], v[190:193], v[36:39]
	v_mfma_f32_16x16x32_bf16 v[32:35], v[154:157], v[190:193], v[32:35]
	v_mfma_f32_16x16x32_bf16 v[196:199], v[136:139], v[158:161], v[60:63]
	s_setprio 0
	s_setprio 1
	v_mfma_f32_16x16x32_bf16 v[28:31], v[128:131], v[92:95], v[28:31]
	v_mfma_f32_16x16x32_bf16 v[24:27], v[200:203], v[92:95], v[24:27]
	v_mfma_f32_16x16x32_bf16 v[20:23], v[128:131], v[170:173], v[20:23]
	v_mfma_f32_16x16x32_bf16 v[16:19], v[200:203], v[170:173], v[16:19]
	v_mfma_f32_16x16x32_bf16 v[12:15], v[128:131], v[178:181], v[12:15]
	v_mfma_f32_16x16x32_bf16 v[8:11], v[200:203], v[178:181], v[8:11]
	v_mfma_f32_16x16x32_bf16 v[4:7], v[128:131], v[186:189], v[4:7]
	v_mfma_f32_16x16x32_bf16 v[0:3], v[200:203], v[186:189], v[0:3]
	v_mfma_f32_16x16x32_bf16 v[28:31], v[162:165], v[158:161], v[28:31]
	v_mfma_f32_16x16x32_bf16 v[24:27], v[204:207], v[158:161], v[24:27]
	v_mfma_f32_16x16x32_bf16 v[20:23], v[162:165], v[174:177], v[20:23]
	v_mfma_f32_16x16x32_bf16 v[16:19], v[204:207], v[174:177], v[16:19]
	v_mfma_f32_16x16x32_bf16 v[12:15], v[162:165], v[182:185], v[12:15]
	v_mfma_f32_16x16x32_bf16 v[8:11], v[204:207], v[182:185], v[8:11]
	v_mfma_f32_16x16x32_bf16 v[4:7], v[162:165], v[190:193], v[4:7]
	v_mfma_f32_16x16x32_bf16 v[0:3], v[204:207], v[190:193], v[0:3]
	s_setprio 0
	s_barrier
	ds_read_b128 v[128:131], v168
	ds_read_b128 v[132:135], v168 offset:1024
	ds_read_b128 v[136:139], v168 offset:2048
	ds_read_b128 v[140:143], v168 offset:3072
	ds_read_b128 v[60:63], v152 offset:32768
	ds_read_b128 v[154:157], v152 offset:33792
	ds_read_b128 v[158:161], v151 offset:32768
	ds_read_b128 v[162:165], v151 offset:33792
	ds_read_b128 v[170:173], v150 offset:32768
	ds_read_b128 v[174:177], v150 offset:33792
	ds_read_b128 v[178:181], v148 offset:32768
	ds_read_b128 v[182:185], v148 offset:33792
	s_waitcnt vmcnt(2)
	s_barrier
	s_waitcnt lgkmcnt(0)
	s_setprio 1
	v_mfma_f32_16x16x32_bf16 v[92:95], v[128:131], v[60:63], v[124:127]
	v_mfma_f32_16x16x32_bf16 v[124:127], v[132:135], v[154:157], v[92:95]
	v_mfma_f32_16x16x32_bf16 v[92:95], v[136:139], v[60:63], v[120:123]
	v_mfma_f32_16x16x32_bf16 v[120:123], v[140:143], v[154:157], v[92:95]
	v_mfma_f32_16x16x32_bf16 v[92:95], v[128:131], v[158:161], v[116:119]
	v_mfma_f32_16x16x32_bf16 v[116:119], v[132:135], v[162:165], v[92:95]
	v_mfma_f32_16x16x32_bf16 v[92:95], v[136:139], v[158:161], v[112:115]
	v_mfma_f32_16x16x32_bf16 v[112:115], v[140:143], v[162:165], v[92:95]
	v_mfma_f32_16x16x32_bf16 v[92:95], v[128:131], v[170:173], v[108:111]
	v_mfma_f32_16x16x32_bf16 v[108:111], v[132:135], v[174:177], v[92:95]
	v_mfma_f32_16x16x32_bf16 v[92:95], v[136:139], v[170:173], v[104:107]
	v_mfma_f32_16x16x32_bf16 v[104:107], v[140:143], v[174:177], v[92:95]
	v_mfma_f32_16x16x32_bf16 v[92:95], v[128:131], v[178:181], v[100:103]
	v_mfma_f32_16x16x32_bf16 v[100:103], v[132:135], v[182:185], v[92:95]
	v_mfma_f32_16x16x32_bf16 v[92:95], v[136:139], v[178:181], v[96:99]
	v_mfma_f32_16x16x32_bf16 v[92:95], v[140:143], v[182:185], v[92:95]
	s_setprio 0
	s_barrier
	ds_read_b128 v[186:189], v169
	ds_read_b128 v[190:193], v169 offset:1024
	ds_read_b128 v[200:203], v169 offset:2048
	ds_read_b128 v[166:169], v169 offset:3072
	s_waitcnt vmcnt(0)
	s_barrier
	s_waitcnt lgkmcnt(0)
	s_setprio 1
	v_mfma_f32_16x16x32_bf16 v[96:99], v[186:189], v[60:63], v[208:211]
	v_mfma_f32_16x16x32_bf16 v[60:63], v[200:203], v[60:63], v[88:91]
	v_mfma_f32_16x16x32_bf16 v[88:91], v[166:169], v[154:157], v[60:63]
	v_mfma_f32_16x16x32_bf16 v[60:63], v[186:189], v[158:161], v[84:87]
	v_mfma_f32_16x16x32_bf16 v[84:87], v[190:193], v[162:165], v[60:63]
	v_mfma_f32_16x16x32_bf16 v[60:63], v[200:203], v[158:161], v[80:83]
	v_mfma_f32_16x16x32_bf16 v[80:83], v[166:169], v[162:165], v[60:63]
	v_mfma_f32_16x16x32_bf16 v[60:63], v[186:189], v[170:173], v[76:79]
	v_mfma_f32_16x16x32_bf16 v[76:79], v[190:193], v[174:177], v[60:63]
	v_mfma_f32_16x16x32_bf16 v[60:63], v[200:203], v[170:173], v[72:75]
	v_mfma_f32_16x16x32_bf16 v[72:75], v[166:169], v[174:177], v[60:63]
	v_mfma_f32_16x16x32_bf16 v[60:63], v[186:189], v[178:181], v[68:71]
	v_mfma_f32_16x16x32_bf16 v[68:71], v[190:193], v[182:185], v[60:63]
	v_mfma_f32_16x16x32_bf16 v[60:63], v[200:203], v[178:181], v[64:67]
	v_mfma_f32_16x16x32_bf16 v[96:99], v[190:193], v[154:157], v[96:99]
	v_mfma_f32_16x16x32_bf16 v[60:63], v[166:169], v[182:185], v[60:63]
	s_setprio 0
	s_barrier
	ds_read_b128 v[154:157], v152 offset:49152
	ds_read_b128 v[158:161], v152 offset:50176
	ds_read_b128 v[162:165], v151 offset:49152
	ds_read_b128 v[170:173], v151 offset:50176
	ds_read_b128 v[174:177], v150 offset:49152
	ds_read_b128 v[150:153], v150 offset:50176
	ds_read_b128 v[178:181], v148 offset:49152
	ds_read_b128 v[182:185], v148 offset:50176
	s_barrier
	s_waitcnt lgkmcnt(0)
	s_setprio 1
	v_mfma_f32_16x16x32_bf16 v[64:67], v[128:131], v[154:157], v[196:199]
	v_mfma_f32_16x16x32_bf16 v[56:59], v[136:139], v[154:157], v[56:59]
	v_mfma_f32_16x16x32_bf16 v[52:55], v[128:131], v[162:165], v[52:55]
	v_mfma_f32_16x16x32_bf16 v[48:51], v[136:139], v[162:165], v[48:51]
	v_mfma_f32_16x16x32_bf16 v[44:47], v[128:131], v[174:177], v[44:47]
	v_mfma_f32_16x16x32_bf16 v[40:43], v[136:139], v[174:177], v[40:43]
	v_mfma_f32_16x16x32_bf16 v[36:39], v[128:131], v[178:181], v[36:39]
	v_mfma_f32_16x16x32_bf16 v[32:35], v[136:139], v[178:181], v[32:35]
	v_mfma_f32_16x16x32_bf16 v[64:67], v[132:135], v[158:161], v[64:67]
	v_mfma_f32_16x16x32_bf16 v[56:59], v[140:143], v[158:161], v[56:59]
	v_mfma_f32_16x16x32_bf16 v[52:55], v[132:135], v[170:173], v[52:55]
	v_mfma_f32_16x16x32_bf16 v[48:51], v[140:143], v[170:173], v[48:51]
	v_mfma_f32_16x16x32_bf16 v[44:47], v[132:135], v[150:153], v[44:47]
	v_mfma_f32_16x16x32_bf16 v[40:43], v[140:143], v[150:153], v[40:43]
	v_mfma_f32_16x16x32_bf16 v[36:39], v[132:135], v[182:185], v[36:39]
	v_mfma_f32_16x16x32_bf16 v[32:35], v[140:143], v[182:185], v[32:35]
	s_setprio 0
	s_setprio 1
	v_mfma_f32_16x16x32_bf16 v[28:31], v[186:189], v[154:157], v[28:31]
	v_mfma_f32_16x16x32_bf16 v[24:27], v[200:203], v[154:157], v[24:27]
	v_mfma_f32_16x16x32_bf16 v[20:23], v[186:189], v[162:165], v[20:23]
	v_mfma_f32_16x16x32_bf16 v[16:19], v[200:203], v[162:165], v[16:19]
	v_mfma_f32_16x16x32_bf16 v[12:15], v[186:189], v[174:177], v[12:15]
	v_mfma_f32_16x16x32_bf16 v[8:11], v[200:203], v[174:177], v[8:11]
	v_mfma_f32_16x16x32_bf16 v[4:7], v[186:189], v[178:181], v[4:7]
	v_mfma_f32_16x16x32_bf16 v[0:3], v[200:203], v[178:181], v[0:3]
	v_mfma_f32_16x16x32_bf16 v[28:31], v[190:193], v[158:161], v[28:31]
	v_mfma_f32_16x16x32_bf16 v[24:27], v[166:169], v[158:161], v[24:27]
	v_mfma_f32_16x16x32_bf16 v[20:23], v[190:193], v[170:173], v[20:23]
	v_mfma_f32_16x16x32_bf16 v[16:19], v[166:169], v[170:173], v[16:19]
	v_mfma_f32_16x16x32_bf16 v[12:15], v[190:193], v[150:153], v[12:15]
	v_mfma_f32_16x16x32_bf16 v[8:11], v[166:169], v[150:153], v[8:11]
	v_mfma_f32_16x16x32_bf16 v[4:7], v[190:193], v[182:185], v[4:7]
	v_mfma_f32_16x16x32_bf16 v[0:3], v[166:169], v[182:185], v[0:3]
	s_setprio 0
	v_readlane_b32 s8, v253, 16
	v_readlane_b32 s9, v253, 17
	s_andn2_b64 vcc, exec, s[8:9]
	s_barrier
	s_cbranch_vccnz .LBB0_601
	s_barrier
	s_branch .LBB0_601

.Lqg16_loop:
	v_add_u32_e32 v165, s56, v164
	ds_read_b128 v[170:173], v165
	ds_read_b128 v[174:177], v165 offset:1024
	ds_read_b128 v[178:181], v165 offset:2048
	ds_read_b128 v[182:185], v165 offset:3072
	v_add_u32_e32 v166, 0xc000, v151
	v_lshl_add_u64 v[194:195], s[76:77], 0, v[142:143]
	v_readfirstlane_b32 s24, v166
	v_add_u32_e32 v167, 0xe000, v151
	v_lshl_add_u64 v[168:169], v[194:195], 0, s[14:15]
	s_mov_b32 m0, s24
	v_lshl_add_u64 v[236:237], s[76:77], 0, v[144:145]
	v_readfirstlane_b32 s24, v167
	ds_read_b128 v[186:189], v153
	ds_read_b128 v[190:193], v153 offset:1024
	ds_read_b128 v[196:199], v152
	ds_read_b128 v[200:203], v152 offset:1024
	ds_read_b128 v[204:207], v150
	ds_read_b128 v[208:211], v150 offset:1024
	ds_read_b128 v[212:215], v149
	ds_read_b128 v[216:219], v149 offset:1024
	global_load_lds_dwordx4 v[168:169], off
	v_lshl_add_u64 v[168:169], v[236:237], 0, s[14:15]
	s_mov_b32 m0, s24
	s_nop 0
	global_load_lds_dwordx4 v[168:169], off
	s_waitcnt lgkmcnt(8)
	s_barrier
	s_waitcnt lgkmcnt(0)
	s_setprio 1
	v_mfma_f32_16x16x32_bf16 v[124:127], v[170:173], v[186:189], v[124:127]
	v_mfma_f32_16x16x32_bf16 v[120:123], v[178:181], v[186:189], v[120:123]
	v_mfma_f32_16x16x32_bf16 v[116:119], v[170:173], v[196:199], v[116:119]
	v_mfma_f32_16x16x32_bf16 v[112:115], v[178:181], v[196:199], v[112:115]
	v_mfma_f32_16x16x32_bf16 v[108:111], v[170:173], v[204:207], v[108:111]
	v_mfma_f32_16x16x32_bf16 v[104:107], v[178:181], v[204:207], v[104:107]
	v_mfma_f32_16x16x32_bf16 v[100:103], v[170:173], v[212:215], v[100:103]
	v_mfma_f32_16x16x32_bf16 v[96:99], v[178:181], v[212:215], v[96:99]
	v_mfma_f32_16x16x32_bf16 v[124:127], v[174:177], v[190:193], v[124:127]
	v_mfma_f32_16x16x32_bf16 v[120:123], v[182:185], v[190:193], v[120:123]
	v_mfma_f32_16x16x32_bf16 v[116:119], v[174:177], v[200:203], v[116:119]
	v_mfma_f32_16x16x32_bf16 v[112:115], v[182:185], v[200:203], v[112:115]
	v_mfma_f32_16x16x32_bf16 v[108:111], v[174:177], v[208:211], v[108:111]
	v_mfma_f32_16x16x32_bf16 v[104:107], v[182:185], v[208:211], v[104:107]
	v_mfma_f32_16x16x32_bf16 v[100:103], v[174:177], v[216:219], v[100:103]
	v_mfma_f32_16x16x32_bf16 v[96:99], v[182:185], v[216:219], v[96:99]
	s_setprio 0
	s_barrier
	v_lshl_add_u64 v[240:241], s[76:77], 0, v[134:135]
	v_readfirstlane_b32 s24, v148
	v_add_u32_e32 v169, 0x2000, v148
	v_add_u32_e32 v168, s61, v164
	v_lshl_add_u64 v[238:239], v[240:241], 0, s[16:17]
	s_mov_b32 m0, s24
	v_lshl_add_u64 v[242:243], s[76:77], 0, v[136:137]
	v_readfirstlane_b32 s24, v169
	ds_read_b128 v[220:223], v168
	ds_read_b128 v[224:227], v168 offset:1024
	ds_read_b128 v[228:231], v168 offset:2048
	ds_read_b128 v[232:235], v168 offset:3072
	global_load_lds_dwordx4 v[238:239], off
	v_lshl_add_u64 v[238:239], v[242:243], 0, s[16:17]
	s_mov_b32 m0, s24
	s_nop 0
	global_load_lds_dwordx4 v[238:239], off
	s_barrier
	s_waitcnt lgkmcnt(0)
	s_setprio 1
	s_setprio 0
	v_lshl_add_u64 v[244:245], s[76:77], 0, v[138:139]
	v_readfirstlane_b32 s24, v151
	v_lshl_add_u64 v[238:239], v[244:245], 0, s[18:19]
	s_mov_b32 m0, s24
	v_lshl_add_u64 v[246:247], s[76:77], 0, v[140:141]
	v_readfirstlane_b32 s24, v154
	s_barrier
	ds_read_b128 v[186:189], v153 offset:16384
	ds_read_b128 v[190:193], v153 offset:17408
	ds_read_b128 v[196:199], v152 offset:16384
	ds_read_b128 v[200:203], v152 offset:17408
	ds_read_b128 v[204:207], v150 offset:16384
	ds_read_b128 v[208:211], v150 offset:17408
	ds_read_b128 v[212:215], v149 offset:16384
	ds_read_b128 v[216:219], v149 offset:17408
	global_load_lds_dwordx4 v[238:239], off
	v_lshl_add_u64 v[238:239], v[246:247], 0, s[18:19]
	s_mov_b32 m0, s24
	s_nop 0
	global_load_lds_dwordx4 v[238:239], off
	s_barrier
	s_waitcnt lgkmcnt(0)
	s_setprio 1
	v_mfma_f32_16x16x32_bf16 v[60:63], v[170:173], v[186:189], v[60:63]
	v_mfma_f32_16x16x32_bf16 v[56:59], v[178:181], v[186:189], v[56:59]
	v_mfma_f32_16x16x32_bf16 v[52:55], v[170:173], v[196:199], v[52:55]
	v_mfma_f32_16x16x32_bf16 v[48:51], v[178:181], v[196:199], v[48:51]
	v_mfma_f32_16x16x32_bf16 v[44:47], v[170:173], v[204:207], v[44:47]
	v_mfma_f32_16x16x32_bf16 v[40:43], v[178:181], v[204:207], v[40:43]
	v_mfma_f32_16x16x32_bf16 v[36:39], v[170:173], v[212:215], v[36:39]
	v_mfma_f32_16x16x32_bf16 v[32:35], v[178:181], v[212:215], v[32:35]
	v_mfma_f32_16x16x32_bf16 v[60:63], v[174:177], v[190:193], v[60:63]
	v_mfma_f32_16x16x32_bf16 v[56:59], v[182:185], v[190:193], v[56:59]
	v_mfma_f32_16x16x32_bf16 v[52:55], v[174:177], v[200:203], v[52:55]
	v_mfma_f32_16x16x32_bf16 v[48:51], v[182:185], v[200:203], v[48:51]
	v_mfma_f32_16x16x32_bf16 v[44:47], v[174:177], v[208:211], v[44:47]
	v_mfma_f32_16x16x32_bf16 v[40:43], v[182:185], v[208:211], v[40:43]
	v_mfma_f32_16x16x32_bf16 v[36:39], v[174:177], v[216:219], v[36:39]
	v_mfma_f32_16x16x32_bf16 v[32:35], v[182:185], v[216:219], v[32:35]
	s_setprio 0
	s_barrier
	v_readfirstlane_b32 s24, v155
	v_add_u32_e32 v169, 0x2000, v155
	v_lshl_add_u64 v[170:171], v[240:241], 0, s[20:21]
	s_mov_b32 m0, s24
	v_readfirstlane_b32 s24, v169
	global_load_lds_dwordx4 v[170:171], off
	v_lshl_add_u64 v[170:171], v[242:243], 0, s[20:21]
	s_mov_b32 m0, s24
	s_nop 0
	global_load_lds_dwordx4 v[170:171], off
	s_waitcnt vmcnt(6)
	s_barrier
	s_setprio 1
	s_setprio 0
	v_add_u32_e32 v169, s62, v164
	s_barrier
	ds_read_b128 v[172:175], v169
	ds_read_b128 v[176:179], v169 offset:1024
	ds_read_b128 v[180:183], v169 offset:2048
	ds_read_b128 v[184:187], v169 offset:3072
	v_readfirstlane_b32 s24, v156
	v_lshl_add_u64 v[170:171], v[194:195], 0, s[18:19]
	s_mov_b32 m0, s24
	v_readfirstlane_b32 s24, v157
	ds_read_b128 v[188:191], v153 offset:32768
	ds_read_b128 v[196:199], v153 offset:33792
	ds_read_b128 v[200:203], v152 offset:32768
	ds_read_b128 v[204:207], v152 offset:33792
	ds_read_b128 v[208:211], v150 offset:32768
	ds_read_b128 v[212:215], v150 offset:33792
	ds_read_b128 v[216:219], v149 offset:32768
	ds_read_b128 v[220:223], v149 offset:33792
	global_load_lds_dwordx4 v[170:171], off
	v_lshl_add_u64 v[170:171], v[236:237], 0, s[18:19]
	s_mov_b32 m0, s24
	s_nop 0
	global_load_lds_dwordx4 v[170:171], off
	s_waitcnt lgkmcnt(8)
	s_barrier
	s_waitcnt lgkmcnt(0)
	s_setprio 1
	v_mfma_f32_16x16x32_bf16 v[124:127], v[172:175], v[188:191], v[124:127]
	v_mfma_f32_16x16x32_bf16 v[120:123], v[180:183], v[188:191], v[120:123]
	v_mfma_f32_16x16x32_bf16 v[116:119], v[172:175], v[200:203], v[116:119]
	v_mfma_f32_16x16x32_bf16 v[112:115], v[180:183], v[200:203], v[112:115]
	v_mfma_f32_16x16x32_bf16 v[108:111], v[172:175], v[208:211], v[108:111]
	v_mfma_f32_16x16x32_bf16 v[104:107], v[180:183], v[208:211], v[104:107]
	v_mfma_f32_16x16x32_bf16 v[100:103], v[172:175], v[216:219], v[100:103]
	v_mfma_f32_16x16x32_bf16 v[96:99], v[180:183], v[216:219], v[96:99]
	v_mfma_f32_16x16x32_bf16 v[124:127], v[176:179], v[196:199], v[124:127]
	v_mfma_f32_16x16x32_bf16 v[120:123], v[184:187], v[196:199], v[120:123]
	v_mfma_f32_16x16x32_bf16 v[116:119], v[176:179], v[204:207], v[116:119]
	v_mfma_f32_16x16x32_bf16 v[112:115], v[184:187], v[204:207], v[112:115]
	v_mfma_f32_16x16x32_bf16 v[108:111], v[176:179], v[212:215], v[108:111]
	v_mfma_f32_16x16x32_bf16 v[104:107], v[184:187], v[212:215], v[104:107]
	v_mfma_f32_16x16x32_bf16 v[100:103], v[176:179], v[220:223], v[100:103]
	v_mfma_f32_16x16x32_bf16 v[96:99], v[184:187], v[220:223], v[96:99]
	s_setprio 0
	s_barrier
	v_readfirstlane_b32 s24, v158
	v_add_u32_e32 v170, s63, v164
	v_lshl_add_u64 v[192:193], v[240:241], 0, s[22:23]
	s_mov_b32 m0, s24
	v_readfirstlane_b32 s24, v159
	ds_read_b128 v[224:227], v170
	ds_read_b128 v[228:231], v170 offset:1024
	ds_read_b128 v[232:235], v170 offset:2048
	ds_read_b128 v[236:239], v170 offset:3072
	global_load_lds_dwordx4 v[192:193], off
	v_lshl_add_u64 v[192:193], v[242:243], 0, s[22:23]
	s_mov_b32 m0, s24
	s_nop 0
	global_load_lds_dwordx4 v[192:193], off
	s_barrier
	s_waitcnt lgkmcnt(0)
	s_setprio 1
	s_setprio 0
	v_readfirstlane_b32 s24, v160
	v_lshl_add_u64 v[192:193], v[244:245], 0, s[36:37]
	s_mov_b32 m0, s24
	v_readfirstlane_b32 s24, v161
	s_barrier
	ds_read_b128 v[188:191], v153 offset:49152
	ds_read_b128 v[196:199], v153 offset:50176
	ds_read_b128 v[200:203], v152 offset:49152
	ds_read_b128 v[204:207], v152 offset:50176
	ds_read_b128 v[208:211], v150 offset:49152
	ds_read_b128 v[212:215], v150 offset:50176
	ds_read_b128 v[216:219], v149 offset:49152
	ds_read_b128 v[220:223], v149 offset:50176
	global_load_lds_dwordx4 v[192:193], off
	v_lshl_add_u64 v[192:193], v[246:247], 0, s[36:37]
	s_mov_b32 m0, s24
	s_nop 0
	global_load_lds_dwordx4 v[192:193], off
	s_barrier
	s_waitcnt lgkmcnt(0)
	s_setprio 1
	v_mfma_f32_16x16x32_bf16 v[60:63], v[172:175], v[188:191], v[60:63]
	v_mfma_f32_16x16x32_bf16 v[56:59], v[180:183], v[188:191], v[56:59]
	v_mfma_f32_16x16x32_bf16 v[52:55], v[172:175], v[200:203], v[52:55]
	v_mfma_f32_16x16x32_bf16 v[48:51], v[180:183], v[200:203], v[48:51]
	v_mfma_f32_16x16x32_bf16 v[44:47], v[172:175], v[208:211], v[44:47]
	v_mfma_f32_16x16x32_bf16 v[40:43], v[180:183], v[208:211], v[40:43]
	v_mfma_f32_16x16x32_bf16 v[36:39], v[172:175], v[216:219], v[36:39]
	v_mfma_f32_16x16x32_bf16 v[32:35], v[180:183], v[216:219], v[32:35]
	v_mfma_f32_16x16x32_bf16 v[60:63], v[176:179], v[196:199], v[60:63]
	v_mfma_f32_16x16x32_bf16 v[56:59], v[184:187], v[196:199], v[56:59]
	v_mfma_f32_16x16x32_bf16 v[52:55], v[176:179], v[204:207], v[52:55]
	v_mfma_f32_16x16x32_bf16 v[48:51], v[184:187], v[204:207], v[48:51]
	v_mfma_f32_16x16x32_bf16 v[44:47], v[176:179], v[212:215], v[44:47]
	v_mfma_f32_16x16x32_bf16 v[40:43], v[184:187], v[212:215], v[40:43]
	v_mfma_f32_16x16x32_bf16 v[36:39], v[176:179], v[220:223], v[36:39]
	v_mfma_f32_16x16x32_bf16 v[32:35], v[184:187], v[220:223], v[32:35]
	s_setprio 0
	s_barrier
	v_readfirstlane_b32 s24, v162
	v_lshl_add_u64 v[172:173], v[240:241], 0, s[38:39]
	s_mov_b32 m0, s24
	v_readfirstlane_b32 s24, v163
	global_load_lds_dwordx4 v[172:173], off
	v_lshl_add_u64 v[172:173], v[242:243], 0, s[38:39]
	s_mov_b32 m0, s24
	s_nop 0
	global_load_lds_dwordx4 v[172:173], off
	s_waitcnt vmcnt(6)
	s_barrier
	s_setprio 1
	s_setprio 0
	s_add_i32 s1, s1, 2
	v_lshl_add_u64 v[134:135], v[134:135], 0, s[40:41]
	v_lshl_add_u64 v[136:137], v[136:137], 0, s[40:41]
	v_lshl_add_u64 v[138:139], v[138:139], 0, s[40:41]
	v_lshl_add_u64 v[140:141], v[140:141], 0, s[40:41]
	v_lshl_add_u64 v[142:143], v[142:143], 0, s[40:41]
	s_cmp_lt_u32 s1, 28
	v_lshl_add_u64 v[144:145], v[144:145], 0, s[40:41]
	s_barrier
	s_cbranch_scc1 .Lqg16_loop
	s_branch .Lqg16_tail

.LBB0_635:
	v_add_u32_e32 v165, s56, v164
	ds_read_b128 v[170:173], v165
	ds_read_b128 v[174:177], v165 offset:1024
	ds_read_b128 v[178:181], v165 offset:2048
	ds_read_b128 v[182:185], v165 offset:3072
	v_add_u32_e32 v166, 0xc000, v151
	v_lshl_add_u64 v[194:195], s[76:77], 0, v[142:143]
	v_readfirstlane_b32 s24, v166
	v_add_u32_e32 v167, 0xe000, v151
	v_lshl_add_u64 v[168:169], v[194:195], 0, s[14:15]
	s_mov_b32 m0, s24
	v_lshl_add_u64 v[236:237], s[76:77], 0, v[144:145]
	v_readfirstlane_b32 s24, v167
	ds_read_b128 v[186:189], v153
	ds_read_b128 v[190:193], v153 offset:1024
	ds_read_b128 v[196:199], v152
	ds_read_b128 v[200:203], v152 offset:1024
	ds_read_b128 v[204:207], v150
	ds_read_b128 v[208:211], v150 offset:1024
	ds_read_b128 v[212:215], v149
	ds_read_b128 v[216:219], v149 offset:1024
	global_load_lds_dwordx4 v[168:169], off
	v_lshl_add_u64 v[168:169], v[236:237], 0, s[14:15]
	s_mov_b32 m0, s24
	s_nop 0
	global_load_lds_dwordx4 v[168:169], off
	s_waitcnt lgkmcnt(8)
	s_barrier
	s_waitcnt lgkmcnt(0)
	s_setprio 1
	v_mfma_f32_16x16x32_bf16 v[124:127], v[170:173], v[186:189], v[124:127]
	v_mfma_f32_16x16x32_bf16 v[120:123], v[178:181], v[186:189], v[120:123]
	v_mfma_f32_16x16x32_bf16 v[116:119], v[170:173], v[196:199], v[116:119]
	v_mfma_f32_16x16x32_bf16 v[112:115], v[178:181], v[196:199], v[112:115]
	v_mfma_f32_16x16x32_bf16 v[108:111], v[170:173], v[204:207], v[108:111]
	v_mfma_f32_16x16x32_bf16 v[104:107], v[178:181], v[204:207], v[104:107]
	v_mfma_f32_16x16x32_bf16 v[100:103], v[170:173], v[212:215], v[100:103]
	v_mfma_f32_16x16x32_bf16 v[96:99], v[178:181], v[212:215], v[96:99]
	v_mfma_f32_16x16x32_bf16 v[124:127], v[174:177], v[190:193], v[124:127]
	v_mfma_f32_16x16x32_bf16 v[120:123], v[182:185], v[190:193], v[120:123]
	v_mfma_f32_16x16x32_bf16 v[116:119], v[174:177], v[200:203], v[116:119]
	v_mfma_f32_16x16x32_bf16 v[112:115], v[182:185], v[200:203], v[112:115]
	v_mfma_f32_16x16x32_bf16 v[108:111], v[174:177], v[208:211], v[108:111]
	v_mfma_f32_16x16x32_bf16 v[104:107], v[182:185], v[208:211], v[104:107]
	v_mfma_f32_16x16x32_bf16 v[100:103], v[174:177], v[216:219], v[100:103]
	v_mfma_f32_16x16x32_bf16 v[96:99], v[182:185], v[216:219], v[96:99]
	s_setprio 0
	s_barrier
	v_lshl_add_u64 v[240:241], s[76:77], 0, v[134:135]
	v_readfirstlane_b32 s24, v148
	v_add_u32_e32 v169, 0x2000, v148
	v_add_u32_e32 v168, s61, v164
	v_lshl_add_u64 v[238:239], v[240:241], 0, s[16:17]
	s_mov_b32 m0, s24
	v_lshl_add_u64 v[242:243], s[76:77], 0, v[136:137]
	v_readfirstlane_b32 s24, v169
	ds_read_b128 v[220:223], v168
	ds_read_b128 v[224:227], v168 offset:1024
	ds_read_b128 v[228:231], v168 offset:2048
	ds_read_b128 v[232:235], v168 offset:3072
	global_load_lds_dwordx4 v[238:239], off
	v_lshl_add_u64 v[238:239], v[242:243], 0, s[16:17]
	s_mov_b32 m0, s24
	s_nop 0
	global_load_lds_dwordx4 v[238:239], off
	s_barrier
	s_waitcnt lgkmcnt(0)
	s_setprio 1
	v_mfma_f32_16x16x32_bf16 v[92:95], v[220:223], v[186:189], v[92:95]
	v_mfma_f32_16x16x32_bf16 v[88:91], v[228:231], v[186:189], v[88:91]
	v_mfma_f32_16x16x32_bf16 v[84:87], v[220:223], v[196:199], v[84:87]
	v_mfma_f32_16x16x32_bf16 v[80:83], v[228:231], v[196:199], v[80:83]
	v_mfma_f32_16x16x32_bf16 v[76:79], v[220:223], v[204:207], v[76:79]
	v_mfma_f32_16x16x32_bf16 v[72:75], v[228:231], v[204:207], v[72:75]
	v_mfma_f32_16x16x32_bf16 v[68:71], v[220:223], v[212:215], v[68:71]
	v_mfma_f32_16x16x32_bf16 v[64:67], v[228:231], v[212:215], v[64:67]
	v_mfma_f32_16x16x32_bf16 v[92:95], v[224:227], v[190:193], v[92:95]
	v_mfma_f32_16x16x32_bf16 v[88:91], v[232:235], v[190:193], v[88:91]
	v_mfma_f32_16x16x32_bf16 v[84:87], v[224:227], v[200:203], v[84:87]
	v_mfma_f32_16x16x32_bf16 v[80:83], v[232:235], v[200:203], v[80:83]
	v_mfma_f32_16x16x32_bf16 v[76:79], v[224:227], v[208:211], v[76:79]
	v_mfma_f32_16x16x32_bf16 v[72:75], v[232:235], v[208:211], v[72:75]
	v_mfma_f32_16x16x32_bf16 v[68:71], v[224:227], v[216:219], v[68:71]
	v_mfma_f32_16x16x32_bf16 v[64:67], v[232:235], v[216:219], v[64:67]
	s_setprio 0
	v_lshl_add_u64 v[244:245], s[76:77], 0, v[138:139]
	v_readfirstlane_b32 s24, v151
	v_lshl_add_u64 v[238:239], v[244:245], 0, s[18:19]
	s_mov_b32 m0, s24
	v_lshl_add_u64 v[246:247], s[76:77], 0, v[140:141]
	v_readfirstlane_b32 s24, v154
	s_barrier
	ds_read_b128 v[186:189], v153 offset:16384
	ds_read_b128 v[190:193], v153 offset:17408
	ds_read_b128 v[196:199], v152 offset:16384
	ds_read_b128 v[200:203], v152 offset:17408
	ds_read_b128 v[204:207], v150 offset:16384
	ds_read_b128 v[208:211], v150 offset:17408
	ds_read_b128 v[212:215], v149 offset:16384
	ds_read_b128 v[216:219], v149 offset:17408
	global_load_lds_dwordx4 v[238:239], off
	v_lshl_add_u64 v[238:239], v[246:247], 0, s[18:19]
	s_mov_b32 m0, s24
	s_nop 0
	global_load_lds_dwordx4 v[238:239], off
	s_barrier
	s_waitcnt lgkmcnt(0)
	s_setprio 1
	v_mfma_f32_16x16x32_bf16 v[60:63], v[170:173], v[186:189], v[60:63]
	v_mfma_f32_16x16x32_bf16 v[56:59], v[178:181], v[186:189], v[56:59]
	v_mfma_f32_16x16x32_bf16 v[52:55], v[170:173], v[196:199], v[52:55]
	v_mfma_f32_16x16x32_bf16 v[48:51], v[178:181], v[196:199], v[48:51]
	v_mfma_f32_16x16x32_bf16 v[44:47], v[170:173], v[204:207], v[44:47]
	v_mfma_f32_16x16x32_bf16 v[40:43], v[178:181], v[204:207], v[40:43]
	v_mfma_f32_16x16x32_bf16 v[36:39], v[170:173], v[212:215], v[36:39]
	v_mfma_f32_16x16x32_bf16 v[32:35], v[178:181], v[212:215], v[32:35]
	v_mfma_f32_16x16x32_bf16 v[60:63], v[174:177], v[190:193], v[60:63]
	v_mfma_f32_16x16x32_bf16 v[56:59], v[182:185], v[190:193], v[56:59]
	v_mfma_f32_16x16x32_bf16 v[52:55], v[174:177], v[200:203], v[52:55]
	v_mfma_f32_16x16x32_bf16 v[48:51], v[182:185], v[200:203], v[48:51]
	v_mfma_f32_16x16x32_bf16 v[44:47], v[174:177], v[208:211], v[44:47]
	v_mfma_f32_16x16x32_bf16 v[40:43], v[182:185], v[208:211], v[40:43]
	v_mfma_f32_16x16x32_bf16 v[36:39], v[174:177], v[216:219], v[36:39]
	v_mfma_f32_16x16x32_bf16 v[32:35], v[182:185], v[216:219], v[32:35]
	s_setprio 0
	s_barrier
	v_readfirstlane_b32 s24, v155
	v_add_u32_e32 v169, 0x2000, v155
	v_lshl_add_u64 v[170:171], v[240:241], 0, s[20:21]
	s_mov_b32 m0, s24
	v_readfirstlane_b32 s24, v169
	global_load_lds_dwordx4 v[170:171], off
	v_lshl_add_u64 v[170:171], v[242:243], 0, s[20:21]
	s_mov_b32 m0, s24
	s_nop 0
	global_load_lds_dwordx4 v[170:171], off
	s_waitcnt vmcnt(6)
	s_barrier
	s_setprio 1
	v_mfma_f32_16x16x32_bf16 v[28:31], v[220:223], v[186:189], v[28:31]
	v_mfma_f32_16x16x32_bf16 v[24:27], v[228:231], v[186:189], v[24:27]
	v_mfma_f32_16x16x32_bf16 v[20:23], v[220:223], v[196:199], v[20:23]
	v_mfma_f32_16x16x32_bf16 v[16:19], v[228:231], v[196:199], v[16:19]
	v_mfma_f32_16x16x32_bf16 v[12:15], v[220:223], v[204:207], v[12:15]
	v_mfma_f32_16x16x32_bf16 v[8:11], v[228:231], v[204:207], v[8:11]
	v_mfma_f32_16x16x32_bf16 v[4:7], v[220:223], v[212:215], v[4:7]
	v_mfma_f32_16x16x32_bf16 v[0:3], v[228:231], v[212:215], v[0:3]
	v_mfma_f32_16x16x32_bf16 v[28:31], v[224:227], v[190:193], v[28:31]
	v_mfma_f32_16x16x32_bf16 v[24:27], v[232:235], v[190:193], v[24:27]
	v_mfma_f32_16x16x32_bf16 v[20:23], v[224:227], v[200:203], v[20:23]
	v_mfma_f32_16x16x32_bf16 v[16:19], v[232:235], v[200:203], v[16:19]
	v_mfma_f32_16x16x32_bf16 v[12:15], v[224:227], v[208:211], v[12:15]
	v_mfma_f32_16x16x32_bf16 v[8:11], v[232:235], v[208:211], v[8:11]
	v_mfma_f32_16x16x32_bf16 v[4:7], v[224:227], v[216:219], v[4:7]
	v_mfma_f32_16x16x32_bf16 v[0:3], v[232:235], v[216:219], v[0:3]
	s_setprio 0
	v_add_u32_e32 v169, s62, v164
	s_barrier
	ds_read_b128 v[172:175], v169
	ds_read_b128 v[176:179], v169 offset:1024
	ds_read_b128 v[180:183], v169 offset:2048
	ds_read_b128 v[184:187], v169 offset:3072
	v_readfirstlane_b32 s24, v156
	v_lshl_add_u64 v[170:171], v[194:195], 0, s[18:19]
	s_mov_b32 m0, s24
	v_readfirstlane_b32 s24, v157
	ds_read_b128 v[188:191], v153 offset:32768
	ds_read_b128 v[196:199], v153 offset:33792
	ds_read_b128 v[200:203], v152 offset:32768
	ds_read_b128 v[204:207], v152 offset:33792
	ds_read_b128 v[208:211], v150 offset:32768
	ds_read_b128 v[212:215], v150 offset:33792
	ds_read_b128 v[216:219], v149 offset:32768
	ds_read_b128 v[220:223], v149 offset:33792
	global_load_lds_dwordx4 v[170:171], off
	v_lshl_add_u64 v[170:171], v[236:237], 0, s[18:19]
	s_mov_b32 m0, s24
	s_nop 0
	global_load_lds_dwordx4 v[170:171], off
	s_waitcnt lgkmcnt(8)
	s_barrier
	s_waitcnt lgkmcnt(0)
	s_setprio 1
	v_mfma_f32_16x16x32_bf16 v[124:127], v[172:175], v[188:191], v[124:127]
	v_mfma_f32_16x16x32_bf16 v[120:123], v[180:183], v[188:191], v[120:123]
	v_mfma_f32_16x16x32_bf16 v[116:119], v[172:175], v[200:203], v[116:119]
	v_mfma_f32_16x16x32_bf16 v[112:115], v[180:183], v[200:203], v[112:115]
	v_mfma_f32_16x16x32_bf16 v[108:111], v[172:175], v[208:211], v[108:111]
	v_mfma_f32_16x16x32_bf16 v[104:107], v[180:183], v[208:211], v[104:107]
	v_mfma_f32_16x16x32_bf16 v[100:103], v[172:175], v[216:219], v[100:103]
	v_mfma_f32_16x16x32_bf16 v[96:99], v[180:183], v[216:219], v[96:99]
	v_mfma_f32_16x16x32_bf16 v[124:127], v[176:179], v[196:199], v[124:127]
	v_mfma_f32_16x16x32_bf16 v[120:123], v[184:187], v[196:199], v[120:123]
	v_mfma_f32_16x16x32_bf16 v[116:119], v[176:179], v[204:207], v[116:119]
	v_mfma_f32_16x16x32_bf16 v[112:115], v[184:187], v[204:207], v[112:115]
	v_mfma_f32_16x16x32_bf16 v[108:111], v[176:179], v[212:215], v[108:111]
	v_mfma_f32_16x16x32_bf16 v[104:107], v[184:187], v[212:215], v[104:107]
	v_mfma_f32_16x16x32_bf16 v[100:103], v[176:179], v[220:223], v[100:103]
	v_mfma_f32_16x16x32_bf16 v[96:99], v[184:187], v[220:223], v[96:99]
	s_setprio 0
	s_barrier
	v_readfirstlane_b32 s24, v158
	v_add_u32_e32 v170, s63, v164
	v_lshl_add_u64 v[192:193], v[240:241], 0, s[22:23]
	s_mov_b32 m0, s24
	v_readfirstlane_b32 s24, v159
	ds_read_b128 v[224:227], v170
	ds_read_b128 v[228:231], v170 offset:1024
	ds_read_b128 v[232:235], v170 offset:2048
	ds_read_b128 v[236:239], v170 offset:3072
	global_load_lds_dwordx4 v[192:193], off
	v_lshl_add_u64 v[192:193], v[242:243], 0, s[22:23]
	s_mov_b32 m0, s24
	s_nop 0
	global_load_lds_dwordx4 v[192:193], off
	s_barrier
	s_waitcnt lgkmcnt(0)
	s_setprio 1
	v_mfma_f32_16x16x32_bf16 v[92:95], v[224:227], v[188:191], v[92:95]
	v_mfma_f32_16x16x32_bf16 v[88:91], v[232:235], v[188:191], v[88:91]
	v_mfma_f32_16x16x32_bf16 v[84:87], v[224:227], v[200:203], v[84:87]
	v_mfma_f32_16x16x32_bf16 v[80:83], v[232:235], v[200:203], v[80:83]
	v_mfma_f32_16x16x32_bf16 v[76:79], v[224:227], v[208:211], v[76:79]
	v_mfma_f32_16x16x32_bf16 v[72:75], v[232:235], v[208:211], v[72:75]
	v_mfma_f32_16x16x32_bf16 v[68:71], v[224:227], v[216:219], v[68:71]
	v_mfma_f32_16x16x32_bf16 v[64:67], v[232:235], v[216:219], v[64:67]
	v_mfma_f32_16x16x32_bf16 v[92:95], v[228:231], v[196:199], v[92:95]
	v_mfma_f32_16x16x32_bf16 v[88:91], v[236:239], v[196:199], v[88:91]
	v_mfma_f32_16x16x32_bf16 v[84:87], v[228:231], v[204:207], v[84:87]
	v_mfma_f32_16x16x32_bf16 v[80:83], v[236:239], v[204:207], v[80:83]
	v_mfma_f32_16x16x32_bf16 v[76:79], v[228:231], v[212:215], v[76:79]
	v_mfma_f32_16x16x32_bf16 v[72:75], v[236:239], v[212:215], v[72:75]
	v_mfma_f32_16x16x32_bf16 v[68:71], v[228:231], v[220:223], v[68:71]
	v_mfma_f32_16x16x32_bf16 v[64:67], v[236:239], v[220:223], v[64:67]
	s_setprio 0
	v_readfirstlane_b32 s24, v160
	v_lshl_add_u64 v[192:193], v[244:245], 0, s[36:37]
	s_mov_b32 m0, s24
	v_readfirstlane_b32 s24, v161
	s_barrier
	ds_read_b128 v[188:191], v153 offset:49152
	ds_read_b128 v[196:199], v153 offset:50176
	ds_read_b128 v[200:203], v152 offset:49152
	ds_read_b128 v[204:207], v152 offset:50176
	ds_read_b128 v[208:211], v150 offset:49152
	ds_read_b128 v[212:215], v150 offset:50176
	ds_read_b128 v[216:219], v149 offset:49152
	ds_read_b128 v[220:223], v149 offset:50176
	global_load_lds_dwordx4 v[192:193], off
	v_lshl_add_u64 v[192:193], v[246:247], 0, s[36:37]
	s_mov_b32 m0, s24
	s_nop 0
	global_load_lds_dwordx4 v[192:193], off
	s_barrier
	s_waitcnt lgkmcnt(0)
	s_setprio 1
	v_mfma_f32_16x16x32_bf16 v[60:63], v[172:175], v[188:191], v[60:63]
	v_mfma_f32_16x16x32_bf16 v[56:59], v[180:183], v[188:191], v[56:59]
	v_mfma_f32_16x16x32_bf16 v[52:55], v[172:175], v[200:203], v[52:55]
	v_mfma_f32_16x16x32_bf16 v[48:51], v[180:183], v[200:203], v[48:51]
	v_mfma_f32_16x16x32_bf16 v[44:47], v[172:175], v[208:211], v[44:47]
	v_mfma_f32_16x16x32_bf16 v[40:43], v[180:183], v[208:211], v[40:43]
	v_mfma_f32_16x16x32_bf16 v[36:39], v[172:175], v[216:219], v[36:39]
	v_mfma_f32_16x16x32_bf16 v[32:35], v[180:183], v[216:219], v[32:35]
	v_mfma_f32_16x16x32_bf16 v[60:63], v[176:179], v[196:199], v[60:63]
	v_mfma_f32_16x16x32_bf16 v[56:59], v[184:187], v[196:199], v[56:59]
	v_mfma_f32_16x16x32_bf16 v[52:55], v[176:179], v[204:207], v[52:55]
	v_mfma_f32_16x16x32_bf16 v[48:51], v[184:187], v[204:207], v[48:51]
	v_mfma_f32_16x16x32_bf16 v[44:47], v[176:179], v[212:215], v[44:47]
	v_mfma_f32_16x16x32_bf16 v[40:43], v[184:187], v[212:215], v[40:43]
	v_mfma_f32_16x16x32_bf16 v[36:39], v[176:179], v[220:223], v[36:39]
	v_mfma_f32_16x16x32_bf16 v[32:35], v[184:187], v[220:223], v[32:35]
	s_setprio 0
	s_barrier
	v_readfirstlane_b32 s24, v162
	v_lshl_add_u64 v[172:173], v[240:241], 0, s[38:39]
	s_mov_b32 m0, s24
	v_readfirstlane_b32 s24, v163
	global_load_lds_dwordx4 v[172:173], off
	v_lshl_add_u64 v[172:173], v[242:243], 0, s[38:39]
	s_mov_b32 m0, s24
	s_nop 0
	global_load_lds_dwordx4 v[172:173], off
	s_waitcnt vmcnt(6)
	s_barrier
	s_setprio 1
	v_mfma_f32_16x16x32_bf16 v[28:31], v[224:227], v[188:191], v[28:31]
	v_mfma_f32_16x16x32_bf16 v[24:27], v[232:235], v[188:191], v[24:27]
	v_mfma_f32_16x16x32_bf16 v[20:23], v[224:227], v[200:203], v[20:23]
	v_mfma_f32_16x16x32_bf16 v[16:19], v[232:235], v[200:203], v[16:19]
	v_mfma_f32_16x16x32_bf16 v[12:15], v[224:227], v[208:211], v[12:15]
	v_mfma_f32_16x16x32_bf16 v[8:11], v[232:235], v[208:211], v[8:11]
	v_mfma_f32_16x16x32_bf16 v[4:7], v[224:227], v[216:219], v[4:7]
	v_mfma_f32_16x16x32_bf16 v[0:3], v[232:235], v[216:219], v[0:3]
	v_mfma_f32_16x16x32_bf16 v[28:31], v[228:231], v[196:199], v[28:31]
	v_mfma_f32_16x16x32_bf16 v[24:27], v[236:239], v[196:199], v[24:27]
	v_mfma_f32_16x16x32_bf16 v[20:23], v[228:231], v[204:207], v[20:23]
	v_mfma_f32_16x16x32_bf16 v[16:19], v[236:239], v[204:207], v[16:19]
	v_mfma_f32_16x16x32_bf16 v[12:15], v[228:231], v[212:215], v[12:15]
	v_mfma_f32_16x16x32_bf16 v[8:11], v[236:239], v[212:215], v[8:11]
	v_mfma_f32_16x16x32_bf16 v[4:7], v[228:231], v[220:223], v[4:7]
	v_mfma_f32_16x16x32_bf16 v[0:3], v[236:239], v[220:223], v[0:3]
	s_setprio 0
	s_add_i32 s1, s1, 2
	v_lshl_add_u64 v[134:135], v[134:135], 0, s[40:41]
	v_lshl_add_u64 v[136:137], v[136:137], 0, s[40:41]
	v_lshl_add_u64 v[138:139], v[138:139], 0, s[40:41]
	v_lshl_add_u64 v[140:141], v[140:141], 0, s[40:41]
	v_lshl_add_u64 v[142:143], v[142:143], 0, s[40:41]
	s_cmp_lt_u32 s1, 28
	v_lshl_add_u64 v[144:145], v[144:145], 0, s[40:41]
	s_barrier
	s_cbranch_scc1 .LBB0_635
.Lqg16_tail:
	v_readfirstlane_b32 s1, v166
	v_lshl_add_u64 v[130:131], v[130:131], 0, s[42:43]
	s_mov_b32 m0, s1
	v_readfirstlane_b32 s1, v167
	ds_read_b128 v[134:137], v165
	ds_read_b128 v[138:141], v165 offset:1024
	ds_read_b128 v[142:145], v165 offset:2048
	ds_read_b128 v[154:157], v165 offset:3072
	ds_read_b128 v[158:161], v153
	ds_read_b128 v[162:165], v153 offset:1024
	ds_read_b128 v[172:175], v152
	ds_read_b128 v[176:179], v152 offset:1024
	ds_read_b128 v[180:183], v150
	ds_read_b128 v[184:187], v150 offset:1024
	ds_read_b128 v[188:191], v149
	ds_read_b128 v[196:199], v149 offset:1024
	global_load_lds_dwordx4 v[130:131], off
	v_lshl_add_u64 v[130:131], v[132:133], 0, s[42:43]
	s_mov_b32 m0, s1
	s_nop 0
	global_load_lds_dwordx4 v[130:131], off
	s_barrier
	s_waitcnt lgkmcnt(0)
	s_setprio 1
	v_mfma_f32_16x16x32_bf16 v[124:127], v[134:137], v[158:161], v[124:127]
	v_mfma_f32_16x16x32_bf16 v[116:119], v[134:137], v[172:175], v[116:119]
	v_mfma_f32_16x16x32_bf16 v[108:111], v[134:137], v[180:183], v[108:111]
	v_mfma_f32_16x16x32_bf16 v[100:103], v[134:137], v[188:191], v[100:103]
	v_mfma_f32_16x16x32_bf16 v[124:127], v[138:141], v[162:165], v[124:127]
	v_mfma_f32_16x16x32_bf16 v[120:123], v[142:145], v[158:161], v[120:123]
	v_mfma_f32_16x16x32_bf16 v[116:119], v[138:141], v[176:179], v[116:119]
	v_mfma_f32_16x16x32_bf16 v[112:115], v[142:145], v[172:175], v[112:115]
	v_mfma_f32_16x16x32_bf16 v[108:111], v[138:141], v[184:187], v[108:111]
	v_mfma_f32_16x16x32_bf16 v[104:107], v[142:145], v[180:183], v[104:107]
	v_mfma_f32_16x16x32_bf16 v[100:103], v[138:141], v[196:199], v[100:103]
	v_mfma_f32_16x16x32_bf16 v[96:99], v[142:145], v[188:191], v[96:99]
	v_mfma_f32_16x16x32_bf16 v[130:133], v[154:157], v[162:165], v[120:123]
	v_mfma_f32_16x16x32_bf16 v[200:203], v[154:157], v[176:179], v[112:115]
	v_mfma_f32_16x16x32_bf16 v[204:207], v[154:157], v[184:187], v[104:107]
	v_mfma_f32_16x16x32_bf16 v[208:211], v[154:157], v[196:199], v[96:99]
	s_setprio 0
	s_barrier
	s_nop 1
	ds_read_b128 v[96:99], v168
	ds_read_b128 v[104:107], v168 offset:1024
	ds_read_b128 v[112:115], v168 offset:2048
	ds_read_b128 v[120:123], v168 offset:3072
	s_barrier
	s_waitcnt lgkmcnt(0)
	s_setprio 1
	v_mfma_f32_16x16x32_bf16 v[92:95], v[96:99], v[158:161], v[92:95]
	v_mfma_f32_16x16x32_bf16 v[84:87], v[96:99], v[172:175], v[84:87]
	v_mfma_f32_16x16x32_bf16 v[76:79], v[96:99], v[180:183], v[76:79]
	v_mfma_f32_16x16x32_bf16 v[68:71], v[96:99], v[188:191], v[68:71]
	v_mfma_f32_16x16x32_bf16 v[92:95], v[104:107], v[162:165], v[92:95]
	v_mfma_f32_16x16x32_bf16 v[88:91], v[112:115], v[158:161], v[88:91]
	v_mfma_f32_16x16x32_bf16 v[84:87], v[104:107], v[176:179], v[84:87]
	v_mfma_f32_16x16x32_bf16 v[80:83], v[112:115], v[172:175], v[80:83]
	v_mfma_f32_16x16x32_bf16 v[76:79], v[104:107], v[184:187], v[76:79]
	v_mfma_f32_16x16x32_bf16 v[72:75], v[112:115], v[180:183], v[72:75]
	v_mfma_f32_16x16x32_bf16 v[68:71], v[104:107], v[196:199], v[68:71]
	v_mfma_f32_16x16x32_bf16 v[64:67], v[112:115], v[188:191], v[64:67]
	v_mfma_f32_16x16x32_bf16 v[158:161], v[120:123], v[162:165], v[88:91]
	v_mfma_f32_16x16x32_bf16 v[162:165], v[120:123], v[176:179], v[80:83]
	v_mfma_f32_16x16x32_bf16 v[172:175], v[120:123], v[184:187], v[72:75]
	v_mfma_f32_16x16x32_bf16 v[176:179], v[120:123], v[196:199], v[64:67]
	s_setprio 0
	s_barrier
	s_nop 1
	ds_read_b128 v[64:67], v153 offset:16384
	ds_read_b128 v[72:75], v153 offset:17408
	ds_read_b128 v[80:83], v152 offset:16384
	ds_read_b128 v[88:91], v152 offset:17408
	ds_read_b128 v[180:183], v150 offset:16384
	ds_read_b128 v[184:187], v150 offset:17408
	ds_read_b128 v[188:191], v149 offset:16384
	ds_read_b128 v[196:199], v149 offset:17408
	s_waitcnt vmcnt(4)
	s_barrier
	s_waitcnt lgkmcnt(0)
	s_setprio 1
	v_mfma_f32_16x16x32_bf16 v[60:63], v[134:137], v[64:67], v[60:63]
	v_mfma_f32_16x16x32_bf16 v[52:55], v[134:137], v[80:83], v[52:55]
	v_mfma_f32_16x16x32_bf16 v[44:47], v[134:137], v[180:183], v[44:47]
	v_mfma_f32_16x16x32_bf16 v[36:39], v[134:137], v[188:191], v[36:39]
	v_mfma_f32_16x16x32_bf16 v[60:63], v[138:141], v[72:75], v[60:63]
	v_mfma_f32_16x16x32_bf16 v[56:59], v[142:145], v[64:67], v[56:59]
	v_mfma_f32_16x16x32_bf16 v[52:55], v[138:141], v[88:91], v[52:55]
	v_mfma_f32_16x16x32_bf16 v[48:51], v[142:145], v[80:83], v[48:51]
	v_mfma_f32_16x16x32_bf16 v[44:47], v[138:141], v[184:187], v[44:47]
	v_mfma_f32_16x16x32_bf16 v[40:43], v[142:145], v[180:183], v[40:43]
	v_mfma_f32_16x16x32_bf16 v[36:39], v[138:141], v[196:199], v[36:39]
	v_mfma_f32_16x16x32_bf16 v[32:35], v[142:145], v[188:191], v[32:35]
	v_mfma_f32_16x16x32_bf16 v[212:215], v[154:157], v[72:75], v[56:59]
	v_mfma_f32_16x16x32_bf16 v[216:219], v[154:157], v[88:91], v[48:51]
	v_mfma_f32_16x16x32_bf16 v[220:223], v[154:157], v[184:187], v[40:43]
	v_mfma_f32_16x16x32_bf16 v[134:137], v[154:157], v[196:199], v[32:35]
	s_setprio 0
	s_setprio 1
	v_mfma_f32_16x16x32_bf16 v[28:31], v[96:99], v[64:67], v[28:31]
	v_mfma_f32_16x16x32_bf16 v[20:23], v[96:99], v[80:83], v[20:23]
	v_mfma_f32_16x16x32_bf16 v[12:15], v[96:99], v[180:183], v[12:15]
	v_mfma_f32_16x16x32_bf16 v[4:7], v[96:99], v[188:191], v[4:7]
	v_mfma_f32_16x16x32_bf16 v[28:31], v[104:107], v[72:75], v[28:31]
	v_mfma_f32_16x16x32_bf16 v[24:27], v[112:115], v[64:67], v[24:27]
	v_mfma_f32_16x16x32_bf16 v[20:23], v[104:107], v[88:91], v[20:23]
	v_mfma_f32_16x16x32_bf16 v[16:19], v[112:115], v[80:83], v[16:19]
	v_mfma_f32_16x16x32_bf16 v[12:15], v[104:107], v[184:187], v[12:15]
	v_mfma_f32_16x16x32_bf16 v[8:11], v[112:115], v[180:183], v[8:11]
	v_mfma_f32_16x16x32_bf16 v[4:7], v[104:107], v[196:199], v[4:7]
	v_mfma_f32_16x16x32_bf16 v[0:3], v[112:115], v[188:191], v[0:3]
	v_mfma_f32_16x16x32_bf16 v[138:141], v[120:123], v[72:75], v[24:27]
	v_mfma_f32_16x16x32_bf16 v[142:145], v[120:123], v[88:91], v[16:19]
	v_mfma_f32_16x16x32_bf16 v[154:157], v[120:123], v[184:187], v[8:11]
	v_mfma_f32_16x16x32_bf16 v[180:183], v[120:123], v[196:199], v[0:3]
	s_setprio 0
	s_barrier
	s_nop 1
	ds_read_b128 v[0:3], v169
	ds_read_b128 v[8:11], v169 offset:1024
	ds_read_b128 v[16:19], v169 offset:2048
	ds_read_b128 v[24:27], v169 offset:3072
	ds_read_b128 v[32:35], v153 offset:32768
	ds_read_b128 v[40:43], v153 offset:33792
	ds_read_b128 v[48:51], v152 offset:32768
	ds_read_b128 v[56:59], v152 offset:33792
	ds_read_b128 v[64:67], v150 offset:32768
	ds_read_b128 v[166:169], v150 offset:33792
	ds_read_b128 v[184:187], v149 offset:32768
	ds_read_b128 v[188:191], v149 offset:33792
	s_waitcnt vmcnt(2)
	s_barrier
	s_waitcnt lgkmcnt(0)
	s_setprio 1
	v_mfma_f32_16x16x32_bf16 v[72:75], v[0:3], v[32:35], v[124:127]
	v_mfma_f32_16x16x32_bf16 v[120:123], v[8:11], v[40:43], v[72:75]
	v_mfma_f32_16x16x32_bf16 v[72:75], v[16:19], v[32:35], v[130:133]
	v_mfma_f32_16x16x32_bf16 v[124:127], v[24:27], v[40:43], v[72:75]
	v_mfma_f32_16x16x32_bf16 v[72:75], v[0:3], v[48:51], v[116:119]
	v_mfma_f32_16x16x32_bf16 v[112:115], v[8:11], v[56:59], v[72:75]
	v_mfma_f32_16x16x32_bf16 v[72:75], v[16:19], v[48:51], v[200:203]
	v_mfma_f32_16x16x32_bf16 v[116:119], v[24:27], v[56:59], v[72:75]
	v_mfma_f32_16x16x32_bf16 v[72:75], v[0:3], v[64:67], v[108:111]
	v_mfma_f32_16x16x32_bf16 v[104:107], v[8:11], v[166:169], v[72:75]
	v_mfma_f32_16x16x32_bf16 v[72:75], v[16:19], v[64:67], v[204:207]
	v_mfma_f32_16x16x32_bf16 v[108:111], v[24:27], v[166:169], v[72:75]
	v_mfma_f32_16x16x32_bf16 v[72:75], v[0:3], v[184:187], v[100:103]
	v_mfma_f32_16x16x32_bf16 v[96:99], v[8:11], v[188:191], v[72:75]
	v_mfma_f32_16x16x32_bf16 v[72:75], v[16:19], v[184:187], v[208:211]
	v_mfma_f32_16x16x32_bf16 v[100:103], v[24:27], v[188:191], v[72:75]
	s_setprio 0
	s_barrier
	ds_read_b128 v[130:133], v170
	ds_read_b128 v[196:199], v170 offset:1024
	ds_read_b128 v[200:203], v170 offset:2048
	ds_read_b128 v[204:207], v170 offset:3072
	s_waitcnt vmcnt(0)
	s_barrier
	s_waitcnt lgkmcnt(0)
	s_setprio 1
	v_mfma_f32_16x16x32_bf16 v[72:75], v[130:133], v[32:35], v[92:95]
	v_mfma_f32_16x16x32_bf16 v[32:35], v[200:203], v[32:35], v[158:161]
	v_mfma_f32_16x16x32_bf16 v[92:95], v[204:207], v[40:43], v[32:35]
	v_mfma_f32_16x16x32_bf16 v[32:35], v[130:133], v[48:51], v[84:87]
	v_mfma_f32_16x16x32_bf16 v[80:83], v[196:199], v[56:59], v[32:35]
	v_mfma_f32_16x16x32_bf16 v[32:35], v[200:203], v[48:51], v[162:165]
	v_mfma_f32_16x16x32_bf16 v[84:87], v[204:207], v[56:59], v[32:35]
	v_mfma_f32_16x16x32_bf16 v[32:35], v[130:133], v[64:67], v[76:79]
	v_mfma_f32_16x16x32_bf16 v[88:91], v[196:199], v[40:43], v[72:75]
	v_mfma_f32_16x16x32_bf16 v[72:75], v[196:199], v[166:169], v[32:35]
	v_mfma_f32_16x16x32_bf16 v[32:35], v[200:203], v[64:67], v[172:175]
	v_mfma_f32_16x16x32_bf16 v[76:79], v[204:207], v[166:169], v[32:35]
	v_mfma_f32_16x16x32_bf16 v[32:35], v[130:133], v[184:187], v[68:71]
	v_mfma_f32_16x16x32_bf16 v[64:67], v[196:199], v[188:191], v[32:35]
	v_mfma_f32_16x16x32_bf16 v[32:35], v[200:203], v[184:187], v[176:179]
	v_mfma_f32_16x16x32_bf16 v[68:71], v[204:207], v[188:191], v[32:35]
	s_setprio 0
	s_barrier
	ds_read_b128 v[158:161], v153 offset:49152
	ds_read_b128 v[162:165], v153 offset:50176
	ds_read_b128 v[166:169], v152 offset:49152
	ds_read_b128 v[170:173], v152 offset:50176
	ds_read_b128 v[174:177], v150 offset:49152
	ds_read_b128 v[150:153], v150 offset:50176
	ds_read_b128 v[184:187], v149 offset:49152
	ds_read_b128 v[188:191], v149 offset:50176
	s_barrier
	s_waitcnt lgkmcnt(0)
	s_setprio 1
	v_mfma_f32_16x16x32_bf16 v[32:35], v[0:3], v[158:161], v[60:63]
	v_mfma_f32_16x16x32_bf16 v[56:59], v[8:11], v[162:165], v[32:35]
	v_mfma_f32_16x16x32_bf16 v[32:35], v[16:19], v[158:161], v[212:215]
	v_mfma_f32_16x16x32_bf16 v[60:63], v[24:27], v[162:165], v[32:35]
	v_mfma_f32_16x16x32_bf16 v[32:35], v[0:3], v[166:169], v[52:55]
	v_mfma_f32_16x16x32_bf16 v[48:51], v[8:11], v[170:173], v[32:35]
	v_mfma_f32_16x16x32_bf16 v[32:35], v[16:19], v[166:169], v[216:219]
	v_mfma_f32_16x16x32_bf16 v[52:55], v[24:27], v[170:173], v[32:35]
	v_mfma_f32_16x16x32_bf16 v[32:35], v[0:3], v[174:177], v[44:47]
	v_mfma_f32_16x16x32_bf16 v[40:43], v[8:11], v[150:153], v[32:35]
	v_mfma_f32_16x16x32_bf16 v[32:35], v[16:19], v[174:177], v[220:223]
	v_mfma_f32_16x16x32_bf16 v[0:3], v[0:3], v[184:187], v[36:39]
	v_mfma_f32_16x16x32_bf16 v[44:47], v[24:27], v[150:153], v[32:35]
	v_mfma_f32_16x16x32_bf16 v[32:35], v[8:11], v[188:191], v[0:3]
	v_mfma_f32_16x16x32_bf16 v[0:3], v[16:19], v[184:187], v[134:137]
	v_mfma_f32_16x16x32_bf16 v[36:39], v[24:27], v[188:191], v[0:3]
	s_setprio 0
	s_setprio 1
	v_mfma_f32_16x16x32_bf16 v[0:3], v[130:133], v[158:161], v[28:31]
	v_mfma_f32_16x16x32_bf16 v[24:27], v[196:199], v[162:165], v[0:3]
	v_mfma_f32_16x16x32_bf16 v[0:3], v[200:203], v[158:161], v[138:141]
	v_mfma_f32_16x16x32_bf16 v[28:31], v[204:207], v[162:165], v[0:3]
	v_mfma_f32_16x16x32_bf16 v[0:3], v[130:133], v[166:169], v[20:23]
	v_mfma_f32_16x16x32_bf16 v[16:19], v[196:199], v[170:173], v[0:3]
	v_mfma_f32_16x16x32_bf16 v[0:3], v[200:203], v[166:169], v[142:145]
	v_mfma_f32_16x16x32_bf16 v[20:23], v[204:207], v[170:173], v[0:3]
	v_mfma_f32_16x16x32_bf16 v[0:3], v[130:133], v[174:177], v[12:15]
	v_mfma_f32_16x16x32_bf16 v[8:11], v[196:199], v[150:153], v[0:3]
	v_mfma_f32_16x16x32_bf16 v[0:3], v[200:203], v[174:177], v[154:157]
	v_mfma_f32_16x16x32_bf16 v[12:15], v[204:207], v[150:153], v[0:3]
	v_mfma_f32_16x16x32_bf16 v[0:3], v[130:133], v[184:187], v[4:7]
	v_mfma_f32_16x16x32_bf16 v[4:7], v[200:203], v[184:187], v[180:183]
	v_mfma_f32_16x16x32_bf16 v[0:3], v[196:199], v[188:191], v[0:3]
	v_mfma_f32_16x16x32_bf16 v[4:7], v[204:207], v[188:191], v[4:7]
	s_setprio 0
	v_readlane_b32 s24, v253, 16
	v_readlane_b32 s25, v253, 17
	s_andn2_b64 vcc, exec, s[24:25]
	s_barrier
	s_cbranch_vccnz .LBB0_638
	s_barrier

.LBB0_680:
	v_add_u32_e32 v165, s56, v164
	ds_read_b128 v[170:173], v165
	ds_read_b128 v[174:177], v165 offset:1024
	ds_read_b128 v[178:181], v165 offset:2048
	ds_read_b128 v[182:185], v165 offset:3072
	v_add_u32_e32 v166, 0xc000, v153
	v_lshl_add_u64 v[194:195], s[76:77], 0, v[142:143]
	v_readfirstlane_b32 s28, v166
	v_add_u32_e32 v167, 0xe000, v153
	v_lshl_add_u64 v[168:169], v[194:195], 0, s[14:15]
	s_mov_b32 m0, s28
	v_lshl_add_u64 v[236:237], s[76:77], 0, v[144:145]
	v_readfirstlane_b32 s28, v167
	ds_read_b128 v[186:189], v152
	ds_read_b128 v[190:193], v152 offset:1024
	ds_read_b128 v[196:199], v151
	ds_read_b128 v[200:203], v151 offset:1024
	ds_read_b128 v[204:207], v150
	ds_read_b128 v[208:211], v150 offset:1024
	ds_read_b128 v[212:215], v149
	ds_read_b128 v[216:219], v149 offset:1024
	global_load_lds_dwordx4 v[168:169], off
	v_lshl_add_u64 v[168:169], v[236:237], 0, s[14:15]
	s_mov_b32 m0, s28
	s_nop 0
	global_load_lds_dwordx4 v[168:169], off
	s_waitcnt lgkmcnt(8)
	s_barrier
	s_waitcnt lgkmcnt(0)
	s_setprio 1
	v_mfma_f32_16x16x32_bf16 v[124:127], v[170:173], v[186:189], v[124:127]
	v_mfma_f32_16x16x32_bf16 v[120:123], v[178:181], v[186:189], v[120:123]
	v_mfma_f32_16x16x32_bf16 v[116:119], v[170:173], v[196:199], v[116:119]
	v_mfma_f32_16x16x32_bf16 v[112:115], v[178:181], v[196:199], v[112:115]
	v_mfma_f32_16x16x32_bf16 v[108:111], v[170:173], v[204:207], v[108:111]
	v_mfma_f32_16x16x32_bf16 v[104:107], v[178:181], v[204:207], v[104:107]
	v_mfma_f32_16x16x32_bf16 v[100:103], v[170:173], v[212:215], v[100:103]
	v_mfma_f32_16x16x32_bf16 v[96:99], v[178:181], v[212:215], v[96:99]
	v_mfma_f32_16x16x32_bf16 v[124:127], v[174:177], v[190:193], v[124:127]
	v_mfma_f32_16x16x32_bf16 v[120:123], v[182:185], v[190:193], v[120:123]
	v_mfma_f32_16x16x32_bf16 v[116:119], v[174:177], v[200:203], v[116:119]
	v_mfma_f32_16x16x32_bf16 v[112:115], v[182:185], v[200:203], v[112:115]
	v_mfma_f32_16x16x32_bf16 v[108:111], v[174:177], v[208:211], v[108:111]
	v_mfma_f32_16x16x32_bf16 v[104:107], v[182:185], v[208:211], v[104:107]
	v_mfma_f32_16x16x32_bf16 v[100:103], v[174:177], v[216:219], v[100:103]
	v_mfma_f32_16x16x32_bf16 v[96:99], v[182:185], v[216:219], v[96:99]
	s_setprio 0
	s_barrier
	v_lshl_add_u64 v[240:241], s[76:77], 0, v[134:135]
	v_readfirstlane_b32 s28, v148
	v_add_u32_e32 v169, 0x2000, v148
	v_add_u32_e32 v168, s61, v164
	v_lshl_add_u64 v[238:239], v[240:241], 0, s[44:45]
	s_mov_b32 m0, s28
	v_lshl_add_u64 v[242:243], s[76:77], 0, v[136:137]
	v_readfirstlane_b32 s28, v169
	ds_read_b128 v[220:223], v168
	ds_read_b128 v[224:227], v168 offset:1024
	ds_read_b128 v[228:231], v168 offset:2048
	ds_read_b128 v[232:235], v168 offset:3072
	global_load_lds_dwordx4 v[238:239], off
	v_lshl_add_u64 v[238:239], v[242:243], 0, s[44:45]
	s_mov_b32 m0, s28
	s_nop 0
	global_load_lds_dwordx4 v[238:239], off
	s_barrier
	s_waitcnt lgkmcnt(0)
	s_setprio 1
	v_mfma_f32_16x16x32_bf16 v[92:95], v[220:223], v[186:189], v[92:95]
	v_mfma_f32_16x16x32_bf16 v[88:91], v[228:231], v[186:189], v[88:91]
	v_mfma_f32_16x16x32_bf16 v[84:87], v[220:223], v[196:199], v[84:87]
	v_mfma_f32_16x16x32_bf16 v[80:83], v[228:231], v[196:199], v[80:83]
	v_mfma_f32_16x16x32_bf16 v[76:79], v[220:223], v[204:207], v[76:79]
	v_mfma_f32_16x16x32_bf16 v[72:75], v[228:231], v[204:207], v[72:75]
	v_mfma_f32_16x16x32_bf16 v[68:71], v[220:223], v[212:215], v[68:71]
	v_mfma_f32_16x16x32_bf16 v[64:67], v[228:231], v[212:215], v[64:67]
	v_mfma_f32_16x16x32_bf16 v[92:95], v[224:227], v[190:193], v[92:95]
	v_mfma_f32_16x16x32_bf16 v[88:91], v[232:235], v[190:193], v[88:91]
	v_mfma_f32_16x16x32_bf16 v[84:87], v[224:227], v[200:203], v[84:87]
	v_mfma_f32_16x16x32_bf16 v[80:83], v[232:235], v[200:203], v[80:83]
	v_mfma_f32_16x16x32_bf16 v[76:79], v[224:227], v[208:211], v[76:79]
	v_mfma_f32_16x16x32_bf16 v[72:75], v[232:235], v[208:211], v[72:75]
	v_mfma_f32_16x16x32_bf16 v[68:71], v[224:227], v[216:219], v[68:71]
	v_mfma_f32_16x16x32_bf16 v[64:67], v[232:235], v[216:219], v[64:67]
	s_setprio 0
	v_lshl_add_u64 v[244:245], s[76:77], 0, v[138:139]
	v_readfirstlane_b32 s28, v153
	v_lshl_add_u64 v[238:239], v[244:245], 0, s[18:19]
	s_mov_b32 m0, s28
	v_lshl_add_u64 v[246:247], s[76:77], 0, v[140:141]
	v_readfirstlane_b32 s28, v154
	s_barrier
	ds_read_b128 v[186:189], v152 offset:16384
	ds_read_b128 v[190:193], v152 offset:17408
	ds_read_b128 v[196:199], v151 offset:16384
	ds_read_b128 v[200:203], v151 offset:17408
	ds_read_b128 v[204:207], v150 offset:16384
	ds_read_b128 v[208:211], v150 offset:17408
	ds_read_b128 v[212:215], v149 offset:16384
	ds_read_b128 v[216:219], v149 offset:17408
	global_load_lds_dwordx4 v[238:239], off
	v_lshl_add_u64 v[238:239], v[246:247], 0, s[18:19]
	s_mov_b32 m0, s28
	s_nop 0
	global_load_lds_dwordx4 v[238:239], off
	s_barrier
	s_waitcnt lgkmcnt(0)
	s_setprio 1
	v_mfma_f32_16x16x32_bf16 v[60:63], v[170:173], v[186:189], v[60:63]
	v_mfma_f32_16x16x32_bf16 v[56:59], v[178:181], v[186:189], v[56:59]
	v_mfma_f32_16x16x32_bf16 v[52:55], v[170:173], v[196:199], v[52:55]
	v_mfma_f32_16x16x32_bf16 v[48:51], v[178:181], v[196:199], v[48:51]
	v_mfma_f32_16x16x32_bf16 v[44:47], v[170:173], v[204:207], v[44:47]
	v_mfma_f32_16x16x32_bf16 v[40:43], v[178:181], v[204:207], v[40:43]
	v_mfma_f32_16x16x32_bf16 v[36:39], v[170:173], v[212:215], v[36:39]
	v_mfma_f32_16x16x32_bf16 v[32:35], v[178:181], v[212:215], v[32:35]
	v_mfma_f32_16x16x32_bf16 v[60:63], v[174:177], v[190:193], v[60:63]
	v_mfma_f32_16x16x32_bf16 v[56:59], v[182:185], v[190:193], v[56:59]
	v_mfma_f32_16x16x32_bf16 v[52:55], v[174:177], v[200:203], v[52:55]
	v_mfma_f32_16x16x32_bf16 v[48:51], v[182:185], v[200:203], v[48:51]
	v_mfma_f32_16x16x32_bf16 v[44:47], v[174:177], v[208:211], v[44:47]
	v_mfma_f32_16x16x32_bf16 v[40:43], v[182:185], v[208:211], v[40:43]
	v_mfma_f32_16x16x32_bf16 v[36:39], v[174:177], v[216:219], v[36:39]
	v_mfma_f32_16x16x32_bf16 v[32:35], v[182:185], v[216:219], v[32:35]
	s_setprio 0
	s_barrier
	v_readfirstlane_b32 s28, v155
	v_add_u32_e32 v169, 0x2000, v155
	v_lshl_add_u64 v[170:171], v[240:241], 0, s[46:47]
	s_mov_b32 m0, s28
	v_readfirstlane_b32 s28, v169
	global_load_lds_dwordx4 v[170:171], off
	v_lshl_add_u64 v[170:171], v[242:243], 0, s[46:47]
	s_mov_b32 m0, s28
	s_nop 0
	global_load_lds_dwordx4 v[170:171], off
	s_waitcnt vmcnt(6)
	s_barrier
	s_setprio 1
	v_mfma_f32_16x16x32_bf16 v[28:31], v[220:223], v[186:189], v[28:31]
	v_mfma_f32_16x16x32_bf16 v[24:27], v[228:231], v[186:189], v[24:27]
	v_mfma_f32_16x16x32_bf16 v[20:23], v[220:223], v[196:199], v[20:23]
	v_mfma_f32_16x16x32_bf16 v[16:19], v[228:231], v[196:199], v[16:19]
	v_mfma_f32_16x16x32_bf16 v[12:15], v[220:223], v[204:207], v[12:15]
	v_mfma_f32_16x16x32_bf16 v[8:11], v[228:231], v[204:207], v[8:11]
	v_mfma_f32_16x16x32_bf16 v[4:7], v[220:223], v[212:215], v[4:7]
	v_mfma_f32_16x16x32_bf16 v[0:3], v[228:231], v[212:215], v[0:3]
	v_mfma_f32_16x16x32_bf16 v[28:31], v[224:227], v[190:193], v[28:31]
	v_mfma_f32_16x16x32_bf16 v[24:27], v[232:235], v[190:193], v[24:27]
	v_mfma_f32_16x16x32_bf16 v[20:23], v[224:227], v[200:203], v[20:23]
	v_mfma_f32_16x16x32_bf16 v[16:19], v[232:235], v[200:203], v[16:19]
	v_mfma_f32_16x16x32_bf16 v[12:15], v[224:227], v[208:211], v[12:15]
	v_mfma_f32_16x16x32_bf16 v[8:11], v[232:235], v[208:211], v[8:11]
	v_mfma_f32_16x16x32_bf16 v[4:7], v[224:227], v[216:219], v[4:7]
	v_mfma_f32_16x16x32_bf16 v[0:3], v[232:235], v[216:219], v[0:3]
	s_setprio 0
	v_add_u32_e32 v169, s62, v164
	s_barrier
	ds_read_b128 v[172:175], v169
	ds_read_b128 v[176:179], v169 offset:1024
	ds_read_b128 v[180:183], v169 offset:2048
	ds_read_b128 v[184:187], v169 offset:3072
	v_readfirstlane_b32 s28, v156
	v_lshl_add_u64 v[170:171], v[194:195], 0, s[18:19]
	s_mov_b32 m0, s28
	v_readfirstlane_b32 s28, v157
	ds_read_b128 v[188:191], v152 offset:32768
	ds_read_b128 v[196:199], v152 offset:33792
	ds_read_b128 v[200:203], v151 offset:32768
	ds_read_b128 v[204:207], v151 offset:33792
	ds_read_b128 v[208:211], v150 offset:32768
	ds_read_b128 v[212:215], v150 offset:33792
	ds_read_b128 v[216:219], v149 offset:32768
	ds_read_b128 v[220:223], v149 offset:33792
	global_load_lds_dwordx4 v[170:171], off
	v_lshl_add_u64 v[170:171], v[236:237], 0, s[18:19]
	s_mov_b32 m0, s28
	s_nop 0
	global_load_lds_dwordx4 v[170:171], off
	s_waitcnt lgkmcnt(8)
	s_barrier
	s_waitcnt lgkmcnt(0)
	s_setprio 1
	v_mfma_f32_16x16x32_bf16 v[124:127], v[172:175], v[188:191], v[124:127]
	v_mfma_f32_16x16x32_bf16 v[120:123], v[180:183], v[188:191], v[120:123]
	v_mfma_f32_16x16x32_bf16 v[116:119], v[172:175], v[200:203], v[116:119]
	v_mfma_f32_16x16x32_bf16 v[112:115], v[180:183], v[200:203], v[112:115]
	v_mfma_f32_16x16x32_bf16 v[108:111], v[172:175], v[208:211], v[108:111]
	v_mfma_f32_16x16x32_bf16 v[104:107], v[180:183], v[208:211], v[104:107]
	v_mfma_f32_16x16x32_bf16 v[100:103], v[172:175], v[216:219], v[100:103]
	v_mfma_f32_16x16x32_bf16 v[96:99], v[180:183], v[216:219], v[96:99]
	v_mfma_f32_16x16x32_bf16 v[124:127], v[176:179], v[196:199], v[124:127]
	v_mfma_f32_16x16x32_bf16 v[120:123], v[184:187], v[196:199], v[120:123]
	v_mfma_f32_16x16x32_bf16 v[116:119], v[176:179], v[204:207], v[116:119]
	v_mfma_f32_16x16x32_bf16 v[112:115], v[184:187], v[204:207], v[112:115]
	v_mfma_f32_16x16x32_bf16 v[108:111], v[176:179], v[212:215], v[108:111]
	v_mfma_f32_16x16x32_bf16 v[104:107], v[184:187], v[212:215], v[104:107]
	v_mfma_f32_16x16x32_bf16 v[100:103], v[176:179], v[220:223], v[100:103]
	v_mfma_f32_16x16x32_bf16 v[96:99], v[184:187], v[220:223], v[96:99]
	s_setprio 0
	s_barrier
	v_readfirstlane_b32 s28, v158
	v_add_u32_e32 v170, s63, v164
	v_lshl_add_u64 v[192:193], v[240:241], 0, s[48:49]
	s_mov_b32 m0, s28
	v_readfirstlane_b32 s28, v159
	ds_read_b128 v[224:227], v170
	ds_read_b128 v[228:231], v170 offset:1024
	ds_read_b128 v[232:235], v170 offset:2048
	ds_read_b128 v[236:239], v170 offset:3072
	global_load_lds_dwordx4 v[192:193], off
	v_lshl_add_u64 v[192:193], v[242:243], 0, s[48:49]
	s_mov_b32 m0, s28
	s_nop 0
	global_load_lds_dwordx4 v[192:193], off
	s_barrier
	s_waitcnt lgkmcnt(0)
	s_setprio 1
	v_mfma_f32_16x16x32_bf16 v[92:95], v[224:227], v[188:191], v[92:95]
	v_mfma_f32_16x16x32_bf16 v[88:91], v[232:235], v[188:191], v[88:91]
	v_mfma_f32_16x16x32_bf16 v[84:87], v[224:227], v[200:203], v[84:87]
	v_mfma_f32_16x16x32_bf16 v[80:83], v[232:235], v[200:203], v[80:83]
	v_mfma_f32_16x16x32_bf16 v[76:79], v[224:227], v[208:211], v[76:79]
	v_mfma_f32_16x16x32_bf16 v[72:75], v[232:235], v[208:211], v[72:75]
	v_mfma_f32_16x16x32_bf16 v[68:71], v[224:227], v[216:219], v[68:71]
	v_mfma_f32_16x16x32_bf16 v[64:67], v[232:235], v[216:219], v[64:67]
	v_mfma_f32_16x16x32_bf16 v[92:95], v[228:231], v[196:199], v[92:95]
	v_mfma_f32_16x16x32_bf16 v[88:91], v[236:239], v[196:199], v[88:91]
	v_mfma_f32_16x16x32_bf16 v[84:87], v[228:231], v[204:207], v[84:87]
	v_mfma_f32_16x16x32_bf16 v[80:83], v[236:239], v[204:207], v[80:83]
	v_mfma_f32_16x16x32_bf16 v[76:79], v[228:231], v[212:215], v[76:79]
	v_mfma_f32_16x16x32_bf16 v[72:75], v[236:239], v[212:215], v[72:75]
	v_mfma_f32_16x16x32_bf16 v[68:71], v[228:231], v[220:223], v[68:71]
	v_mfma_f32_16x16x32_bf16 v[64:67], v[236:239], v[220:223], v[64:67]
	s_setprio 0
	v_readfirstlane_b32 s28, v160
	v_lshl_add_u64 v[192:193], v[244:245], 0, s[36:37]
	s_mov_b32 m0, s28
	v_readfirstlane_b32 s28, v161
	s_barrier
	ds_read_b128 v[188:191], v152 offset:49152
	ds_read_b128 v[196:199], v152 offset:50176
	ds_read_b128 v[200:203], v151 offset:49152
	ds_read_b128 v[204:207], v151 offset:50176
	ds_read_b128 v[208:211], v150 offset:49152
	ds_read_b128 v[212:215], v150 offset:50176
	ds_read_b128 v[216:219], v149 offset:49152
	ds_read_b128 v[220:223], v149 offset:50176
	global_load_lds_dwordx4 v[192:193], off
	v_lshl_add_u64 v[192:193], v[246:247], 0, s[36:37]
	s_mov_b32 m0, s28
	s_nop 0
	global_load_lds_dwordx4 v[192:193], off
	s_barrier
	s_waitcnt lgkmcnt(0)
	s_setprio 1
	v_mfma_f32_16x16x32_bf16 v[60:63], v[172:175], v[188:191], v[60:63]
	v_mfma_f32_16x16x32_bf16 v[56:59], v[180:183], v[188:191], v[56:59]
	v_mfma_f32_16x16x32_bf16 v[52:55], v[172:175], v[200:203], v[52:55]
	v_mfma_f32_16x16x32_bf16 v[48:51], v[180:183], v[200:203], v[48:51]
	v_mfma_f32_16x16x32_bf16 v[44:47], v[172:175], v[208:211], v[44:47]
	v_mfma_f32_16x16x32_bf16 v[40:43], v[180:183], v[208:211], v[40:43]
	v_mfma_f32_16x16x32_bf16 v[36:39], v[172:175], v[216:219], v[36:39]
	v_mfma_f32_16x16x32_bf16 v[32:35], v[180:183], v[216:219], v[32:35]
	v_mfma_f32_16x16x32_bf16 v[60:63], v[176:179], v[196:199], v[60:63]
	v_mfma_f32_16x16x32_bf16 v[56:59], v[184:187], v[196:199], v[56:59]
	v_mfma_f32_16x16x32_bf16 v[52:55], v[176:179], v[204:207], v[52:55]
	v_mfma_f32_16x16x32_bf16 v[48:51], v[184:187], v[204:207], v[48:51]
	v_mfma_f32_16x16x32_bf16 v[44:47], v[176:179], v[212:215], v[44:47]
	v_mfma_f32_16x16x32_bf16 v[40:43], v[184:187], v[212:215], v[40:43]
	v_mfma_f32_16x16x32_bf16 v[36:39], v[176:179], v[220:223], v[36:39]
	v_mfma_f32_16x16x32_bf16 v[32:35], v[184:187], v[220:223], v[32:35]
	s_setprio 0
	s_barrier
	v_readfirstlane_b32 s28, v162
	v_lshl_add_u64 v[172:173], v[240:241], 0, s[50:51]
	s_mov_b32 m0, s28
	v_readfirstlane_b32 s28, v163
	global_load_lds_dwordx4 v[172:173], off
	v_lshl_add_u64 v[172:173], v[242:243], 0, s[50:51]
	s_mov_b32 m0, s28
	s_nop 0
	global_load_lds_dwordx4 v[172:173], off
	s_waitcnt vmcnt(6)
	s_barrier
	s_setprio 1
	v_mfma_f32_16x16x32_bf16 v[28:31], v[224:227], v[188:191], v[28:31]
	v_mfma_f32_16x16x32_bf16 v[24:27], v[232:235], v[188:191], v[24:27]
	v_mfma_f32_16x16x32_bf16 v[20:23], v[224:227], v[200:203], v[20:23]
	v_mfma_f32_16x16x32_bf16 v[16:19], v[232:235], v[200:203], v[16:19]
	v_mfma_f32_16x16x32_bf16 v[12:15], v[224:227], v[208:211], v[12:15]
	v_mfma_f32_16x16x32_bf16 v[8:11], v[232:235], v[208:211], v[8:11]
	v_mfma_f32_16x16x32_bf16 v[4:7], v[224:227], v[216:219], v[4:7]
	v_mfma_f32_16x16x32_bf16 v[0:3], v[232:235], v[216:219], v[0:3]
	v_mfma_f32_16x16x32_bf16 v[28:31], v[228:231], v[196:199], v[28:31]
	v_mfma_f32_16x16x32_bf16 v[24:27], v[236:239], v[196:199], v[24:27]
	v_mfma_f32_16x16x32_bf16 v[20:23], v[228:231], v[204:207], v[20:23]
	v_mfma_f32_16x16x32_bf16 v[16:19], v[236:239], v[204:207], v[16:19]
	v_mfma_f32_16x16x32_bf16 v[12:15], v[228:231], v[212:215], v[12:15]
	v_mfma_f32_16x16x32_bf16 v[8:11], v[236:239], v[212:215], v[8:11]
	v_mfma_f32_16x16x32_bf16 v[4:7], v[228:231], v[220:223], v[4:7]
	v_mfma_f32_16x16x32_bf16 v[0:3], v[236:239], v[220:223], v[0:3]
	s_setprio 0
	s_add_i32 s1, s1, 2
	v_lshl_add_u64 v[134:135], v[134:135], 0, s[40:41]
	v_lshl_add_u64 v[136:137], v[136:137], 0, s[40:41]
	v_lshl_add_u64 v[138:139], v[138:139], 0, s[40:41]
	v_lshl_add_u64 v[140:141], v[140:141], 0, s[40:41]
	v_lshl_add_u64 v[142:143], v[142:143], 0, s[40:41]
	s_cmp_lt_u32 s1, 28
	v_lshl_add_u64 v[144:145], v[144:145], 0, s[40:41]
	s_barrier
	s_cbranch_scc1 .LBB0_680
	v_readfirstlane_b32 s1, v166
	v_lshl_add_u64 v[130:131], v[130:131], 0, s[42:43]
	s_mov_b32 m0, s1
	v_readfirstlane_b32 s1, v167
	ds_read_b128 v[134:137], v165
	ds_read_b128 v[138:141], v165 offset:1024
	ds_read_b128 v[142:145], v165 offset:2048
	ds_read_b128 v[154:157], v165 offset:3072
	ds_read_b128 v[158:161], v152
	ds_read_b128 v[162:165], v152 offset:1024
	ds_read_b128 v[172:175], v151
	ds_read_b128 v[176:179], v151 offset:1024
	ds_read_b128 v[180:183], v150
	ds_read_b128 v[184:187], v150 offset:1024
	ds_read_b128 v[188:191], v149
	ds_read_b128 v[196:199], v149 offset:1024
	global_load_lds_dwordx4 v[130:131], off
	v_lshl_add_u64 v[130:131], v[132:133], 0, s[42:43]
	s_mov_b32 m0, s1
	s_nop 0
	global_load_lds_dwordx4 v[130:131], off
	s_barrier
	s_waitcnt lgkmcnt(0)
	s_setprio 1
	v_mfma_f32_16x16x32_bf16 v[124:127], v[134:137], v[158:161], v[124:127]
	v_mfma_f32_16x16x32_bf16 v[116:119], v[134:137], v[172:175], v[116:119]
	v_mfma_f32_16x16x32_bf16 v[108:111], v[134:137], v[180:183], v[108:111]
	v_mfma_f32_16x16x32_bf16 v[100:103], v[134:137], v[188:191], v[100:103]
	v_mfma_f32_16x16x32_bf16 v[124:127], v[138:141], v[162:165], v[124:127]
	v_mfma_f32_16x16x32_bf16 v[120:123], v[142:145], v[158:161], v[120:123]
	v_mfma_f32_16x16x32_bf16 v[116:119], v[138:141], v[176:179], v[116:119]
	v_mfma_f32_16x16x32_bf16 v[112:115], v[142:145], v[172:175], v[112:115]
	v_mfma_f32_16x16x32_bf16 v[108:111], v[138:141], v[184:187], v[108:111]
	v_mfma_f32_16x16x32_bf16 v[104:107], v[142:145], v[180:183], v[104:107]
	v_mfma_f32_16x16x32_bf16 v[100:103], v[138:141], v[196:199], v[100:103]
	v_mfma_f32_16x16x32_bf16 v[96:99], v[142:145], v[188:191], v[96:99]
	v_mfma_f32_16x16x32_bf16 v[130:133], v[154:157], v[162:165], v[120:123]
	v_mfma_f32_16x16x32_bf16 v[200:203], v[154:157], v[176:179], v[112:115]
	v_mfma_f32_16x16x32_bf16 v[204:207], v[154:157], v[184:187], v[104:107]
	v_mfma_f32_16x16x32_bf16 v[208:211], v[154:157], v[196:199], v[96:99]
	s_setprio 0
	s_barrier
	s_nop 1
	ds_read_b128 v[96:99], v168
	ds_read_b128 v[104:107], v168 offset:1024
	ds_read_b128 v[112:115], v168 offset:2048
	ds_read_b128 v[120:123], v168 offset:3072
	s_barrier
	s_waitcnt lgkmcnt(0)
	s_setprio 1
	v_mfma_f32_16x16x32_bf16 v[92:95], v[96:99], v[158:161], v[92:95]
	v_mfma_f32_16x16x32_bf16 v[84:87], v[96:99], v[172:175], v[84:87]
	v_mfma_f32_16x16x32_bf16 v[76:79], v[96:99], v[180:183], v[76:79]
	v_mfma_f32_16x16x32_bf16 v[68:71], v[96:99], v[188:191], v[68:71]
	v_mfma_f32_16x16x32_bf16 v[64:67], v[112:115], v[188:191], v[64:67]
	v_mfma_f32_16x16x32_bf16 v[92:95], v[104:107], v[162:165], v[92:95]
	v_mfma_f32_16x16x32_bf16 v[88:91], v[112:115], v[158:161], v[88:91]
	v_mfma_f32_16x16x32_bf16 v[84:87], v[104:107], v[176:179], v[84:87]
	v_mfma_f32_16x16x32_bf16 v[80:83], v[112:115], v[172:175], v[80:83]
	v_mfma_f32_16x16x32_bf16 v[76:79], v[104:107], v[184:187], v[76:79]
	v_mfma_f32_16x16x32_bf16 v[72:75], v[112:115], v[180:183], v[72:75]
	v_mfma_f32_16x16x32_bf16 v[68:71], v[104:107], v[196:199], v[68:71]
	v_mfma_f32_16x16x32_bf16 v[64:67], v[120:123], v[196:199], v[64:67]
	v_mfma_f32_16x16x32_bf16 v[158:161], v[120:123], v[162:165], v[88:91]
	v_mfma_f32_16x16x32_bf16 v[162:165], v[120:123], v[176:179], v[80:83]
	v_mfma_f32_16x16x32_bf16 v[172:175], v[120:123], v[184:187], v[72:75]
	s_setprio 0
	s_barrier
	s_nop 0
	ds_read_b128 v[72:75], v152 offset:16384
	ds_read_b128 v[80:83], v152 offset:17408
	ds_read_b128 v[88:91], v151 offset:16384
	ds_read_b128 v[176:179], v151 offset:17408
	ds_read_b128 v[180:183], v150 offset:16384
	ds_read_b128 v[184:187], v150 offset:17408
	ds_read_b128 v[188:191], v149 offset:16384
	ds_read_b128 v[196:199], v149 offset:17408
	s_waitcnt vmcnt(4)
	s_barrier
	s_waitcnt lgkmcnt(0)
	s_setprio 1
	v_mfma_f32_16x16x32_bf16 v[52:55], v[134:137], v[88:91], v[52:55]
	v_mfma_f32_16x16x32_bf16 v[44:47], v[134:137], v[180:183], v[44:47]
	v_mfma_f32_16x16x32_bf16 v[36:39], v[134:137], v[188:191], v[36:39]
	v_mfma_f32_16x16x32_bf16 v[60:63], v[134:137], v[72:75], v[60:63]
	v_mfma_f32_16x16x32_bf16 v[56:59], v[142:145], v[72:75], v[56:59]
	v_mfma_f32_16x16x32_bf16 v[52:55], v[138:141], v[176:179], v[52:55]
	v_mfma_f32_16x16x32_bf16 v[48:51], v[142:145], v[88:91], v[48:51]
	v_mfma_f32_16x16x32_bf16 v[44:47], v[138:141], v[184:187], v[44:47]
	v_mfma_f32_16x16x32_bf16 v[40:43], v[142:145], v[180:183], v[40:43]
	v_mfma_f32_16x16x32_bf16 v[36:39], v[138:141], v[196:199], v[36:39]
	v_mfma_f32_16x16x32_bf16 v[32:35], v[142:145], v[188:191], v[32:35]
	v_mfma_f32_16x16x32_bf16 v[212:215], v[138:141], v[80:83], v[60:63]
	v_mfma_f32_16x16x32_bf16 v[216:219], v[154:157], v[80:83], v[56:59]
	v_mfma_f32_16x16x32_bf16 v[220:223], v[154:157], v[176:179], v[48:51]
	v_mfma_f32_16x16x32_bf16 v[224:227], v[154:157], v[184:187], v[40:43]
	v_mfma_f32_16x16x32_bf16 v[134:137], v[154:157], v[196:199], v[32:35]
	s_setprio 0
	s_setprio 1
	v_mfma_f32_16x16x32_bf16 v[28:31], v[96:99], v[72:75], v[28:31]
	v_mfma_f32_16x16x32_bf16 v[20:23], v[96:99], v[88:91], v[20:23]
	v_mfma_f32_16x16x32_bf16 v[12:15], v[96:99], v[180:183], v[12:15]
	v_mfma_f32_16x16x32_bf16 v[4:7], v[96:99], v[188:191], v[4:7]
	v_mfma_f32_16x16x32_bf16 v[28:31], v[104:107], v[80:83], v[28:31]
	v_mfma_f32_16x16x32_bf16 v[24:27], v[112:115], v[72:75], v[24:27]
	v_mfma_f32_16x16x32_bf16 v[20:23], v[104:107], v[176:179], v[20:23]
	v_mfma_f32_16x16x32_bf16 v[16:19], v[112:115], v[88:91], v[16:19]
	v_mfma_f32_16x16x32_bf16 v[12:15], v[104:107], v[184:187], v[12:15]
	v_mfma_f32_16x16x32_bf16 v[8:11], v[112:115], v[180:183], v[8:11]
	v_mfma_f32_16x16x32_bf16 v[4:7], v[104:107], v[196:199], v[4:7]
	v_mfma_f32_16x16x32_bf16 v[0:3], v[112:115], v[188:191], v[0:3]
	v_mfma_f32_16x16x32_bf16 v[138:141], v[120:123], v[80:83], v[24:27]
	v_mfma_f32_16x16x32_bf16 v[142:145], v[120:123], v[176:179], v[16:19]
	v_mfma_f32_16x16x32_bf16 v[154:157], v[120:123], v[184:187], v[8:11]
	v_mfma_f32_16x16x32_bf16 v[176:179], v[120:123], v[196:199], v[0:3]
	s_setprio 0
	s_barrier
	s_nop 1
	ds_read_b128 v[0:3], v169
	ds_read_b128 v[8:11], v169 offset:1024
	ds_read_b128 v[16:19], v169 offset:2048
	ds_read_b128 v[24:27], v169 offset:3072
	ds_read_b128 v[32:35], v152 offset:32768
	ds_read_b128 v[40:43], v152 offset:33792
	ds_read_b128 v[48:51], v151 offset:32768
	ds_read_b128 v[56:59], v151 offset:33792
	ds_read_b128 v[60:63], v150 offset:32768
	ds_read_b128 v[166:169], v150 offset:33792
	ds_read_b128 v[180:183], v149 offset:32768
	ds_read_b128 v[184:187], v149 offset:33792
	s_waitcnt vmcnt(2)
	s_barrier
	s_waitcnt lgkmcnt(0)
	s_setprio 1
	v_mfma_f32_16x16x32_bf16 v[72:75], v[0:3], v[32:35], v[124:127]
	v_mfma_f32_16x16x32_bf16 v[120:123], v[8:11], v[40:43], v[72:75]
	v_mfma_f32_16x16x32_bf16 v[72:75], v[16:19], v[32:35], v[130:133]
	v_mfma_f32_16x16x32_bf16 v[124:127], v[24:27], v[40:43], v[72:75]
	v_mfma_f32_16x16x32_bf16 v[72:75], v[0:3], v[48:51], v[116:119]
	v_mfma_f32_16x16x32_bf16 v[112:115], v[8:11], v[56:59], v[72:75]
	v_mfma_f32_16x16x32_bf16 v[72:75], v[16:19], v[48:51], v[200:203]
	v_mfma_f32_16x16x32_bf16 v[116:119], v[24:27], v[56:59], v[72:75]
	v_mfma_f32_16x16x32_bf16 v[72:75], v[0:3], v[60:63], v[108:111]
	v_mfma_f32_16x16x32_bf16 v[104:107], v[8:11], v[166:169], v[72:75]
	v_mfma_f32_16x16x32_bf16 v[72:75], v[16:19], v[60:63], v[204:207]
	v_mfma_f32_16x16x32_bf16 v[108:111], v[24:27], v[166:169], v[72:75]
	v_mfma_f32_16x16x32_bf16 v[72:75], v[0:3], v[180:183], v[100:103]
	v_mfma_f32_16x16x32_bf16 v[96:99], v[8:11], v[184:187], v[72:75]
	v_mfma_f32_16x16x32_bf16 v[72:75], v[16:19], v[180:183], v[208:211]
	v_mfma_f32_16x16x32_bf16 v[100:103], v[24:27], v[184:187], v[72:75]
	s_setprio 0
	s_barrier
	ds_read_b128 v[130:133], v170
	ds_read_b128 v[188:191], v170 offset:1024
	ds_read_b128 v[196:199], v170 offset:2048
	ds_read_b128 v[200:203], v170 offset:3072
	s_waitcnt vmcnt(0)
	s_barrier
	s_waitcnt lgkmcnt(0)
	s_setprio 1
	v_mfma_f32_16x16x32_bf16 v[72:75], v[130:133], v[32:35], v[92:95]
	v_mfma_f32_16x16x32_bf16 v[32:35], v[196:199], v[32:35], v[158:161]
	v_mfma_f32_16x16x32_bf16 v[92:95], v[200:203], v[40:43], v[32:35]
	v_mfma_f32_16x16x32_bf16 v[32:35], v[130:133], v[48:51], v[84:87]
	v_mfma_f32_16x16x32_bf16 v[80:83], v[188:191], v[56:59], v[32:35]
	v_mfma_f32_16x16x32_bf16 v[32:35], v[196:199], v[48:51], v[162:165]
	v_mfma_f32_16x16x32_bf16 v[84:87], v[200:203], v[56:59], v[32:35]
	v_mfma_f32_16x16x32_bf16 v[32:35], v[130:133], v[60:63], v[76:79]
	v_mfma_f32_16x16x32_bf16 v[88:91], v[188:191], v[40:43], v[72:75]
	v_mfma_f32_16x16x32_bf16 v[72:75], v[188:191], v[166:169], v[32:35]
	v_mfma_f32_16x16x32_bf16 v[32:35], v[196:199], v[60:63], v[172:175]
	v_mfma_f32_16x16x32_bf16 v[76:79], v[200:203], v[166:169], v[32:35]
	v_mfma_f32_16x16x32_bf16 v[32:35], v[130:133], v[180:183], v[68:71]
	v_mfma_f32_16x16x32_bf16 v[56:59], v[188:191], v[184:187], v[32:35]
	v_mfma_f32_16x16x32_bf16 v[32:35], v[196:199], v[180:183], v[64:67]
	v_mfma_f32_16x16x32_bf16 v[60:63], v[200:203], v[184:187], v[32:35]
	s_setprio 0
	s_barrier
	ds_read_b128 v[158:161], v152 offset:49152
	ds_read_b128 v[162:165], v152 offset:50176
	ds_read_b128 v[166:169], v151 offset:49152
	ds_read_b128 v[170:173], v151 offset:50176
	ds_read_b128 v[180:183], v150 offset:49152
	ds_read_b128 v[150:153], v150 offset:50176
	ds_read_b128 v[184:187], v149 offset:49152
	ds_read_b128 v[204:207], v149 offset:50176
	s_barrier
	s_waitcnt lgkmcnt(0)
	s_setprio 1
	v_mfma_f32_16x16x32_bf16 v[32:35], v[0:3], v[158:161], v[212:215]
	v_mfma_f32_16x16x32_bf16 v[64:67], v[8:11], v[162:165], v[32:35]
	v_mfma_f32_16x16x32_bf16 v[32:35], v[16:19], v[158:161], v[216:219]
	v_mfma_f32_16x16x32_bf16 v[68:71], v[24:27], v[162:165], v[32:35]
	v_mfma_f32_16x16x32_bf16 v[32:35], v[0:3], v[166:169], v[52:55]
	v_mfma_f32_16x16x32_bf16 v[48:51], v[8:11], v[170:173], v[32:35]
	v_mfma_f32_16x16x32_bf16 v[32:35], v[16:19], v[166:169], v[220:223]
	v_mfma_f32_16x16x32_bf16 v[52:55], v[24:27], v[170:173], v[32:35]
	v_mfma_f32_16x16x32_bf16 v[32:35], v[0:3], v[180:183], v[44:47]
	v_mfma_f32_16x16x32_bf16 v[40:43], v[8:11], v[150:153], v[32:35]
	v_mfma_f32_16x16x32_bf16 v[32:35], v[16:19], v[180:183], v[224:227]
	v_mfma_f32_16x16x32_bf16 v[0:3], v[0:3], v[184:187], v[36:39]
	v_mfma_f32_16x16x32_bf16 v[44:47], v[24:27], v[150:153], v[32:35]
	v_mfma_f32_16x16x32_bf16 v[32:35], v[8:11], v[204:207], v[0:3]
	v_mfma_f32_16x16x32_bf16 v[0:3], v[16:19], v[184:187], v[134:137]
	v_mfma_f32_16x16x32_bf16 v[36:39], v[24:27], v[204:207], v[0:3]
	s_setprio 0
	s_setprio 1
	v_mfma_f32_16x16x32_bf16 v[0:3], v[130:133], v[158:161], v[28:31]
	v_mfma_f32_16x16x32_bf16 v[24:27], v[188:191], v[162:165], v[0:3]
	v_mfma_f32_16x16x32_bf16 v[0:3], v[196:199], v[158:161], v[138:141]
	v_mfma_f32_16x16x32_bf16 v[28:31], v[200:203], v[162:165], v[0:3]
	v_mfma_f32_16x16x32_bf16 v[0:3], v[130:133], v[166:169], v[20:23]
	v_mfma_f32_16x16x32_bf16 v[16:19], v[188:191], v[170:173], v[0:3]
	v_mfma_f32_16x16x32_bf16 v[0:3], v[196:199], v[166:169], v[142:145]
	v_mfma_f32_16x16x32_bf16 v[20:23], v[200:203], v[170:173], v[0:3]
	v_mfma_f32_16x16x32_bf16 v[0:3], v[130:133], v[180:183], v[12:15]
	v_mfma_f32_16x16x32_bf16 v[8:11], v[188:191], v[150:153], v[0:3]
	v_mfma_f32_16x16x32_bf16 v[0:3], v[196:199], v[180:183], v[154:157]
	v_mfma_f32_16x16x32_bf16 v[12:15], v[200:203], v[150:153], v[0:3]
	v_mfma_f32_16x16x32_bf16 v[0:3], v[130:133], v[184:187], v[4:7]
	v_mfma_f32_16x16x32_bf16 v[4:7], v[196:199], v[184:187], v[176:179]
	v_mfma_f32_16x16x32_bf16 v[0:3], v[188:191], v[204:207], v[0:3]
	v_mfma_f32_16x16x32_bf16 v[4:7], v[200:203], v[204:207], v[4:7]
	s_setprio 0
	v_readlane_b32 s28, v253, 16
	v_readlane_b32 s29, v253, 17
	s_andn2_b64 vcc, exec, s[28:29]
	s_barrier
	s_cbranch_vccnz .LBB0_683
	s_barrier

.LBB0_688:
	v_add_u32_e32 v165, s56, v164
	ds_read_b128 v[170:173], v165
	ds_read_b128 v[174:177], v165 offset:1024
	ds_read_b128 v[178:181], v165 offset:2048
	ds_read_b128 v[182:185], v165 offset:3072
	v_add_u32_e32 v166, 0xc000, v153
	v_lshl_add_u64 v[194:195], s[76:77], 0, v[142:143]
	v_readfirstlane_b32 s1, v166
	v_add_u32_e32 v167, 0xe000, v153
	v_lshl_add_u64 v[168:169], v[194:195], 0, s[14:15]
	s_mov_b32 m0, s1
	v_lshl_add_u64 v[236:237], s[76:77], 0, v[144:145]
	v_readfirstlane_b32 s1, v167
	ds_read_b128 v[186:189], v152
	ds_read_b128 v[190:193], v152 offset:1024
	ds_read_b128 v[196:199], v151
	ds_read_b128 v[200:203], v151 offset:1024
	ds_read_b128 v[204:207], v150
	ds_read_b128 v[208:211], v150 offset:1024
	ds_read_b128 v[212:215], v149
	ds_read_b128 v[216:219], v149 offset:1024
	global_load_lds_dwordx4 v[168:169], off
	v_lshl_add_u64 v[168:169], v[236:237], 0, s[14:15]
	s_mov_b32 m0, s1
	s_nop 0
	global_load_lds_dwordx4 v[168:169], off
	s_waitcnt lgkmcnt(8)
	s_barrier
	s_waitcnt lgkmcnt(0)
	s_setprio 1
	v_mfma_f32_16x16x32_bf16 v[124:127], v[186:189], v[170:173], v[124:127]
	v_mfma_f32_16x16x32_bf16 v[120:123], v[186:189], v[178:181], v[120:123]
	v_mfma_f32_16x16x32_bf16 v[116:119], v[196:199], v[170:173], v[116:119]
	v_mfma_f32_16x16x32_bf16 v[112:115], v[196:199], v[178:181], v[112:115]
	v_mfma_f32_16x16x32_bf16 v[108:111], v[204:207], v[170:173], v[108:111]
	v_mfma_f32_16x16x32_bf16 v[104:107], v[204:207], v[178:181], v[104:107]
	v_mfma_f32_16x16x32_bf16 v[100:103], v[212:215], v[170:173], v[100:103]
	v_mfma_f32_16x16x32_bf16 v[96:99], v[212:215], v[178:181], v[96:99]
	v_mfma_f32_16x16x32_bf16 v[124:127], v[190:193], v[174:177], v[124:127]
	v_mfma_f32_16x16x32_bf16 v[120:123], v[190:193], v[182:185], v[120:123]
	v_mfma_f32_16x16x32_bf16 v[116:119], v[200:203], v[174:177], v[116:119]
	v_mfma_f32_16x16x32_bf16 v[112:115], v[200:203], v[182:185], v[112:115]
	v_mfma_f32_16x16x32_bf16 v[108:111], v[208:211], v[174:177], v[108:111]
	v_mfma_f32_16x16x32_bf16 v[104:107], v[208:211], v[182:185], v[104:107]
	v_mfma_f32_16x16x32_bf16 v[100:103], v[216:219], v[174:177], v[100:103]
	v_mfma_f32_16x16x32_bf16 v[96:99], v[216:219], v[182:185], v[96:99]
	s_setprio 0
	s_barrier
	v_lshl_add_u64 v[240:241], s[76:77], 0, v[134:135]
	v_readfirstlane_b32 s1, v148
	v_add_u32_e32 v169, 0x2000, v148
	v_add_u32_e32 v168, s61, v164
	v_lshl_add_u64 v[238:239], v[240:241], 0, s[44:45]
	s_mov_b32 m0, s1
	v_lshl_add_u64 v[242:243], s[76:77], 0, v[136:137]
	v_readfirstlane_b32 s1, v169
	ds_read_b128 v[220:223], v168
	ds_read_b128 v[224:227], v168 offset:1024
	ds_read_b128 v[228:231], v168 offset:2048
	ds_read_b128 v[232:235], v168 offset:3072
	global_load_lds_dwordx4 v[238:239], off
	v_lshl_add_u64 v[238:239], v[242:243], 0, s[44:45]
	s_mov_b32 m0, s1
	s_nop 0
	global_load_lds_dwordx4 v[238:239], off
	s_barrier
	s_waitcnt lgkmcnt(0)
	s_setprio 1
	v_mfma_f32_16x16x32_bf16 v[92:95], v[186:189], v[220:223], v[92:95]
	v_mfma_f32_16x16x32_bf16 v[88:91], v[186:189], v[228:231], v[88:91]
	v_mfma_f32_16x16x32_bf16 v[84:87], v[196:199], v[220:223], v[84:87]
	v_mfma_f32_16x16x32_bf16 v[80:83], v[196:199], v[228:231], v[80:83]
	v_mfma_f32_16x16x32_bf16 v[76:79], v[204:207], v[220:223], v[76:79]
	v_mfma_f32_16x16x32_bf16 v[72:75], v[204:207], v[228:231], v[72:75]
	v_mfma_f32_16x16x32_bf16 v[68:71], v[212:215], v[220:223], v[68:71]
	v_mfma_f32_16x16x32_bf16 v[64:67], v[212:215], v[228:231], v[64:67]
	v_mfma_f32_16x16x32_bf16 v[92:95], v[190:193], v[224:227], v[92:95]
	v_mfma_f32_16x16x32_bf16 v[88:91], v[190:193], v[232:235], v[88:91]
	v_mfma_f32_16x16x32_bf16 v[84:87], v[200:203], v[224:227], v[84:87]
	v_mfma_f32_16x16x32_bf16 v[80:83], v[200:203], v[232:235], v[80:83]
	v_mfma_f32_16x16x32_bf16 v[76:79], v[208:211], v[224:227], v[76:79]
	v_mfma_f32_16x16x32_bf16 v[72:75], v[208:211], v[232:235], v[72:75]
	v_mfma_f32_16x16x32_bf16 v[68:71], v[216:219], v[224:227], v[68:71]
	v_mfma_f32_16x16x32_bf16 v[64:67], v[216:219], v[232:235], v[64:67]
	s_setprio 0
	v_lshl_add_u64 v[244:245], s[76:77], 0, v[138:139]
	v_readfirstlane_b32 s1, v153
	v_lshl_add_u64 v[238:239], v[244:245], 0, s[18:19]
	s_mov_b32 m0, s1
	v_lshl_add_u64 v[246:247], s[76:77], 0, v[140:141]
	v_readfirstlane_b32 s1, v154
	s_barrier
	ds_read_b128 v[186:189], v152 offset:16384
	ds_read_b128 v[190:193], v152 offset:17408
	ds_read_b128 v[196:199], v151 offset:16384
	ds_read_b128 v[200:203], v151 offset:17408
	ds_read_b128 v[204:207], v150 offset:16384
	ds_read_b128 v[208:211], v150 offset:17408
	ds_read_b128 v[212:215], v149 offset:16384
	ds_read_b128 v[216:219], v149 offset:17408
	global_load_lds_dwordx4 v[238:239], off
	v_lshl_add_u64 v[238:239], v[246:247], 0, s[18:19]
	s_mov_b32 m0, s1
	s_nop 0
	global_load_lds_dwordx4 v[238:239], off
	s_barrier
	s_waitcnt lgkmcnt(0)
	s_setprio 1
	v_mfma_f32_16x16x32_bf16 v[60:63], v[186:189], v[170:173], v[60:63]
	v_mfma_f32_16x16x32_bf16 v[56:59], v[186:189], v[178:181], v[56:59]
	v_mfma_f32_16x16x32_bf16 v[52:55], v[196:199], v[170:173], v[52:55]
	v_mfma_f32_16x16x32_bf16 v[48:51], v[196:199], v[178:181], v[48:51]
	v_mfma_f32_16x16x32_bf16 v[44:47], v[204:207], v[170:173], v[44:47]
	v_mfma_f32_16x16x32_bf16 v[40:43], v[204:207], v[178:181], v[40:43]
	v_mfma_f32_16x16x32_bf16 v[36:39], v[212:215], v[170:173], v[36:39]
	v_mfma_f32_16x16x32_bf16 v[32:35], v[212:215], v[178:181], v[32:35]
	v_mfma_f32_16x16x32_bf16 v[60:63], v[190:193], v[174:177], v[60:63]
	v_mfma_f32_16x16x32_bf16 v[56:59], v[190:193], v[182:185], v[56:59]
	v_mfma_f32_16x16x32_bf16 v[52:55], v[200:203], v[174:177], v[52:55]
	v_mfma_f32_16x16x32_bf16 v[48:51], v[200:203], v[182:185], v[48:51]
	v_mfma_f32_16x16x32_bf16 v[44:47], v[208:211], v[174:177], v[44:47]
	v_mfma_f32_16x16x32_bf16 v[40:43], v[208:211], v[182:185], v[40:43]
	v_mfma_f32_16x16x32_bf16 v[36:39], v[216:219], v[174:177], v[36:39]
	v_mfma_f32_16x16x32_bf16 v[32:35], v[216:219], v[182:185], v[32:35]
	s_setprio 0
	s_barrier
	v_readfirstlane_b32 s1, v155
	v_add_u32_e32 v169, 0x2000, v155
	v_lshl_add_u64 v[170:171], v[240:241], 0, s[46:47]
	s_mov_b32 m0, s1
	v_readfirstlane_b32 s1, v169
	global_load_lds_dwordx4 v[170:171], off
	v_lshl_add_u64 v[170:171], v[242:243], 0, s[46:47]
	s_mov_b32 m0, s1
	s_nop 0
	global_load_lds_dwordx4 v[170:171], off
	s_waitcnt vmcnt(6)
	s_barrier
	s_setprio 1
	v_mfma_f32_16x16x32_bf16 v[28:31], v[186:189], v[220:223], v[28:31]
	v_mfma_f32_16x16x32_bf16 v[24:27], v[186:189], v[228:231], v[24:27]
	v_mfma_f32_16x16x32_bf16 v[20:23], v[196:199], v[220:223], v[20:23]
	v_mfma_f32_16x16x32_bf16 v[16:19], v[196:199], v[228:231], v[16:19]
	v_mfma_f32_16x16x32_bf16 v[12:15], v[204:207], v[220:223], v[12:15]
	v_mfma_f32_16x16x32_bf16 v[8:11], v[204:207], v[228:231], v[8:11]
	v_mfma_f32_16x16x32_bf16 v[4:7], v[212:215], v[220:223], v[4:7]
	v_mfma_f32_16x16x32_bf16 v[0:3], v[212:215], v[228:231], v[0:3]
	v_mfma_f32_16x16x32_bf16 v[28:31], v[190:193], v[224:227], v[28:31]
	v_mfma_f32_16x16x32_bf16 v[24:27], v[190:193], v[232:235], v[24:27]
	v_mfma_f32_16x16x32_bf16 v[20:23], v[200:203], v[224:227], v[20:23]
	v_mfma_f32_16x16x32_bf16 v[16:19], v[200:203], v[232:235], v[16:19]
	v_mfma_f32_16x16x32_bf16 v[12:15], v[208:211], v[224:227], v[12:15]
	v_mfma_f32_16x16x32_bf16 v[8:11], v[208:211], v[232:235], v[8:11]
	v_mfma_f32_16x16x32_bf16 v[4:7], v[216:219], v[224:227], v[4:7]
	v_mfma_f32_16x16x32_bf16 v[0:3], v[216:219], v[232:235], v[0:3]
	s_setprio 0
	v_add_u32_e32 v169, s62, v164
	s_barrier
	ds_read_b128 v[172:175], v169
	ds_read_b128 v[176:179], v169 offset:1024
	ds_read_b128 v[180:183], v169 offset:2048
	ds_read_b128 v[184:187], v169 offset:3072
	v_readfirstlane_b32 s1, v156
	v_lshl_add_u64 v[170:171], v[194:195], 0, s[18:19]
	s_mov_b32 m0, s1
	v_readfirstlane_b32 s1, v157
	ds_read_b128 v[188:191], v152 offset:32768
	ds_read_b128 v[196:199], v152 offset:33792
	ds_read_b128 v[200:203], v151 offset:32768
	ds_read_b128 v[204:207], v151 offset:33792
	ds_read_b128 v[208:211], v150 offset:32768
	ds_read_b128 v[212:215], v150 offset:33792
	ds_read_b128 v[216:219], v149 offset:32768
	ds_read_b128 v[220:223], v149 offset:33792
	global_load_lds_dwordx4 v[170:171], off
	v_lshl_add_u64 v[170:171], v[236:237], 0, s[18:19]
	s_mov_b32 m0, s1
	s_nop 0
	global_load_lds_dwordx4 v[170:171], off
	s_waitcnt lgkmcnt(8)
	s_barrier
	s_waitcnt lgkmcnt(0)
	s_setprio 1
	v_mfma_f32_16x16x32_bf16 v[124:127], v[188:191], v[172:175], v[124:127]
	v_mfma_f32_16x16x32_bf16 v[120:123], v[188:191], v[180:183], v[120:123]
	v_mfma_f32_16x16x32_bf16 v[116:119], v[200:203], v[172:175], v[116:119]
	v_mfma_f32_16x16x32_bf16 v[112:115], v[200:203], v[180:183], v[112:115]
	v_mfma_f32_16x16x32_bf16 v[108:111], v[208:211], v[172:175], v[108:111]
	v_mfma_f32_16x16x32_bf16 v[104:107], v[208:211], v[180:183], v[104:107]
	v_mfma_f32_16x16x32_bf16 v[100:103], v[216:219], v[172:175], v[100:103]
	v_mfma_f32_16x16x32_bf16 v[96:99], v[216:219], v[180:183], v[96:99]
	v_mfma_f32_16x16x32_bf16 v[124:127], v[196:199], v[176:179], v[124:127]
	v_mfma_f32_16x16x32_bf16 v[120:123], v[196:199], v[184:187], v[120:123]
	v_mfma_f32_16x16x32_bf16 v[116:119], v[204:207], v[176:179], v[116:119]
	v_mfma_f32_16x16x32_bf16 v[112:115], v[204:207], v[184:187], v[112:115]
	v_mfma_f32_16x16x32_bf16 v[108:111], v[212:215], v[176:179], v[108:111]
	v_mfma_f32_16x16x32_bf16 v[104:107], v[212:215], v[184:187], v[104:107]
	v_mfma_f32_16x16x32_bf16 v[100:103], v[220:223], v[176:179], v[100:103]
	v_mfma_f32_16x16x32_bf16 v[96:99], v[220:223], v[184:187], v[96:99]
	s_setprio 0
	s_barrier
	v_readfirstlane_b32 s1, v158
	v_add_u32_e32 v170, s63, v164
	v_lshl_add_u64 v[192:193], v[240:241], 0, s[48:49]
	s_mov_b32 m0, s1
	v_readfirstlane_b32 s1, v159
	ds_read_b128 v[224:227], v170
	ds_read_b128 v[228:231], v170 offset:1024
	ds_read_b128 v[232:235], v170 offset:2048
	ds_read_b128 v[236:239], v170 offset:3072
	global_load_lds_dwordx4 v[192:193], off
	v_lshl_add_u64 v[192:193], v[242:243], 0, s[48:49]
	s_mov_b32 m0, s1
	s_nop 0
	global_load_lds_dwordx4 v[192:193], off
	s_barrier
	s_waitcnt lgkmcnt(0)
	s_setprio 1
	v_mfma_f32_16x16x32_bf16 v[92:95], v[188:191], v[224:227], v[92:95]
	v_mfma_f32_16x16x32_bf16 v[88:91], v[188:191], v[232:235], v[88:91]
	v_mfma_f32_16x16x32_bf16 v[84:87], v[200:203], v[224:227], v[84:87]
	v_mfma_f32_16x16x32_bf16 v[80:83], v[200:203], v[232:235], v[80:83]
	v_mfma_f32_16x16x32_bf16 v[76:79], v[208:211], v[224:227], v[76:79]
	v_mfma_f32_16x16x32_bf16 v[72:75], v[208:211], v[232:235], v[72:75]
	v_mfma_f32_16x16x32_bf16 v[68:71], v[216:219], v[224:227], v[68:71]
	v_mfma_f32_16x16x32_bf16 v[64:67], v[216:219], v[232:235], v[64:67]
	v_mfma_f32_16x16x32_bf16 v[92:95], v[196:199], v[228:231], v[92:95]
	v_mfma_f32_16x16x32_bf16 v[88:91], v[196:199], v[236:239], v[88:91]
	v_mfma_f32_16x16x32_bf16 v[84:87], v[204:207], v[228:231], v[84:87]
	v_mfma_f32_16x16x32_bf16 v[80:83], v[204:207], v[236:239], v[80:83]
	v_mfma_f32_16x16x32_bf16 v[76:79], v[212:215], v[228:231], v[76:79]
	v_mfma_f32_16x16x32_bf16 v[72:75], v[212:215], v[236:239], v[72:75]
	v_mfma_f32_16x16x32_bf16 v[68:71], v[220:223], v[228:231], v[68:71]
	v_mfma_f32_16x16x32_bf16 v[64:67], v[220:223], v[236:239], v[64:67]
	s_setprio 0
	v_readfirstlane_b32 s1, v160
	v_lshl_add_u64 v[192:193], v[244:245], 0, s[36:37]
	s_mov_b32 m0, s1
	v_readfirstlane_b32 s1, v161
	s_barrier
	ds_read_b128 v[188:191], v152 offset:49152
	ds_read_b128 v[196:199], v152 offset:50176
	ds_read_b128 v[200:203], v151 offset:49152
	ds_read_b128 v[204:207], v151 offset:50176
	ds_read_b128 v[208:211], v150 offset:49152
	ds_read_b128 v[212:215], v150 offset:50176
	ds_read_b128 v[216:219], v149 offset:49152
	ds_read_b128 v[220:223], v149 offset:50176
	global_load_lds_dwordx4 v[192:193], off
	v_lshl_add_u64 v[192:193], v[246:247], 0, s[36:37]
	s_mov_b32 m0, s1
	s_nop 0
	global_load_lds_dwordx4 v[192:193], off
	s_barrier
	s_waitcnt lgkmcnt(0)
	s_setprio 1
	v_mfma_f32_16x16x32_bf16 v[60:63], v[188:191], v[172:175], v[60:63]
	v_mfma_f32_16x16x32_bf16 v[56:59], v[188:191], v[180:183], v[56:59]
	v_mfma_f32_16x16x32_bf16 v[52:55], v[200:203], v[172:175], v[52:55]
	v_mfma_f32_16x16x32_bf16 v[48:51], v[200:203], v[180:183], v[48:51]
	v_mfma_f32_16x16x32_bf16 v[44:47], v[208:211], v[172:175], v[44:47]
	v_mfma_f32_16x16x32_bf16 v[40:43], v[208:211], v[180:183], v[40:43]
	v_mfma_f32_16x16x32_bf16 v[36:39], v[216:219], v[172:175], v[36:39]
	v_mfma_f32_16x16x32_bf16 v[32:35], v[216:219], v[180:183], v[32:35]
	v_mfma_f32_16x16x32_bf16 v[60:63], v[196:199], v[176:179], v[60:63]
	v_mfma_f32_16x16x32_bf16 v[56:59], v[196:199], v[184:187], v[56:59]
	v_mfma_f32_16x16x32_bf16 v[52:55], v[204:207], v[176:179], v[52:55]
	v_mfma_f32_16x16x32_bf16 v[48:51], v[204:207], v[184:187], v[48:51]
	v_mfma_f32_16x16x32_bf16 v[44:47], v[212:215], v[176:179], v[44:47]
	v_mfma_f32_16x16x32_bf16 v[40:43], v[212:215], v[184:187], v[40:43]
	v_mfma_f32_16x16x32_bf16 v[36:39], v[220:223], v[176:179], v[36:39]
	v_mfma_f32_16x16x32_bf16 v[32:35], v[220:223], v[184:187], v[32:35]
	s_setprio 0
	s_barrier
	v_readfirstlane_b32 s1, v162
	v_lshl_add_u64 v[172:173], v[240:241], 0, s[50:51]
	s_mov_b32 m0, s1
	v_readfirstlane_b32 s1, v163
	global_load_lds_dwordx4 v[172:173], off
	v_lshl_add_u64 v[172:173], v[242:243], 0, s[50:51]
	s_mov_b32 m0, s1
	s_nop 0
	global_load_lds_dwordx4 v[172:173], off
	s_waitcnt vmcnt(6)
	s_barrier
	s_setprio 1
	v_mfma_f32_16x16x32_bf16 v[28:31], v[188:191], v[224:227], v[28:31]
	v_mfma_f32_16x16x32_bf16 v[24:27], v[188:191], v[232:235], v[24:27]
	v_mfma_f32_16x16x32_bf16 v[20:23], v[200:203], v[224:227], v[20:23]
	v_mfma_f32_16x16x32_bf16 v[16:19], v[200:203], v[232:235], v[16:19]
	v_mfma_f32_16x16x32_bf16 v[12:15], v[208:211], v[224:227], v[12:15]
	v_mfma_f32_16x16x32_bf16 v[8:11], v[208:211], v[232:235], v[8:11]
	v_mfma_f32_16x16x32_bf16 v[4:7], v[216:219], v[224:227], v[4:7]
	v_mfma_f32_16x16x32_bf16 v[0:3], v[216:219], v[232:235], v[0:3]
	v_mfma_f32_16x16x32_bf16 v[28:31], v[196:199], v[228:231], v[28:31]
	v_mfma_f32_16x16x32_bf16 v[24:27], v[196:199], v[236:239], v[24:27]
	v_mfma_f32_16x16x32_bf16 v[20:23], v[204:207], v[228:231], v[20:23]
	v_mfma_f32_16x16x32_bf16 v[16:19], v[204:207], v[236:239], v[16:19]
	v_mfma_f32_16x16x32_bf16 v[12:15], v[212:215], v[228:231], v[12:15]
	v_mfma_f32_16x16x32_bf16 v[8:11], v[212:215], v[236:239], v[8:11]
	v_mfma_f32_16x16x32_bf16 v[4:7], v[220:223], v[228:231], v[4:7]
	v_mfma_f32_16x16x32_bf16 v[0:3], v[220:223], v[236:239], v[0:3]
	s_setprio 0
	s_add_i32 s0, s0, 2
	v_lshl_add_u64 v[134:135], v[134:135], 0, s[40:41]
	v_lshl_add_u64 v[136:137], v[136:137], 0, s[40:41]
	v_lshl_add_u64 v[138:139], v[138:139], 0, s[40:41]
	v_lshl_add_u64 v[140:141], v[140:141], 0, s[40:41]
	v_lshl_add_u64 v[142:143], v[142:143], 0, s[40:41]
	s_cmp_lt_u32 s0, 28
	v_lshl_add_u64 v[144:145], v[144:145], 0, s[40:41]
	s_barrier
	s_cbranch_scc1 .LBB0_688
	v_readfirstlane_b32 s0, v166
	v_lshl_add_u64 v[130:131], v[130:131], 0, s[42:43]
	s_mov_b32 m0, s0
	v_readfirstlane_b32 s0, v167
	ds_read_b128 v[134:137], v165
	ds_read_b128 v[138:141], v165 offset:1024
	ds_read_b128 v[142:145], v165 offset:2048
	ds_read_b128 v[154:157], v165 offset:3072
	ds_read_b128 v[158:161], v152
	ds_read_b128 v[162:165], v152 offset:1024
	ds_read_b128 v[172:175], v151
	ds_read_b128 v[176:179], v151 offset:1024
	ds_read_b128 v[180:183], v150
	ds_read_b128 v[184:187], v150 offset:1024
	ds_read_b128 v[188:191], v149
	ds_read_b128 v[196:199], v149 offset:1024
	global_load_lds_dwordx4 v[130:131], off
	v_lshl_add_u64 v[130:131], v[132:133], 0, s[42:43]
	s_mov_b32 m0, s0
	s_nop 0
	global_load_lds_dwordx4 v[130:131], off
	s_barrier
	s_waitcnt lgkmcnt(0)
	s_setprio 1
	v_mfma_f32_16x16x32_bf16 v[124:127], v[158:161], v[134:137], v[124:127]
	v_mfma_f32_16x16x32_bf16 v[116:119], v[172:175], v[134:137], v[116:119]
	v_mfma_f32_16x16x32_bf16 v[108:111], v[180:183], v[134:137], v[108:111]
	v_mfma_f32_16x16x32_bf16 v[100:103], v[188:191], v[134:137], v[100:103]
	v_mfma_f32_16x16x32_bf16 v[96:99], v[188:191], v[142:145], v[96:99]
	v_mfma_f32_16x16x32_bf16 v[124:127], v[162:165], v[138:141], v[124:127]
	v_mfma_f32_16x16x32_bf16 v[120:123], v[158:161], v[142:145], v[120:123]
	v_mfma_f32_16x16x32_bf16 v[116:119], v[176:179], v[138:141], v[116:119]
	v_mfma_f32_16x16x32_bf16 v[112:115], v[172:175], v[142:145], v[112:115]
	v_mfma_f32_16x16x32_bf16 v[108:111], v[184:187], v[138:141], v[108:111]
	v_mfma_f32_16x16x32_bf16 v[104:107], v[180:183], v[142:145], v[104:107]
	v_mfma_f32_16x16x32_bf16 v[100:103], v[196:199], v[138:141], v[100:103]
	v_mfma_f32_16x16x32_bf16 v[96:99], v[196:199], v[154:157], v[96:99]
	v_mfma_f32_16x16x32_bf16 v[130:133], v[162:165], v[154:157], v[120:123]
	v_mfma_f32_16x16x32_bf16 v[200:203], v[176:179], v[154:157], v[112:115]
	v_mfma_f32_16x16x32_bf16 v[204:207], v[184:187], v[154:157], v[104:107]
	s_setprio 0
	s_barrier
	s_nop 0
	ds_read_b128 v[104:107], v168
	ds_read_b128 v[112:115], v168 offset:1024
	ds_read_b128 v[120:123], v168 offset:2048
	ds_read_b128 v[208:211], v168 offset:3072
	s_barrier
	s_waitcnt lgkmcnt(0)
	s_setprio 1
	v_mfma_f32_16x16x32_bf16 v[92:95], v[158:161], v[104:107], v[92:95]
	v_mfma_f32_16x16x32_bf16 v[84:87], v[172:175], v[104:107], v[84:87]
	v_mfma_f32_16x16x32_bf16 v[76:79], v[180:183], v[104:107], v[76:79]
	v_mfma_f32_16x16x32_bf16 v[68:71], v[188:191], v[104:107], v[68:71]
	v_mfma_f32_16x16x32_bf16 v[64:67], v[188:191], v[120:123], v[64:67]
	v_mfma_f32_16x16x32_bf16 v[92:95], v[162:165], v[112:115], v[92:95]
	v_mfma_f32_16x16x32_bf16 v[88:91], v[158:161], v[120:123], v[88:91]
	v_mfma_f32_16x16x32_bf16 v[84:87], v[176:179], v[112:115], v[84:87]
	v_mfma_f32_16x16x32_bf16 v[80:83], v[172:175], v[120:123], v[80:83]
	v_mfma_f32_16x16x32_bf16 v[76:79], v[184:187], v[112:115], v[76:79]
	v_mfma_f32_16x16x32_bf16 v[72:75], v[180:183], v[120:123], v[72:75]
	v_mfma_f32_16x16x32_bf16 v[68:71], v[196:199], v[112:115], v[68:71]
	v_mfma_f32_16x16x32_bf16 v[64:67], v[196:199], v[208:211], v[64:67]
	v_mfma_f32_16x16x32_bf16 v[158:161], v[162:165], v[208:211], v[88:91]
	v_mfma_f32_16x16x32_bf16 v[162:165], v[176:179], v[208:211], v[80:83]
	v_mfma_f32_16x16x32_bf16 v[172:175], v[184:187], v[208:211], v[72:75]
	s_setprio 0
	s_barrier
	s_nop 0
	ds_read_b128 v[72:75], v152 offset:16384
	ds_read_b128 v[80:83], v152 offset:17408
	ds_read_b128 v[88:91], v151 offset:16384
	ds_read_b128 v[176:179], v151 offset:17408
	ds_read_b128 v[180:183], v150 offset:16384
	ds_read_b128 v[184:187], v150 offset:17408
	ds_read_b128 v[188:191], v149 offset:16384
	ds_read_b128 v[196:199], v149 offset:17408
	s_waitcnt vmcnt(4)
	s_barrier
	s_waitcnt lgkmcnt(0)
	s_setprio 1
	v_mfma_f32_16x16x32_bf16 v[60:63], v[72:75], v[134:137], v[60:63]
	v_mfma_f32_16x16x32_bf16 v[52:55], v[88:91], v[134:137], v[52:55]
	v_mfma_f32_16x16x32_bf16 v[44:47], v[180:183], v[134:137], v[44:47]
	v_mfma_f32_16x16x32_bf16 v[36:39], v[188:191], v[134:137], v[36:39]
	v_mfma_f32_16x16x32_bf16 v[60:63], v[80:83], v[138:141], v[60:63]
	v_mfma_f32_16x16x32_bf16 v[56:59], v[72:75], v[142:145], v[56:59]
	v_mfma_f32_16x16x32_bf16 v[52:55], v[176:179], v[138:141], v[52:55]
	v_mfma_f32_16x16x32_bf16 v[48:51], v[88:91], v[142:145], v[48:51]
	v_mfma_f32_16x16x32_bf16 v[44:47], v[184:187], v[138:141], v[44:47]
	v_mfma_f32_16x16x32_bf16 v[40:43], v[180:183], v[142:145], v[40:43]
	v_mfma_f32_16x16x32_bf16 v[36:39], v[196:199], v[138:141], v[36:39]
	v_mfma_f32_16x16x32_bf16 v[32:35], v[188:191], v[142:145], v[32:35]
	v_mfma_f32_16x16x32_bf16 v[212:215], v[80:83], v[154:157], v[56:59]
	v_mfma_f32_16x16x32_bf16 v[216:219], v[176:179], v[154:157], v[48:51]
	v_mfma_f32_16x16x32_bf16 v[220:223], v[184:187], v[154:157], v[40:43]
	v_mfma_f32_16x16x32_bf16 v[134:137], v[196:199], v[154:157], v[32:35]
	s_setprio 0
	s_setprio 1
	v_mfma_f32_16x16x32_bf16 v[28:31], v[72:75], v[104:107], v[28:31]
	v_mfma_f32_16x16x32_bf16 v[20:23], v[88:91], v[104:107], v[20:23]
	v_mfma_f32_16x16x32_bf16 v[12:15], v[180:183], v[104:107], v[12:15]
	v_mfma_f32_16x16x32_bf16 v[4:7], v[188:191], v[104:107], v[4:7]
	v_mfma_f32_16x16x32_bf16 v[28:31], v[80:83], v[112:115], v[28:31]
	v_mfma_f32_16x16x32_bf16 v[24:27], v[72:75], v[120:123], v[24:27]
	v_mfma_f32_16x16x32_bf16 v[20:23], v[176:179], v[112:115], v[20:23]
	v_mfma_f32_16x16x32_bf16 v[16:19], v[88:91], v[120:123], v[16:19]
	v_mfma_f32_16x16x32_bf16 v[12:15], v[184:187], v[112:115], v[12:15]
	v_mfma_f32_16x16x32_bf16 v[8:11], v[180:183], v[120:123], v[8:11]
	v_mfma_f32_16x16x32_bf16 v[4:7], v[196:199], v[112:115], v[4:7]
	v_mfma_f32_16x16x32_bf16 v[0:3], v[188:191], v[120:123], v[0:3]
	v_mfma_f32_16x16x32_bf16 v[138:141], v[80:83], v[208:211], v[24:27]
	v_mfma_f32_16x16x32_bf16 v[142:145], v[176:179], v[208:211], v[16:19]
	v_mfma_f32_16x16x32_bf16 v[154:157], v[184:187], v[208:211], v[8:11]
	v_mfma_f32_16x16x32_bf16 v[176:179], v[196:199], v[208:211], v[0:3]
	s_setprio 0
	s_barrier
	s_nop 1
	ds_read_b128 v[0:3], v169
	ds_read_b128 v[8:11], v169 offset:1024
	ds_read_b128 v[16:19], v169 offset:2048
	ds_read_b128 v[24:27], v169 offset:3072
	ds_read_b128 v[32:35], v152 offset:32768
	ds_read_b128 v[40:43], v152 offset:33792
	ds_read_b128 v[48:51], v151 offset:32768
	ds_read_b128 v[56:59], v151 offset:33792
	ds_read_b128 v[166:169], v150 offset:32768
	ds_read_b128 v[180:183], v150 offset:33792
	ds_read_b128 v[184:187], v149 offset:32768
	ds_read_b128 v[188:191], v149 offset:33792
	s_waitcnt vmcnt(2)
	s_barrier
	s_waitcnt lgkmcnt(0)
	s_setprio 1
	v_mfma_f32_16x16x32_bf16 v[72:75], v[32:35], v[0:3], v[124:127]
	v_mfma_f32_16x16x32_bf16 v[120:123], v[40:43], v[8:11], v[72:75]
	v_mfma_f32_16x16x32_bf16 v[72:75], v[32:35], v[16:19], v[130:133]
	v_mfma_f32_16x16x32_bf16 v[112:115], v[40:43], v[24:27], v[72:75]
	v_mfma_f32_16x16x32_bf16 v[72:75], v[48:51], v[0:3], v[116:119]
	v_mfma_f32_16x16x32_bf16 v[124:127], v[56:59], v[8:11], v[72:75]
	v_mfma_f32_16x16x32_bf16 v[72:75], v[48:51], v[16:19], v[200:203]
	v_mfma_f32_16x16x32_bf16 v[116:119], v[56:59], v[24:27], v[72:75]
	v_mfma_f32_16x16x32_bf16 v[72:75], v[166:169], v[0:3], v[108:111]
	v_mfma_f32_16x16x32_bf16 v[104:107], v[180:183], v[8:11], v[72:75]
	v_mfma_f32_16x16x32_bf16 v[72:75], v[166:169], v[16:19], v[204:207]
	v_mfma_f32_16x16x32_bf16 v[88:91], v[180:183], v[24:27], v[72:75]
	v_mfma_f32_16x16x32_bf16 v[72:75], v[184:187], v[0:3], v[100:103]
	v_mfma_f32_16x16x32_bf16 v[108:111], v[188:191], v[8:11], v[72:75]
	v_mfma_f32_16x16x32_bf16 v[72:75], v[184:187], v[16:19], v[96:99]
	v_mfma_f32_16x16x32_bf16 v[96:99], v[188:191], v[24:27], v[72:75]
	s_setprio 0
	s_barrier
	ds_read_b128 v[130:133], v170
	ds_read_b128 v[196:199], v170 offset:1024
	ds_read_b128 v[200:203], v170 offset:2048
	ds_read_b128 v[204:207], v170 offset:3072
	s_waitcnt vmcnt(0)
	s_barrier
	s_waitcnt lgkmcnt(0)
	s_setprio 1
	v_mfma_f32_16x16x32_bf16 v[72:75], v[32:35], v[130:133], v[92:95]
	v_mfma_f32_16x16x32_bf16 v[32:35], v[32:35], v[200:203], v[158:161]
	v_mfma_f32_16x16x32_bf16 v[80:83], v[40:43], v[204:207], v[32:35]
	v_mfma_f32_16x16x32_bf16 v[32:35], v[48:51], v[130:133], v[84:87]
	v_mfma_f32_16x16x32_bf16 v[100:103], v[56:59], v[196:199], v[32:35]
	v_mfma_f32_16x16x32_bf16 v[32:35], v[48:51], v[200:203], v[162:165]
	v_mfma_f32_16x16x32_bf16 v[84:87], v[56:59], v[204:207], v[32:35]
	v_mfma_f32_16x16x32_bf16 v[32:35], v[166:169], v[130:133], v[76:79]
	v_mfma_f32_16x16x32_bf16 v[92:95], v[40:43], v[196:199], v[72:75]
	v_mfma_f32_16x16x32_bf16 v[72:75], v[180:183], v[196:199], v[32:35]
	v_mfma_f32_16x16x32_bf16 v[32:35], v[166:169], v[200:203], v[172:175]
	v_mfma_f32_16x16x32_bf16 v[56:59], v[180:183], v[204:207], v[32:35]
	v_mfma_f32_16x16x32_bf16 v[32:35], v[184:187], v[130:133], v[68:71]
	v_mfma_f32_16x16x32_bf16 v[76:79], v[188:191], v[196:199], v[32:35]
	v_mfma_f32_16x16x32_bf16 v[32:35], v[184:187], v[200:203], v[64:67]
	v_mfma_f32_16x16x32_bf16 v[64:67], v[188:191], v[204:207], v[32:35]
	s_setprio 0
	s_barrier
	ds_read_b128 v[158:161], v152 offset:49152
	ds_read_b128 v[162:165], v152 offset:50176
	ds_read_b128 v[166:169], v151 offset:49152
	ds_read_b128 v[170:173], v151 offset:50176
	ds_read_b128 v[180:183], v150 offset:49152
	ds_read_b128 v[150:153], v150 offset:50176
	ds_read_b128 v[184:187], v149 offset:49152
	ds_read_b128 v[188:191], v149 offset:50176
	s_barrier
	s_waitcnt lgkmcnt(0)
	s_setprio 1
	v_mfma_f32_16x16x32_bf16 v[32:35], v[158:161], v[0:3], v[60:63]
	v_mfma_f32_16x16x32_bf16 v[60:63], v[162:165], v[8:11], v[32:35]
	v_mfma_f32_16x16x32_bf16 v[32:35], v[158:161], v[16:19], v[212:215]
	v_mfma_f32_16x16x32_bf16 v[48:51], v[162:165], v[24:27], v[32:35]
	v_mfma_f32_16x16x32_bf16 v[32:35], v[166:169], v[0:3], v[52:55]
	v_mfma_f32_16x16x32_bf16 v[68:71], v[170:173], v[8:11], v[32:35]
	v_mfma_f32_16x16x32_bf16 v[32:35], v[166:169], v[16:19], v[216:219]
	v_mfma_f32_16x16x32_bf16 v[52:55], v[170:173], v[24:27], v[32:35]
	v_mfma_f32_16x16x32_bf16 v[32:35], v[180:183], v[0:3], v[44:47]
	v_mfma_f32_16x16x32_bf16 v[0:3], v[184:187], v[0:3], v[36:39]
	v_mfma_f32_16x16x32_bf16 v[40:43], v[150:153], v[8:11], v[32:35]
	v_mfma_f32_16x16x32_bf16 v[32:35], v[180:183], v[16:19], v[220:223]
	v_mfma_f32_16x16x32_bf16 v[44:47], v[188:191], v[8:11], v[0:3]
	v_mfma_f32_16x16x32_bf16 v[0:3], v[184:187], v[16:19], v[134:137]
	v_mfma_f32_16x16x32_bf16 v[32:35], v[150:153], v[24:27], v[32:35]
	v_mfma_f32_16x16x32_bf16 v[36:39], v[188:191], v[24:27], v[0:3]
	s_setprio 0
	s_setprio 1
	v_mfma_f32_16x16x32_bf16 v[0:3], v[158:161], v[130:133], v[28:31]
	v_mfma_f32_16x16x32_bf16 v[24:27], v[162:165], v[196:199], v[0:3]
	v_mfma_f32_16x16x32_bf16 v[0:3], v[158:161], v[200:203], v[138:141]
	v_mfma_f32_16x16x32_bf16 v[16:19], v[162:165], v[204:207], v[0:3]
	v_mfma_f32_16x16x32_bf16 v[0:3], v[166:169], v[130:133], v[20:23]
	v_mfma_f32_16x16x32_bf16 v[28:31], v[170:173], v[196:199], v[0:3]
	v_mfma_f32_16x16x32_bf16 v[0:3], v[166:169], v[200:203], v[142:145]
	v_mfma_f32_16x16x32_bf16 v[20:23], v[170:173], v[204:207], v[0:3]
	v_mfma_f32_16x16x32_bf16 v[0:3], v[180:183], v[130:133], v[12:15]
	v_mfma_f32_16x16x32_bf16 v[4:7], v[184:187], v[130:133], v[4:7]
	v_mfma_f32_16x16x32_bf16 v[8:11], v[150:153], v[196:199], v[0:3]
	v_mfma_f32_16x16x32_bf16 v[0:3], v[180:183], v[200:203], v[154:157]
	v_mfma_f32_16x16x32_bf16 v[12:15], v[188:191], v[196:199], v[4:7]
	v_mfma_f32_16x16x32_bf16 v[4:7], v[184:187], v[200:203], v[176:179]
	v_mfma_f32_16x16x32_bf16 v[0:3], v[150:153], v[204:207], v[0:3]
	v_mfma_f32_16x16x32_bf16 v[4:7], v[188:191], v[204:207], v[4:7]
	s_setprio 0
	v_readlane_b32 s0, v253, 16
	v_readlane_b32 s1, v253, 17
	s_andn2_b64 vcc, exec, s[0:1]
	s_barrier
	s_cbranch_vccnz .LBB0_629
	s_barrier
	s_branch .LBB0_629

.LBB0_735:
	v_add_u32_e32 v164, s26, v163
	ds_read_b128 v[168:171], v164
	ds_read_b128 v[172:175], v164 offset:1024
	ds_read_b128 v[176:179], v164 offset:2048
	ds_read_b128 v[180:183], v164 offset:3072
	v_add_u32_e32 v165, 0xc000, v152
	v_lshl_add_u64 v[240:241], s[76:77], 0, v[142:143]
	v_readfirstlane_b32 s28, v165
	v_lshl_add_u64 v[166:167], v[240:241], 0, s[18:19]
	s_mov_b32 m0, s28
	ds_read_b128 v[184:187], v148
	ds_read_b128 v[188:191], v148 offset:1024
	ds_read_b128 v[196:199], v149
	ds_read_b128 v[200:203], v149 offset:1024
	ds_read_b128 v[204:207], v150
	ds_read_b128 v[208:211], v150 offset:1024
	ds_read_b128 v[212:215], v151
	ds_read_b128 v[216:219], v151 offset:1024
	global_load_lds_dwordx4 v[166:167], off
	v_add_u32_e32 v166, 0xe000, v152
	v_lshl_add_u64 v[242:243], s[76:77], 0, v[144:145]
	v_readfirstlane_b32 s28, v166
	v_lshl_add_u64 v[220:221], v[242:243], 0, s[18:19]
	s_mov_b32 m0, s28
	s_nop 0
	global_load_lds_dwordx4 v[220:221], off
	s_waitcnt lgkmcnt(8)
	s_barrier
	s_waitcnt lgkmcnt(0)
	s_setprio 1
	v_mfma_f32_16x16x32_bf16 v[126:129], v[168:171], v[184:187], v[126:129]
	v_mfma_f32_16x16x32_bf16 v[122:125], v[176:179], v[184:187], v[122:125]
	v_mfma_f32_16x16x32_bf16 v[118:121], v[168:171], v[196:199], v[118:121]
	v_mfma_f32_16x16x32_bf16 v[114:117], v[176:179], v[196:199], v[114:117]
	v_mfma_f32_16x16x32_bf16 v[110:113], v[168:171], v[204:207], v[110:113]
	v_mfma_f32_16x16x32_bf16 v[106:109], v[176:179], v[204:207], v[106:109]
	v_mfma_f32_16x16x32_bf16 v[102:105], v[168:171], v[212:215], v[102:105]
	v_mfma_f32_16x16x32_bf16 v[98:101], v[176:179], v[212:215], v[98:101]
	v_mfma_f32_16x16x32_bf16 v[126:129], v[172:175], v[188:191], v[126:129]
	v_mfma_f32_16x16x32_bf16 v[122:125], v[180:183], v[188:191], v[122:125]
	v_mfma_f32_16x16x32_bf16 v[118:121], v[172:175], v[200:203], v[118:121]
	v_mfma_f32_16x16x32_bf16 v[114:117], v[180:183], v[200:203], v[114:117]
	v_mfma_f32_16x16x32_bf16 v[110:113], v[172:175], v[208:211], v[110:113]
	v_mfma_f32_16x16x32_bf16 v[106:109], v[180:183], v[208:211], v[106:109]
	v_mfma_f32_16x16x32_bf16 v[102:105], v[172:175], v[216:219], v[102:105]
	v_mfma_f32_16x16x32_bf16 v[98:101], v[180:183], v[216:219], v[98:101]
	s_setprio 0
	s_barrier
	v_lshl_add_u64 v[244:245], s[76:77], 0, v[138:139]
	v_readfirstlane_b32 s28, v147
	v_add_u32_e32 v194, 0x2000, v147
	v_add_u32_e32 v167, s29, v163
	v_lshl_add_u64 v[236:237], v[244:245], 0, s[20:21]
	s_mov_b32 m0, s28
	v_lshl_add_u64 v[246:247], s[76:77], 0, v[140:141]
	v_readfirstlane_b32 s28, v194
	ds_read_b128 v[220:223], v167
	ds_read_b128 v[224:227], v167 offset:1024
	ds_read_b128 v[228:231], v167 offset:2048
	ds_read_b128 v[232:235], v167 offset:3072
	global_load_lds_dwordx4 v[236:237], off
	v_lshl_add_u64 v[236:237], v[246:247], 0, s[20:21]
	s_mov_b32 m0, s28
	s_nop 0
	global_load_lds_dwordx4 v[236:237], off
	s_barrier
	s_waitcnt lgkmcnt(0)
	s_setprio 1
	v_mfma_f32_16x16x32_bf16 v[94:97], v[220:223], v[184:187], v[94:97]
	v_mfma_f32_16x16x32_bf16 v[90:93], v[228:231], v[184:187], v[90:93]
	v_mfma_f32_16x16x32_bf16 v[86:89], v[220:223], v[196:199], v[86:89]
	v_mfma_f32_16x16x32_bf16 v[82:85], v[228:231], v[196:199], v[82:85]
	v_mfma_f32_16x16x32_bf16 v[78:81], v[220:223], v[204:207], v[78:81]
	v_mfma_f32_16x16x32_bf16 v[74:77], v[228:231], v[204:207], v[74:77]
	v_mfma_f32_16x16x32_bf16 v[70:73], v[220:223], v[212:215], v[70:73]
	v_mfma_f32_16x16x32_bf16 v[66:69], v[228:231], v[212:215], v[66:69]
	v_mfma_f32_16x16x32_bf16 v[94:97], v[224:227], v[188:191], v[94:97]
	v_mfma_f32_16x16x32_bf16 v[90:93], v[232:235], v[188:191], v[90:93]
	v_mfma_f32_16x16x32_bf16 v[86:89], v[224:227], v[200:203], v[86:89]
	v_mfma_f32_16x16x32_bf16 v[82:85], v[232:235], v[200:203], v[82:85]
	v_mfma_f32_16x16x32_bf16 v[78:81], v[224:227], v[208:211], v[78:81]
	v_mfma_f32_16x16x32_bf16 v[74:77], v[232:235], v[208:211], v[74:77]
	v_mfma_f32_16x16x32_bf16 v[70:73], v[224:227], v[216:219], v[70:73]
	v_mfma_f32_16x16x32_bf16 v[66:69], v[232:235], v[216:219], v[66:69]
	s_setprio 0
	v_readfirstlane_b32 s28, v152
	v_lshl_add_u64 v[236:237], v[240:241], 0, s[22:23]
	s_mov_b32 m0, s28
	v_readfirstlane_b32 s28, v153
	s_barrier
	ds_read_b128 v[184:187], v148 offset:16384
	ds_read_b128 v[188:191], v148 offset:17408
	ds_read_b128 v[196:199], v149 offset:16384
	ds_read_b128 v[200:203], v149 offset:17408
	ds_read_b128 v[204:207], v150 offset:16384
	ds_read_b128 v[208:211], v150 offset:17408
	ds_read_b128 v[212:215], v151 offset:16384
	ds_read_b128 v[216:219], v151 offset:17408
	global_load_lds_dwordx4 v[236:237], off
	v_lshl_add_u64 v[236:237], v[242:243], 0, s[22:23]
	s_mov_b32 m0, s28
	s_nop 0
	global_load_lds_dwordx4 v[236:237], off
	s_barrier
	s_waitcnt lgkmcnt(0)
	s_setprio 1
	v_mfma_f32_16x16x32_bf16 v[62:65], v[168:171], v[184:187], v[62:65]
	v_mfma_f32_16x16x32_bf16 v[58:61], v[176:179], v[184:187], v[58:61]
	v_mfma_f32_16x16x32_bf16 v[54:57], v[168:171], v[196:199], v[54:57]
	v_mfma_f32_16x16x32_bf16 v[50:53], v[176:179], v[196:199], v[50:53]
	v_mfma_f32_16x16x32_bf16 v[46:49], v[168:171], v[204:207], v[46:49]
	v_mfma_f32_16x16x32_bf16 v[42:45], v[176:179], v[204:207], v[42:45]
	v_mfma_f32_16x16x32_bf16 v[38:41], v[168:171], v[212:215], v[38:41]
	v_mfma_f32_16x16x32_bf16 v[34:37], v[176:179], v[212:215], v[34:37]
	v_mfma_f32_16x16x32_bf16 v[62:65], v[172:175], v[188:191], v[62:65]
	v_mfma_f32_16x16x32_bf16 v[58:61], v[180:183], v[188:191], v[58:61]
	v_mfma_f32_16x16x32_bf16 v[54:57], v[172:175], v[200:203], v[54:57]
	v_mfma_f32_16x16x32_bf16 v[50:53], v[180:183], v[200:203], v[50:53]
	v_mfma_f32_16x16x32_bf16 v[46:49], v[172:175], v[208:211], v[46:49]
	v_mfma_f32_16x16x32_bf16 v[42:45], v[180:183], v[208:211], v[42:45]
	v_mfma_f32_16x16x32_bf16 v[38:41], v[172:175], v[216:219], v[38:41]
	v_mfma_f32_16x16x32_bf16 v[34:37], v[180:183], v[216:219], v[34:37]
	s_setprio 0
	s_barrier
	v_readfirstlane_b32 s28, v154
	v_add_u32_e32 v170, 0x2000, v154
	v_lshl_add_u64 v[168:169], v[244:245], 0, s[30:31]
	s_mov_b32 m0, s28
	v_readfirstlane_b32 s28, v170
	global_load_lds_dwordx4 v[168:169], off
	v_lshl_add_u64 v[168:169], v[246:247], 0, s[30:31]
	s_mov_b32 m0, s28
	s_nop 0
	global_load_lds_dwordx4 v[168:169], off
	s_waitcnt vmcnt(6)
	s_barrier
	s_setprio 1
	v_mfma_f32_16x16x32_bf16 v[30:33], v[220:223], v[184:187], v[30:33]
	v_mfma_f32_16x16x32_bf16 v[26:29], v[228:231], v[184:187], v[26:29]
	v_mfma_f32_16x16x32_bf16 v[22:25], v[220:223], v[196:199], v[22:25]
	v_mfma_f32_16x16x32_bf16 v[18:21], v[228:231], v[196:199], v[18:21]
	v_mfma_f32_16x16x32_bf16 v[14:17], v[220:223], v[204:207], v[14:17]
	v_mfma_f32_16x16x32_bf16 v[10:13], v[228:231], v[204:207], v[10:13]
	v_mfma_f32_16x16x32_bf16 v[6:9], v[220:223], v[212:215], v[6:9]
	v_mfma_f32_16x16x32_bf16 v[2:5], v[228:231], v[212:215], v[2:5]
	v_mfma_f32_16x16x32_bf16 v[30:33], v[224:227], v[188:191], v[30:33]
	v_mfma_f32_16x16x32_bf16 v[26:29], v[232:235], v[188:191], v[26:29]
	v_mfma_f32_16x16x32_bf16 v[22:25], v[224:227], v[200:203], v[22:25]
	v_mfma_f32_16x16x32_bf16 v[18:21], v[232:235], v[200:203], v[18:21]
	v_mfma_f32_16x16x32_bf16 v[14:17], v[224:227], v[208:211], v[14:17]
	v_mfma_f32_16x16x32_bf16 v[10:13], v[232:235], v[208:211], v[10:13]
	v_mfma_f32_16x16x32_bf16 v[6:9], v[224:227], v[216:219], v[6:9]
	v_mfma_f32_16x16x32_bf16 v[2:5], v[232:235], v[216:219], v[2:5]
	s_setprio 0
	v_add_u32_e32 v168, s47, v163
	s_barrier
	ds_read_b128 v[170:173], v168
	ds_read_b128 v[174:177], v168 offset:1024
	ds_read_b128 v[178:181], v168 offset:2048
	ds_read_b128 v[182:185], v168 offset:3072
	v_readfirstlane_b32 s28, v155
	v_lshl_add_u64 v[190:191], v[240:241], 0, s[34:35]
	s_mov_b32 m0, s28
	v_readfirstlane_b32 s28, v156
	ds_read_b128 v[186:189], v148 offset:32768
	ds_read_b128 v[196:199], v148 offset:33792
	ds_read_b128 v[200:203], v149 offset:32768
	ds_read_b128 v[204:207], v149 offset:33792
	ds_read_b128 v[208:211], v150 offset:32768
	ds_read_b128 v[212:215], v150 offset:33792
	ds_read_b128 v[216:219], v151 offset:32768
	ds_read_b128 v[220:223], v151 offset:33792
	global_load_lds_dwordx4 v[190:191], off
	v_lshl_add_u64 v[190:191], v[242:243], 0, s[34:35]
	s_mov_b32 m0, s28
	s_nop 0
	global_load_lds_dwordx4 v[190:191], off
	s_waitcnt lgkmcnt(8)
	s_barrier
	s_waitcnt lgkmcnt(0)
	s_setprio 1
	v_mfma_f32_16x16x32_bf16 v[126:129], v[170:173], v[186:189], v[126:129]
	v_mfma_f32_16x16x32_bf16 v[122:125], v[178:181], v[186:189], v[122:125]
	v_mfma_f32_16x16x32_bf16 v[118:121], v[170:173], v[200:203], v[118:121]
	v_mfma_f32_16x16x32_bf16 v[114:117], v[178:181], v[200:203], v[114:117]
	v_mfma_f32_16x16x32_bf16 v[110:113], v[170:173], v[208:211], v[110:113]
	v_mfma_f32_16x16x32_bf16 v[106:109], v[178:181], v[208:211], v[106:109]
	v_mfma_f32_16x16x32_bf16 v[102:105], v[170:173], v[216:219], v[102:105]
	v_mfma_f32_16x16x32_bf16 v[98:101], v[178:181], v[216:219], v[98:101]
	v_mfma_f32_16x16x32_bf16 v[126:129], v[174:177], v[196:199], v[126:129]
	v_mfma_f32_16x16x32_bf16 v[122:125], v[182:185], v[196:199], v[122:125]
	v_mfma_f32_16x16x32_bf16 v[118:121], v[174:177], v[204:207], v[118:121]
	v_mfma_f32_16x16x32_bf16 v[114:117], v[182:185], v[204:207], v[114:117]
	v_mfma_f32_16x16x32_bf16 v[110:113], v[174:177], v[212:215], v[110:113]
	v_mfma_f32_16x16x32_bf16 v[106:109], v[182:185], v[212:215], v[106:109]
	v_mfma_f32_16x16x32_bf16 v[102:105], v[174:177], v[220:223], v[102:105]
	v_mfma_f32_16x16x32_bf16 v[98:101], v[182:185], v[220:223], v[98:101]
	s_setprio 0
	s_barrier
	v_readfirstlane_b32 s28, v157
	v_add_u32_e32 v169, s48, v163
	v_lshl_add_u64 v[190:191], v[244:245], 0, s[36:37]
	s_mov_b32 m0, s28
	v_readfirstlane_b32 s28, v158
	ds_read_b128 v[224:227], v169
	ds_read_b128 v[228:231], v169 offset:1024
	ds_read_b128 v[232:235], v169 offset:2048
	ds_read_b128 v[236:239], v169 offset:3072
	global_load_lds_dwordx4 v[190:191], off
	v_lshl_add_u64 v[190:191], v[246:247], 0, s[36:37]
	s_mov_b32 m0, s28
	s_nop 0
	global_load_lds_dwordx4 v[190:191], off
	s_barrier
	s_waitcnt lgkmcnt(0)
	s_setprio 1
	v_mfma_f32_16x16x32_bf16 v[94:97], v[224:227], v[186:189], v[94:97]
	v_mfma_f32_16x16x32_bf16 v[90:93], v[232:235], v[186:189], v[90:93]
	v_mfma_f32_16x16x32_bf16 v[86:89], v[224:227], v[200:203], v[86:89]
	v_mfma_f32_16x16x32_bf16 v[82:85], v[232:235], v[200:203], v[82:85]
	v_mfma_f32_16x16x32_bf16 v[78:81], v[224:227], v[208:211], v[78:81]
	v_mfma_f32_16x16x32_bf16 v[74:77], v[232:235], v[208:211], v[74:77]
	v_mfma_f32_16x16x32_bf16 v[70:73], v[224:227], v[216:219], v[70:73]
	v_mfma_f32_16x16x32_bf16 v[66:69], v[232:235], v[216:219], v[66:69]
	v_mfma_f32_16x16x32_bf16 v[94:97], v[228:231], v[196:199], v[94:97]
	v_mfma_f32_16x16x32_bf16 v[90:93], v[236:239], v[196:199], v[90:93]
	v_mfma_f32_16x16x32_bf16 v[86:89], v[228:231], v[204:207], v[86:89]
	v_mfma_f32_16x16x32_bf16 v[82:85], v[236:239], v[204:207], v[82:85]
	v_mfma_f32_16x16x32_bf16 v[78:81], v[228:231], v[212:215], v[78:81]
	v_mfma_f32_16x16x32_bf16 v[74:77], v[236:239], v[212:215], v[74:77]
	v_mfma_f32_16x16x32_bf16 v[70:73], v[228:231], v[220:223], v[70:73]
	v_mfma_f32_16x16x32_bf16 v[66:69], v[236:239], v[220:223], v[66:69]
	s_setprio 0
	v_readfirstlane_b32 s28, v159
	v_lshl_add_u64 v[190:191], v[240:241], 0, s[38:39]
	s_mov_b32 m0, s28
	v_readfirstlane_b32 s28, v160
	s_barrier
	ds_read_b128 v[186:189], v148 offset:49152
	ds_read_b128 v[196:199], v148 offset:50176
	ds_read_b128 v[200:203], v149 offset:49152
	ds_read_b128 v[204:207], v149 offset:50176
	ds_read_b128 v[208:211], v150 offset:49152
	ds_read_b128 v[212:215], v150 offset:50176
	ds_read_b128 v[216:219], v151 offset:49152
	ds_read_b128 v[220:223], v151 offset:50176
	global_load_lds_dwordx4 v[190:191], off
	v_lshl_add_u64 v[190:191], v[242:243], 0, s[38:39]
	s_mov_b32 m0, s28
	s_nop 0
	global_load_lds_dwordx4 v[190:191], off
	s_barrier
	s_waitcnt lgkmcnt(0)
	s_setprio 1
	v_mfma_f32_16x16x32_bf16 v[62:65], v[170:173], v[186:189], v[62:65]
	v_mfma_f32_16x16x32_bf16 v[58:61], v[178:181], v[186:189], v[58:61]
	v_mfma_f32_16x16x32_bf16 v[54:57], v[170:173], v[200:203], v[54:57]
	v_mfma_f32_16x16x32_bf16 v[50:53], v[178:181], v[200:203], v[50:53]
	v_mfma_f32_16x16x32_bf16 v[46:49], v[170:173], v[208:211], v[46:49]
	v_mfma_f32_16x16x32_bf16 v[42:45], v[178:181], v[208:211], v[42:45]
	v_mfma_f32_16x16x32_bf16 v[38:41], v[170:173], v[216:219], v[38:41]
	v_mfma_f32_16x16x32_bf16 v[34:37], v[178:181], v[216:219], v[34:37]
	v_mfma_f32_16x16x32_bf16 v[62:65], v[174:177], v[196:199], v[62:65]
	v_mfma_f32_16x16x32_bf16 v[58:61], v[182:185], v[196:199], v[58:61]
	v_mfma_f32_16x16x32_bf16 v[54:57], v[174:177], v[204:207], v[54:57]
	v_mfma_f32_16x16x32_bf16 v[50:53], v[182:185], v[204:207], v[50:53]
	v_mfma_f32_16x16x32_bf16 v[46:49], v[174:177], v[212:215], v[46:49]
	v_mfma_f32_16x16x32_bf16 v[42:45], v[182:185], v[212:215], v[42:45]
	v_mfma_f32_16x16x32_bf16 v[38:41], v[174:177], v[220:223], v[38:41]
	v_mfma_f32_16x16x32_bf16 v[34:37], v[182:185], v[220:223], v[34:37]
	s_setprio 0
	s_barrier
	v_readfirstlane_b32 s28, v161
	v_lshl_add_u64 v[170:171], v[244:245], 0, s[40:41]
	s_mov_b32 m0, s28
	v_readfirstlane_b32 s28, v162
	global_load_lds_dwordx4 v[170:171], off
	v_lshl_add_u64 v[170:171], v[246:247], 0, s[40:41]
	s_mov_b32 m0, s28
	s_nop 0
	global_load_lds_dwordx4 v[170:171], off
	s_waitcnt vmcnt(6)
	s_barrier
	s_setprio 1
	v_mfma_f32_16x16x32_bf16 v[30:33], v[224:227], v[186:189], v[30:33]
	v_mfma_f32_16x16x32_bf16 v[26:29], v[232:235], v[186:189], v[26:29]
	v_mfma_f32_16x16x32_bf16 v[22:25], v[224:227], v[200:203], v[22:25]
	v_mfma_f32_16x16x32_bf16 v[18:21], v[232:235], v[200:203], v[18:21]
	v_mfma_f32_16x16x32_bf16 v[14:17], v[224:227], v[208:211], v[14:17]
	v_mfma_f32_16x16x32_bf16 v[10:13], v[232:235], v[208:211], v[10:13]
	v_mfma_f32_16x16x32_bf16 v[6:9], v[224:227], v[216:219], v[6:9]
	v_mfma_f32_16x16x32_bf16 v[2:5], v[232:235], v[216:219], v[2:5]
	v_mfma_f32_16x16x32_bf16 v[30:33], v[228:231], v[196:199], v[30:33]
	v_mfma_f32_16x16x32_bf16 v[26:29], v[236:239], v[196:199], v[26:29]
	v_mfma_f32_16x16x32_bf16 v[22:25], v[228:231], v[204:207], v[22:25]
	v_mfma_f32_16x16x32_bf16 v[18:21], v[236:239], v[204:207], v[18:21]
	v_mfma_f32_16x16x32_bf16 v[14:17], v[228:231], v[212:215], v[14:17]
	v_mfma_f32_16x16x32_bf16 v[10:13], v[236:239], v[212:215], v[10:13]
	v_mfma_f32_16x16x32_bf16 v[6:9], v[228:231], v[220:223], v[6:9]
	v_mfma_f32_16x16x32_bf16 v[2:5], v[236:239], v[220:223], v[2:5]
	s_setprio 0
	s_add_i32 s46, s46, 2
	v_lshl_add_u64 v[138:139], v[138:139], 0, s[14:15]
	v_lshl_add_u64 v[140:141], v[140:141], 0, s[14:15]
	v_lshl_add_u64 v[142:143], v[142:143], 0, s[42:43]
	s_cmp_lt_u32 s46, 28
	v_lshl_add_u64 v[144:145], v[144:145], 0, s[42:43]
	s_barrier
	s_cbranch_scc1 .LBB0_735
	v_lshl_add_u64 v[130:131], v[130:131], 1, v[134:135]
	v_readfirstlane_b32 s28, v165
	v_lshl_add_u64 v[130:131], v[130:131], 0, s[44:45]
	s_mov_b32 m0, s28
	ds_read_b128 v[138:141], v164
	ds_read_b128 v[142:145], v164 offset:1024
	ds_read_b128 v[152:155], v164 offset:2048
	ds_read_b128 v[156:159], v164 offset:3072
	ds_read_b128 v[160:163], v148
	ds_read_b128 v[170:173], v148 offset:1024
	ds_read_b128 v[174:177], v149
	ds_read_b128 v[178:181], v149 offset:1024
	ds_read_b128 v[182:185], v150
	ds_read_b128 v[186:189], v150 offset:1024
	ds_read_b128 v[196:199], v151
	ds_read_b128 v[200:203], v151 offset:1024
	global_load_lds_dwordx4 v[130:131], off
	v_lshl_add_u64 v[130:131], v[132:133], 1, v[136:137]
	v_readfirstlane_b32 s28, v166
	v_lshl_add_u64 v[130:131], v[130:131], 0, s[44:45]
	s_mov_b32 m0, s28
	s_nop 0
	global_load_lds_dwordx4 v[130:131], off
	s_barrier
	s_waitcnt lgkmcnt(0)
	s_setprio 1
	v_mfma_f32_16x16x32_bf16 v[126:129], v[138:141], v[160:163], v[126:129]
	v_mfma_f32_16x16x32_bf16 v[122:125], v[152:155], v[160:163], v[122:125]
	v_mfma_f32_16x16x32_bf16 v[118:121], v[138:141], v[174:177], v[118:121]
	v_mfma_f32_16x16x32_bf16 v[114:117], v[152:155], v[174:177], v[114:117]
	v_mfma_f32_16x16x32_bf16 v[110:113], v[138:141], v[182:185], v[110:113]
	v_mfma_f32_16x16x32_bf16 v[106:109], v[152:155], v[182:185], v[106:109]
	v_mfma_f32_16x16x32_bf16 v[102:105], v[138:141], v[196:199], v[102:105]
	v_mfma_f32_16x16x32_bf16 v[98:101], v[152:155], v[196:199], v[98:101]
	v_mfma_f32_16x16x32_bf16 v[126:129], v[142:145], v[170:173], v[126:129]
	v_mfma_f32_16x16x32_bf16 v[122:125], v[156:159], v[170:173], v[122:125]
	v_mfma_f32_16x16x32_bf16 v[118:121], v[142:145], v[178:181], v[118:121]
	v_mfma_f32_16x16x32_bf16 v[114:117], v[156:159], v[178:181], v[114:117]
	v_mfma_f32_16x16x32_bf16 v[110:113], v[142:145], v[186:189], v[110:113]
	v_mfma_f32_16x16x32_bf16 v[106:109], v[156:159], v[186:189], v[106:109]
	v_mfma_f32_16x16x32_bf16 v[102:105], v[142:145], v[200:203], v[102:105]
	v_mfma_f32_16x16x32_bf16 v[98:101], v[156:159], v[200:203], v[98:101]
	s_setprio 0
	s_barrier
	ds_read_b128 v[130:133], v167
	ds_read_b128 v[134:137], v167 offset:1024
	ds_read_b128 v[204:207], v167 offset:2048
	ds_read_b128 v[164:167], v167 offset:3072
	s_barrier
	s_waitcnt lgkmcnt(0)
	s_setprio 1
	v_mfma_f32_16x16x32_bf16 v[94:97], v[130:133], v[160:163], v[94:97]
	v_mfma_f32_16x16x32_bf16 v[90:93], v[204:207], v[160:163], v[90:93]
	v_mfma_f32_16x16x32_bf16 v[86:89], v[130:133], v[174:177], v[86:89]
	v_mfma_f32_16x16x32_bf16 v[82:85], v[204:207], v[174:177], v[82:85]
	v_mfma_f32_16x16x32_bf16 v[78:81], v[130:133], v[182:185], v[78:81]
	v_mfma_f32_16x16x32_bf16 v[74:77], v[204:207], v[182:185], v[74:77]
	v_mfma_f32_16x16x32_bf16 v[70:73], v[130:133], v[196:199], v[70:73]
	v_mfma_f32_16x16x32_bf16 v[94:97], v[134:137], v[170:173], v[94:97]
	v_mfma_f32_16x16x32_bf16 v[90:93], v[164:167], v[170:173], v[90:93]
	v_mfma_f32_16x16x32_bf16 v[86:89], v[134:137], v[178:181], v[86:89]
	v_mfma_f32_16x16x32_bf16 v[82:85], v[164:167], v[178:181], v[82:85]
	v_mfma_f32_16x16x32_bf16 v[78:81], v[134:137], v[186:189], v[78:81]
	v_mfma_f32_16x16x32_bf16 v[74:77], v[164:167], v[186:189], v[74:77]
	v_mfma_f32_16x16x32_bf16 v[70:73], v[134:137], v[200:203], v[70:73]
	v_mfma_f32_16x16x32_bf16 v[66:69], v[204:207], v[196:199], v[66:69]
	v_mfma_f32_16x16x32_bf16 v[160:163], v[164:167], v[200:203], v[66:69]
	s_setprio 0
	s_barrier
	s_nop 4
	ds_read_b128 v[66:69], v148 offset:16384
	ds_read_b128 v[170:173], v148 offset:17408
	ds_read_b128 v[174:177], v149 offset:16384
	ds_read_b128 v[178:181], v149 offset:17408
	ds_read_b128 v[182:185], v150 offset:16384
	ds_read_b128 v[186:189], v150 offset:17408
	ds_read_b128 v[196:199], v151 offset:16384
	ds_read_b128 v[200:203], v151 offset:17408
	s_waitcnt vmcnt(4)
	s_barrier
	s_waitcnt lgkmcnt(0)
	s_setprio 1
	v_mfma_f32_16x16x32_bf16 v[58:61], v[152:155], v[66:69], v[58:61]
	v_mfma_f32_16x16x32_bf16 v[50:53], v[152:155], v[174:177], v[50:53]
	v_mfma_f32_16x16x32_bf16 v[62:65], v[138:141], v[66:69], v[62:65]
	v_mfma_f32_16x16x32_bf16 v[58:61], v[156:159], v[170:173], v[58:61]
	v_mfma_f32_16x16x32_bf16 v[54:57], v[138:141], v[174:177], v[54:57]
	v_mfma_f32_16x16x32_bf16 v[50:53], v[156:159], v[178:181], v[50:53]
	v_mfma_f32_16x16x32_bf16 v[46:49], v[138:141], v[182:185], v[46:49]
	v_mfma_f32_16x16x32_bf16 v[42:45], v[152:155], v[182:185], v[42:45]
	v_mfma_f32_16x16x32_bf16 v[38:41], v[138:141], v[196:199], v[38:41]
	v_mfma_f32_16x16x32_bf16 v[34:37], v[152:155], v[196:199], v[34:37]
	v_mfma_f32_16x16x32_bf16 v[208:211], v[142:145], v[170:173], v[62:65]
	v_mfma_f32_16x16x32_bf16 v[212:215], v[142:145], v[178:181], v[54:57]
	v_mfma_f32_16x16x32_bf16 v[216:219], v[142:145], v[186:189], v[46:49]
	v_mfma_f32_16x16x32_bf16 v[220:223], v[156:159], v[186:189], v[42:45]
	v_mfma_f32_16x16x32_bf16 v[138:141], v[142:145], v[200:203], v[38:41]
	v_mfma_f32_16x16x32_bf16 v[142:145], v[156:159], v[200:203], v[34:37]
	s_setprio 0
	s_setprio 1
	v_mfma_f32_16x16x32_bf16 v[30:33], v[130:133], v[66:69], v[30:33]
	v_mfma_f32_16x16x32_bf16 v[26:29], v[204:207], v[66:69], v[26:29]
	v_mfma_f32_16x16x32_bf16 v[22:25], v[130:133], v[174:177], v[22:25]
	v_mfma_f32_16x16x32_bf16 v[18:21], v[204:207], v[174:177], v[18:21]
	v_mfma_f32_16x16x32_bf16 v[14:17], v[130:133], v[182:185], v[14:17]
	v_mfma_f32_16x16x32_bf16 v[10:13], v[204:207], v[182:185], v[10:13]
	v_mfma_f32_16x16x32_bf16 v[6:9], v[130:133], v[196:199], v[6:9]
	v_mfma_f32_16x16x32_bf16 v[2:5], v[204:207], v[196:199], v[2:5]
	v_mfma_f32_16x16x32_bf16 v[152:155], v[134:137], v[170:173], v[30:33]
	v_mfma_f32_16x16x32_bf16 v[156:159], v[164:167], v[170:173], v[26:29]
	v_mfma_f32_16x16x32_bf16 v[170:173], v[134:137], v[178:181], v[22:25]
	v_mfma_f32_16x16x32_bf16 v[174:177], v[164:167], v[178:181], v[18:21]
	v_mfma_f32_16x16x32_bf16 v[178:181], v[134:137], v[186:189], v[14:17]
	v_mfma_f32_16x16x32_bf16 v[182:185], v[164:167], v[186:189], v[10:13]
	v_mfma_f32_16x16x32_bf16 v[130:133], v[134:137], v[200:203], v[6:9]
	v_mfma_f32_16x16x32_bf16 v[134:137], v[164:167], v[200:203], v[2:5]
	s_setprio 0
	s_barrier
	ds_read_b128 v[164:167], v168
	ds_read_b128 v[186:189], v168 offset:1024
	ds_read_b128 v[196:199], v168 offset:2048
	ds_read_b128 v[200:203], v168 offset:3072
	ds_read_b128 v[38:41], v148 offset:32768
	ds_read_b128 v[42:45], v148 offset:33792
	ds_read_b128 v[46:49], v149 offset:32768
	ds_read_b128 v[54:57], v149 offset:33792
	ds_read_b128 v[62:65], v150 offset:32768
	ds_read_b128 v[66:69], v150 offset:33792
	ds_read_b128 v[204:207], v151 offset:32768
	ds_read_b128 v[224:227], v151 offset:33792
	s_waitcnt vmcnt(2)
	s_barrier
	s_waitcnt lgkmcnt(0)
	s_setprio 1
	v_mfma_f32_16x16x32_bf16 v[2:5], v[164:167], v[38:41], v[126:129]
	v_mfma_f32_16x16x32_bf16 v[26:29], v[186:189], v[42:45], v[2:5]
	v_mfma_f32_16x16x32_bf16 v[2:5], v[196:199], v[38:41], v[122:125]
	v_mfma_f32_16x16x32_bf16 v[34:37], v[200:203], v[42:45], v[2:5]
	v_mfma_f32_16x16x32_bf16 v[2:5], v[164:167], v[46:49], v[118:121]
	v_mfma_f32_16x16x32_bf16 v[18:21], v[186:189], v[54:57], v[2:5]
	v_mfma_f32_16x16x32_bf16 v[2:5], v[196:199], v[46:49], v[114:117]
	v_mfma_f32_16x16x32_bf16 v[22:25], v[200:203], v[54:57], v[2:5]
	v_mfma_f32_16x16x32_bf16 v[2:5], v[164:167], v[62:65], v[110:113]
	v_mfma_f32_16x16x32_bf16 v[10:13], v[186:189], v[66:69], v[2:5]
	v_mfma_f32_16x16x32_bf16 v[2:5], v[196:199], v[62:65], v[106:109]
	v_mfma_f32_16x16x32_bf16 v[14:17], v[200:203], v[66:69], v[2:5]
	v_mfma_f32_16x16x32_bf16 v[2:5], v[164:167], v[204:207], v[102:105]
	v_mfma_f32_16x16x32_bf16 v[6:9], v[196:199], v[204:207], v[98:101]
	v_mfma_f32_16x16x32_bf16 v[2:5], v[186:189], v[224:227], v[2:5]
	v_mfma_f32_16x16x32_bf16 v[6:9], v[200:203], v[224:227], v[6:9]
	s_setprio 0
	s_barrier
	ds_read_b128 v[114:117], v169
	ds_read_b128 v[118:121], v169 offset:1024
	ds_read_b128 v[228:231], v169 offset:2048
	ds_read_b128 v[232:235], v169 offset:3072
	s_waitcnt vmcnt(0)
	s_barrier
	s_waitcnt lgkmcnt(0)
	s_setprio 1
	v_mfma_f32_16x16x32_bf16 v[30:33], v[114:117], v[38:41], v[94:97]
	v_mfma_f32_16x16x32_bf16 v[38:41], v[228:231], v[38:41], v[90:93]
	v_mfma_f32_16x16x32_bf16 v[30:33], v[118:121], v[42:45], v[30:33]
	v_mfma_f32_16x16x32_bf16 v[38:41], v[232:235], v[42:45], v[38:41]
	v_mfma_f32_16x16x32_bf16 v[42:45], v[114:117], v[46:49], v[86:89]
	v_mfma_f32_16x16x32_bf16 v[46:49], v[228:231], v[46:49], v[82:85]
	v_mfma_f32_16x16x32_bf16 v[42:45], v[118:121], v[54:57], v[42:45]
	v_mfma_f32_16x16x32_bf16 v[46:49], v[232:235], v[54:57], v[46:49]
	v_mfma_f32_16x16x32_bf16 v[54:57], v[114:117], v[62:65], v[78:81]
	v_mfma_f32_16x16x32_bf16 v[62:65], v[228:231], v[62:65], v[74:77]
	v_mfma_f32_16x16x32_bf16 v[54:57], v[118:121], v[66:69], v[54:57]
	v_mfma_f32_16x16x32_bf16 v[62:65], v[232:235], v[66:69], v[62:65]
	v_mfma_f32_16x16x32_bf16 v[66:69], v[114:117], v[204:207], v[70:73]
	v_mfma_f32_16x16x32_bf16 v[70:73], v[228:231], v[204:207], v[160:163]
	v_mfma_f32_16x16x32_bf16 v[66:69], v[118:121], v[224:227], v[66:69]
	v_mfma_f32_16x16x32_bf16 v[70:73], v[232:235], v[224:227], v[70:73]
	s_setprio 0
	s_barrier
	ds_read_b128 v[86:89], v148 offset:49152
	ds_read_b128 v[90:93], v148 offset:50176
	ds_read_b128 v[94:97], v149 offset:49152
	ds_read_b128 v[102:105], v149 offset:50176
	ds_read_b128 v[110:113], v150 offset:49152
	ds_read_b128 v[160:163], v150 offset:50176
	ds_read_b128 v[204:207], v151 offset:49152
	ds_read_b128 v[148:151], v151 offset:50176
	s_barrier
	s_waitcnt lgkmcnt(0)
	s_setprio 1
	v_mfma_f32_16x16x32_bf16 v[50:53], v[196:199], v[94:97], v[50:53]
	v_mfma_f32_16x16x32_bf16 v[74:77], v[164:167], v[86:89], v[208:211]
	v_mfma_f32_16x16x32_bf16 v[58:61], v[196:199], v[86:89], v[58:61]
	v_mfma_f32_16x16x32_bf16 v[106:109], v[200:203], v[102:105], v[50:53]
	v_mfma_f32_16x16x32_bf16 v[50:53], v[164:167], v[110:113], v[216:219]
	v_mfma_f32_16x16x32_bf16 v[122:125], v[186:189], v[90:93], v[74:77]
	v_mfma_f32_16x16x32_bf16 v[126:129], v[200:203], v[90:93], v[58:61]
	v_mfma_f32_16x16x32_bf16 v[58:61], v[164:167], v[94:97], v[212:215]
	v_mfma_f32_16x16x32_bf16 v[74:77], v[186:189], v[160:163], v[50:53]
	v_mfma_f32_16x16x32_bf16 v[50:53], v[196:199], v[110:113], v[220:223]
	v_mfma_f32_16x16x32_bf16 v[98:101], v[186:189], v[102:105], v[58:61]
	v_mfma_f32_16x16x32_bf16 v[82:85], v[200:203], v[160:163], v[50:53]
	v_mfma_f32_16x16x32_bf16 v[50:53], v[164:167], v[204:207], v[138:141]
	v_mfma_f32_16x16x32_bf16 v[58:61], v[196:199], v[204:207], v[142:145]
	v_mfma_f32_16x16x32_bf16 v[50:53], v[186:189], v[148:151], v[50:53]
	v_mfma_f32_16x16x32_bf16 v[58:61], v[200:203], v[148:151], v[58:61]
	s_setprio 0
	s_setprio 1
	v_mfma_f32_16x16x32_bf16 v[78:81], v[114:117], v[86:89], v[152:155]
	v_mfma_f32_16x16x32_bf16 v[86:89], v[228:231], v[86:89], v[156:159]
	v_mfma_f32_16x16x32_bf16 v[78:81], v[118:121], v[90:93], v[78:81]
	v_mfma_f32_16x16x32_bf16 v[86:89], v[232:235], v[90:93], v[86:89]
	v_mfma_f32_16x16x32_bf16 v[90:93], v[114:117], v[94:97], v[170:173]
	v_mfma_f32_16x16x32_bf16 v[94:97], v[228:231], v[94:97], v[174:177]
	v_mfma_f32_16x16x32_bf16 v[90:93], v[118:121], v[102:105], v[90:93]
	v_mfma_f32_16x16x32_bf16 v[94:97], v[232:235], v[102:105], v[94:97]
	v_mfma_f32_16x16x32_bf16 v[102:105], v[114:117], v[110:113], v[178:181]
	v_mfma_f32_16x16x32_bf16 v[114:117], v[114:117], v[204:207], v[130:133]
	v_mfma_f32_16x16x32_bf16 v[102:105], v[118:121], v[160:163], v[102:105]
	v_mfma_f32_16x16x32_bf16 v[110:113], v[228:231], v[110:113], v[182:185]
	v_mfma_f32_16x16x32_bf16 v[114:117], v[118:121], v[148:151], v[114:117]
	v_mfma_f32_16x16x32_bf16 v[118:121], v[228:231], v[204:207], v[134:137]
	v_mfma_f32_16x16x32_bf16 v[110:113], v[232:235], v[160:163], v[110:113]
	v_mfma_f32_16x16x32_bf16 v[118:121], v[232:235], v[148:151], v[118:121]
	s_setprio 0
	v_readlane_b32 s28, v253, 16
	v_readlane_b32 s29, v253, 17
	s_andn2_b64 vcc, exec, s[28:29]
	s_barrier
	s_cbranch_vccnz .LBB0_700
	s_barrier
	s_branch .LBB0_700

.LBB0_1003:
	v_add_u32_e32 v163, s39, v162
	ds_read_b128 v[168:171], v163
	ds_read_b128 v[172:175], v163 offset:1024
	ds_read_b128 v[176:179], v163 offset:2048
	ds_read_b128 v[180:183], v163 offset:3072
	v_add_u32_e32 v164, 0xc000, v151
	v_lshl_add_u64 v[234:235], s[76:77], 0, v[140:141]
	v_readfirstlane_b32 s30, v164
	v_add_u32_e32 v165, 0xe000, v151
	v_lshl_add_u64 v[166:167], v[234:235], 0, s[2:3]
	s_mov_b32 m0, s30
	v_lshl_add_u64 v[236:237], s[76:77], 0, v[142:143]
	v_readfirstlane_b32 s30, v165
	ds_read_b128 v[184:187], v150
	ds_read_b128 v[188:191], v150 offset:1024
	ds_read_b128 v[194:197], v149
	ds_read_b128 v[198:201], v149 offset:1024
	ds_read_b128 v[202:205], v148
	ds_read_b128 v[206:209], v148 offset:1024
	ds_read_b128 v[210:213], v147
	ds_read_b128 v[214:217], v147 offset:1024
	global_load_lds_dwordx4 v[166:167], off
	v_lshl_add_u64 v[166:167], v[236:237], 0, s[2:3]
	s_mov_b32 m0, s30
	s_nop 0
	global_load_lds_dwordx4 v[166:167], off
	s_waitcnt lgkmcnt(8)
	s_barrier
	s_waitcnt lgkmcnt(0)
	s_setprio 1
	v_mfma_f32_16x16x32_bf16 v[124:127], v[168:171], v[184:187], v[124:127]
	v_mfma_f32_16x16x32_bf16 v[120:123], v[176:179], v[184:187], v[120:123]
	v_mfma_f32_16x16x32_bf16 v[116:119], v[168:171], v[194:197], v[116:119]
	v_mfma_f32_16x16x32_bf16 v[112:115], v[176:179], v[194:197], v[112:115]
	v_mfma_f32_16x16x32_bf16 v[108:111], v[168:171], v[202:205], v[108:111]
	v_mfma_f32_16x16x32_bf16 v[104:107], v[176:179], v[202:205], v[104:107]
	v_mfma_f32_16x16x32_bf16 v[100:103], v[168:171], v[210:213], v[100:103]
	v_mfma_f32_16x16x32_bf16 v[96:99], v[176:179], v[210:213], v[96:99]
	v_mfma_f32_16x16x32_bf16 v[124:127], v[172:175], v[188:191], v[124:127]
	v_mfma_f32_16x16x32_bf16 v[120:123], v[180:183], v[188:191], v[120:123]
	v_mfma_f32_16x16x32_bf16 v[116:119], v[172:175], v[198:201], v[116:119]
	v_mfma_f32_16x16x32_bf16 v[112:115], v[180:183], v[198:201], v[112:115]
	v_mfma_f32_16x16x32_bf16 v[108:111], v[172:175], v[206:209], v[108:111]
	v_mfma_f32_16x16x32_bf16 v[104:107], v[180:183], v[206:209], v[104:107]
	v_mfma_f32_16x16x32_bf16 v[100:103], v[172:175], v[214:217], v[100:103]
	v_mfma_f32_16x16x32_bf16 v[96:99], v[180:183], v[214:217], v[96:99]
	s_setprio 0
	s_barrier
	v_lshl_add_u64 v[238:239], s[76:77], 0, v[132:133]
	v_readfirstlane_b32 s30, v146
	v_add_u32_e32 v166, s31, v162
	v_lshl_add_u64 v[240:241], v[238:239], 0, s[4:5]
	s_mov_b32 m0, s30
	v_add_u32_e32 v167, 0x2000, v146
	ds_read_b128 v[218:221], v166
	ds_read_b128 v[222:225], v166 offset:1024
	ds_read_b128 v[226:229], v166 offset:2048
	ds_read_b128 v[230:233], v166 offset:3072
	global_load_lds_dwordx4 v[240:241], off
	v_lshl_add_u64 v[240:241], s[76:77], 0, v[134:135]
	v_readfirstlane_b32 s30, v167
	v_lshl_add_u64 v[242:243], v[240:241], 0, s[4:5]
	s_mov_b32 m0, s30
	s_nop 0
	global_load_lds_dwordx4 v[242:243], off
	s_barrier
	s_waitcnt lgkmcnt(0)
	s_setprio 1
	v_mfma_f32_16x16x32_bf16 v[92:95], v[218:221], v[184:187], v[92:95]
	v_mfma_f32_16x16x32_bf16 v[88:91], v[226:229], v[184:187], v[88:91]
	v_mfma_f32_16x16x32_bf16 v[84:87], v[218:221], v[194:197], v[84:87]
	v_mfma_f32_16x16x32_bf16 v[80:83], v[226:229], v[194:197], v[80:83]
	v_mfma_f32_16x16x32_bf16 v[76:79], v[218:221], v[202:205], v[76:79]
	v_mfma_f32_16x16x32_bf16 v[72:75], v[226:229], v[202:205], v[72:75]
	v_mfma_f32_16x16x32_bf16 v[68:71], v[218:221], v[210:213], v[68:71]
	v_mfma_f32_16x16x32_bf16 v[64:67], v[226:229], v[210:213], v[64:67]
	v_mfma_f32_16x16x32_bf16 v[92:95], v[222:225], v[188:191], v[92:95]
	v_mfma_f32_16x16x32_bf16 v[88:91], v[230:233], v[188:191], v[88:91]
	v_mfma_f32_16x16x32_bf16 v[84:87], v[222:225], v[198:201], v[84:87]
	v_mfma_f32_16x16x32_bf16 v[80:83], v[230:233], v[198:201], v[80:83]
	v_mfma_f32_16x16x32_bf16 v[76:79], v[222:225], v[206:209], v[76:79]
	v_mfma_f32_16x16x32_bf16 v[72:75], v[230:233], v[206:209], v[72:75]
	v_mfma_f32_16x16x32_bf16 v[68:71], v[222:225], v[214:217], v[68:71]
	v_mfma_f32_16x16x32_bf16 v[64:67], v[230:233], v[214:217], v[64:67]
	s_setprio 0
	v_lshl_add_u64 v[242:243], s[76:77], 0, v[136:137]
	v_readfirstlane_b32 s30, v151
	v_lshl_add_u64 v[244:245], v[242:243], 0, s[6:7]
	s_mov_b32 m0, s30
	s_barrier
	ds_read_b128 v[184:187], v150 offset:16384
	ds_read_b128 v[188:191], v150 offset:17408
	ds_read_b128 v[194:197], v149 offset:16384
	ds_read_b128 v[198:201], v149 offset:17408
	ds_read_b128 v[202:205], v148 offset:16384
	ds_read_b128 v[206:209], v148 offset:17408
	ds_read_b128 v[210:213], v147 offset:16384
	ds_read_b128 v[214:217], v147 offset:17408
	global_load_lds_dwordx4 v[244:245], off
	v_lshl_add_u64 v[244:245], s[76:77], 0, v[138:139]
	v_readfirstlane_b32 s30, v152
	v_lshl_add_u64 v[246:247], v[244:245], 0, s[6:7]
	s_mov_b32 m0, s30
	s_nop 0
	global_load_lds_dwordx4 v[246:247], off
	s_barrier
	s_waitcnt lgkmcnt(0)
	s_setprio 1
	v_mfma_f32_16x16x32_bf16 v[60:63], v[168:171], v[184:187], v[60:63]
	v_mfma_f32_16x16x32_bf16 v[56:59], v[176:179], v[184:187], v[56:59]
	v_mfma_f32_16x16x32_bf16 v[52:55], v[168:171], v[194:197], v[52:55]
	v_mfma_f32_16x16x32_bf16 v[48:51], v[176:179], v[194:197], v[48:51]
	v_mfma_f32_16x16x32_bf16 v[44:47], v[168:171], v[202:205], v[44:47]
	v_mfma_f32_16x16x32_bf16 v[40:43], v[176:179], v[202:205], v[40:43]
	v_mfma_f32_16x16x32_bf16 v[36:39], v[168:171], v[210:213], v[36:39]
	v_mfma_f32_16x16x32_bf16 v[32:35], v[176:179], v[210:213], v[32:35]
	v_mfma_f32_16x16x32_bf16 v[60:63], v[172:175], v[188:191], v[60:63]
	v_mfma_f32_16x16x32_bf16 v[56:59], v[180:183], v[188:191], v[56:59]
	v_mfma_f32_16x16x32_bf16 v[52:55], v[172:175], v[198:201], v[52:55]
	v_mfma_f32_16x16x32_bf16 v[48:51], v[180:183], v[198:201], v[48:51]
	v_mfma_f32_16x16x32_bf16 v[44:47], v[172:175], v[206:209], v[44:47]
	v_mfma_f32_16x16x32_bf16 v[40:43], v[180:183], v[206:209], v[40:43]
	v_mfma_f32_16x16x32_bf16 v[36:39], v[172:175], v[214:217], v[36:39]
	v_mfma_f32_16x16x32_bf16 v[32:35], v[180:183], v[214:217], v[32:35]
	s_setprio 0
	s_barrier
	v_readfirstlane_b32 s30, v153
	v_add_u32_e32 v167, 0x2000, v153
	v_lshl_add_u64 v[168:169], v[238:239], 0, s[8:9]
	s_mov_b32 m0, s30
	v_readfirstlane_b32 s30, v167
	global_load_lds_dwordx4 v[168:169], off
	v_lshl_add_u64 v[168:169], v[240:241], 0, s[8:9]
	s_mov_b32 m0, s30
	s_nop 0
	global_load_lds_dwordx4 v[168:169], off
	s_waitcnt vmcnt(6)
	s_barrier
	s_setprio 1
	v_mfma_f32_16x16x32_bf16 v[28:31], v[218:221], v[184:187], v[28:31]
	v_mfma_f32_16x16x32_bf16 v[24:27], v[226:229], v[184:187], v[24:27]
	v_mfma_f32_16x16x32_bf16 v[20:23], v[218:221], v[194:197], v[20:23]
	v_mfma_f32_16x16x32_bf16 v[16:19], v[226:229], v[194:197], v[16:19]
	v_mfma_f32_16x16x32_bf16 v[12:15], v[218:221], v[202:205], v[12:15]
	v_mfma_f32_16x16x32_bf16 v[8:11], v[226:229], v[202:205], v[8:11]
	v_mfma_f32_16x16x32_bf16 v[4:7], v[218:221], v[210:213], v[4:7]
	v_mfma_f32_16x16x32_bf16 v[0:3], v[226:229], v[210:213], v[0:3]
	v_mfma_f32_16x16x32_bf16 v[28:31], v[222:225], v[188:191], v[28:31]
	v_mfma_f32_16x16x32_bf16 v[24:27], v[230:233], v[188:191], v[24:27]
	v_mfma_f32_16x16x32_bf16 v[20:23], v[222:225], v[198:201], v[20:23]
	v_mfma_f32_16x16x32_bf16 v[16:19], v[230:233], v[198:201], v[16:19]
	v_mfma_f32_16x16x32_bf16 v[12:15], v[222:225], v[206:209], v[12:15]
	v_mfma_f32_16x16x32_bf16 v[8:11], v[230:233], v[206:209], v[8:11]
	v_mfma_f32_16x16x32_bf16 v[4:7], v[222:225], v[214:217], v[4:7]
	v_mfma_f32_16x16x32_bf16 v[0:3], v[230:233], v[214:217], v[0:3]
	s_setprio 0
	v_add_u32_e32 v167, s33, v162
	s_barrier
	ds_read_b128 v[170:173], v167
	ds_read_b128 v[174:177], v167 offset:1024
	ds_read_b128 v[178:181], v167 offset:2048
	ds_read_b128 v[182:185], v167 offset:3072
	v_readfirstlane_b32 s30, v154
	v_lshl_add_u64 v[168:169], v[234:235], 0, s[6:7]
	s_mov_b32 m0, s30
	v_readfirstlane_b32 s30, v155
	ds_read_b128 v[186:189], v150 offset:32768
	ds_read_b128 v[194:197], v150 offset:33792
	ds_read_b128 v[198:201], v149 offset:32768
	ds_read_b128 v[202:205], v149 offset:33792
	ds_read_b128 v[206:209], v148 offset:32768
	ds_read_b128 v[210:213], v148 offset:33792
	ds_read_b128 v[214:217], v147 offset:32768
	ds_read_b128 v[218:221], v147 offset:33792
	global_load_lds_dwordx4 v[168:169], off
	v_lshl_add_u64 v[168:169], v[236:237], 0, s[6:7]
	s_mov_b32 m0, s30
	s_nop 0
	global_load_lds_dwordx4 v[168:169], off
	s_waitcnt lgkmcnt(8)
	s_barrier
	s_waitcnt lgkmcnt(0)
	s_setprio 1
	v_mfma_f32_16x16x32_bf16 v[124:127], v[170:173], v[186:189], v[124:127]
	v_mfma_f32_16x16x32_bf16 v[120:123], v[178:181], v[186:189], v[120:123]
	v_mfma_f32_16x16x32_bf16 v[116:119], v[170:173], v[198:201], v[116:119]
	v_mfma_f32_16x16x32_bf16 v[112:115], v[178:181], v[198:201], v[112:115]
	v_mfma_f32_16x16x32_bf16 v[108:111], v[170:173], v[206:209], v[108:111]
	v_mfma_f32_16x16x32_bf16 v[104:107], v[178:181], v[206:209], v[104:107]
	v_mfma_f32_16x16x32_bf16 v[100:103], v[170:173], v[214:217], v[100:103]
	v_mfma_f32_16x16x32_bf16 v[96:99], v[178:181], v[214:217], v[96:99]
	v_mfma_f32_16x16x32_bf16 v[124:127], v[174:177], v[194:197], v[124:127]
	v_mfma_f32_16x16x32_bf16 v[120:123], v[182:185], v[194:197], v[120:123]
	v_mfma_f32_16x16x32_bf16 v[116:119], v[174:177], v[202:205], v[116:119]
	v_mfma_f32_16x16x32_bf16 v[112:115], v[182:185], v[202:205], v[112:115]
	v_mfma_f32_16x16x32_bf16 v[108:111], v[174:177], v[210:213], v[108:111]
	v_mfma_f32_16x16x32_bf16 v[104:107], v[182:185], v[210:213], v[104:107]
	v_mfma_f32_16x16x32_bf16 v[100:103], v[174:177], v[218:221], v[100:103]
	v_mfma_f32_16x16x32_bf16 v[96:99], v[182:185], v[218:221], v[96:99]
	s_setprio 0
	s_barrier
	v_readfirstlane_b32 s30, v156
	v_add_u32_e32 v168, s34, v162
	v_lshl_add_u64 v[190:191], v[238:239], 0, s[10:11]
	s_mov_b32 m0, s30
	v_readfirstlane_b32 s30, v157
	ds_read_b128 v[222:225], v168
	ds_read_b128 v[226:229], v168 offset:1024
	ds_read_b128 v[230:233], v168 offset:2048
	ds_read_b128 v[234:237], v168 offset:3072
	global_load_lds_dwordx4 v[190:191], off
	v_lshl_add_u64 v[190:191], v[240:241], 0, s[10:11]
	s_mov_b32 m0, s30
	s_nop 0
	global_load_lds_dwordx4 v[190:191], off
	s_barrier
	s_waitcnt lgkmcnt(0)
	s_setprio 1
	v_mfma_f32_16x16x32_bf16 v[92:95], v[222:225], v[186:189], v[92:95]
	v_mfma_f32_16x16x32_bf16 v[88:91], v[230:233], v[186:189], v[88:91]
	v_mfma_f32_16x16x32_bf16 v[84:87], v[222:225], v[198:201], v[84:87]
	v_mfma_f32_16x16x32_bf16 v[80:83], v[230:233], v[198:201], v[80:83]
	v_mfma_f32_16x16x32_bf16 v[76:79], v[222:225], v[206:209], v[76:79]
	v_mfma_f32_16x16x32_bf16 v[72:75], v[230:233], v[206:209], v[72:75]
	v_mfma_f32_16x16x32_bf16 v[68:71], v[222:225], v[214:217], v[68:71]
	v_mfma_f32_16x16x32_bf16 v[64:67], v[230:233], v[214:217], v[64:67]
	v_mfma_f32_16x16x32_bf16 v[92:95], v[226:229], v[194:197], v[92:95]
	v_mfma_f32_16x16x32_bf16 v[88:91], v[234:237], v[194:197], v[88:91]
	v_mfma_f32_16x16x32_bf16 v[84:87], v[226:229], v[202:205], v[84:87]
	v_mfma_f32_16x16x32_bf16 v[80:83], v[234:237], v[202:205], v[80:83]
	v_mfma_f32_16x16x32_bf16 v[76:79], v[226:229], v[210:213], v[76:79]
	v_mfma_f32_16x16x32_bf16 v[72:75], v[234:237], v[210:213], v[72:75]
	v_mfma_f32_16x16x32_bf16 v[68:71], v[226:229], v[218:221], v[68:71]
	v_mfma_f32_16x16x32_bf16 v[64:67], v[234:237], v[218:221], v[64:67]
	s_setprio 0
	v_readfirstlane_b32 s30, v158
	v_lshl_add_u64 v[190:191], v[242:243], 0, s[12:13]
	s_mov_b32 m0, s30
	v_readfirstlane_b32 s30, v159
	s_barrier
	ds_read_b128 v[186:189], v150 offset:49152
	ds_read_b128 v[194:197], v150 offset:50176
	ds_read_b128 v[198:201], v149 offset:49152
	ds_read_b128 v[202:205], v149 offset:50176
	ds_read_b128 v[206:209], v148 offset:49152
	ds_read_b128 v[210:213], v148 offset:50176
	ds_read_b128 v[214:217], v147 offset:49152
	ds_read_b128 v[218:221], v147 offset:50176
	global_load_lds_dwordx4 v[190:191], off
	v_lshl_add_u64 v[190:191], v[244:245], 0, s[12:13]
	s_mov_b32 m0, s30
	s_nop 0
	global_load_lds_dwordx4 v[190:191], off
	s_barrier
	s_waitcnt lgkmcnt(0)
	s_setprio 1
	v_mfma_f32_16x16x32_bf16 v[60:63], v[170:173], v[186:189], v[60:63]
	v_mfma_f32_16x16x32_bf16 v[56:59], v[178:181], v[186:189], v[56:59]
	v_mfma_f32_16x16x32_bf16 v[52:55], v[170:173], v[198:201], v[52:55]
	v_mfma_f32_16x16x32_bf16 v[48:51], v[178:181], v[198:201], v[48:51]
	v_mfma_f32_16x16x32_bf16 v[44:47], v[170:173], v[206:209], v[44:47]
	v_mfma_f32_16x16x32_bf16 v[40:43], v[178:181], v[206:209], v[40:43]
	v_mfma_f32_16x16x32_bf16 v[36:39], v[170:173], v[214:217], v[36:39]
	v_mfma_f32_16x16x32_bf16 v[32:35], v[178:181], v[214:217], v[32:35]
	v_mfma_f32_16x16x32_bf16 v[60:63], v[174:177], v[194:197], v[60:63]
	v_mfma_f32_16x16x32_bf16 v[56:59], v[182:185], v[194:197], v[56:59]
	v_mfma_f32_16x16x32_bf16 v[52:55], v[174:177], v[202:205], v[52:55]
	v_mfma_f32_16x16x32_bf16 v[48:51], v[182:185], v[202:205], v[48:51]
	v_mfma_f32_16x16x32_bf16 v[44:47], v[174:177], v[210:213], v[44:47]
	v_mfma_f32_16x16x32_bf16 v[40:43], v[182:185], v[210:213], v[40:43]
	v_mfma_f32_16x16x32_bf16 v[36:39], v[174:177], v[218:221], v[36:39]
	v_mfma_f32_16x16x32_bf16 v[32:35], v[182:185], v[218:221], v[32:35]
	s_setprio 0
	s_barrier
	v_readfirstlane_b32 s30, v160
	v_lshl_add_u64 v[170:171], v[238:239], 0, s[14:15]
	s_mov_b32 m0, s30
	v_readfirstlane_b32 s30, v161
	global_load_lds_dwordx4 v[170:171], off
	v_lshl_add_u64 v[170:171], v[240:241], 0, s[14:15]
	s_mov_b32 m0, s30
	s_nop 0
	global_load_lds_dwordx4 v[170:171], off
	s_waitcnt vmcnt(6)
	s_barrier
	s_setprio 1
	v_mfma_f32_16x16x32_bf16 v[28:31], v[222:225], v[186:189], v[28:31]
	v_mfma_f32_16x16x32_bf16 v[24:27], v[230:233], v[186:189], v[24:27]
	v_mfma_f32_16x16x32_bf16 v[20:23], v[222:225], v[198:201], v[20:23]
	v_mfma_f32_16x16x32_bf16 v[16:19], v[230:233], v[198:201], v[16:19]
	v_mfma_f32_16x16x32_bf16 v[12:15], v[222:225], v[206:209], v[12:15]
	v_mfma_f32_16x16x32_bf16 v[8:11], v[230:233], v[206:209], v[8:11]
	v_mfma_f32_16x16x32_bf16 v[4:7], v[222:225], v[214:217], v[4:7]
	v_mfma_f32_16x16x32_bf16 v[0:3], v[230:233], v[214:217], v[0:3]
	v_mfma_f32_16x16x32_bf16 v[28:31], v[226:229], v[194:197], v[28:31]
	v_mfma_f32_16x16x32_bf16 v[24:27], v[234:237], v[194:197], v[24:27]
	v_mfma_f32_16x16x32_bf16 v[20:23], v[226:229], v[202:205], v[20:23]
	v_mfma_f32_16x16x32_bf16 v[16:19], v[234:237], v[202:205], v[16:19]
	v_mfma_f32_16x16x32_bf16 v[12:15], v[226:229], v[210:213], v[12:15]
	v_mfma_f32_16x16x32_bf16 v[8:11], v[234:237], v[210:213], v[8:11]
	v_mfma_f32_16x16x32_bf16 v[4:7], v[226:229], v[218:221], v[4:7]
	v_mfma_f32_16x16x32_bf16 v[0:3], v[234:237], v[218:221], v[0:3]
	s_setprio 0
	s_add_i32 s21, s21, 2
	v_lshl_add_u64 v[132:133], v[132:133], 0, s[16:17]
	v_lshl_add_u64 v[134:135], v[134:135], 0, s[16:17]
	v_lshl_add_u64 v[136:137], v[136:137], 0, s[16:17]
	v_lshl_add_u64 v[138:139], v[138:139], 0, s[16:17]
	v_lshl_add_u64 v[140:141], v[140:141], 0, s[16:17]
	s_cmp_lt_u32 s21, 28
	v_lshl_add_u64 v[142:143], v[142:143], 0, s[16:17]
	s_barrier
	s_cbranch_scc1 .LBB0_1003
	v_readfirstlane_b32 s21, v164
	v_lshl_add_u64 v[128:129], v[128:129], 0, s[18:19]
	s_mov_b32 m0, s21
	v_readfirstlane_b32 s21, v165
	ds_read_b128 v[132:135], v163
	ds_read_b128 v[136:139], v163 offset:1024
	ds_read_b128 v[140:143], v163 offset:2048
	ds_read_b128 v[152:155], v163 offset:3072
	ds_read_b128 v[156:159], v150
	ds_read_b128 v[160:163], v150 offset:1024
	ds_read_b128 v[170:173], v149
	ds_read_b128 v[174:177], v149 offset:1024
	ds_read_b128 v[178:181], v148
	ds_read_b128 v[182:185], v148 offset:1024
	ds_read_b128 v[186:189], v147
	ds_read_b128 v[194:197], v147 offset:1024
	global_load_lds_dwordx4 v[128:129], off
	v_lshl_add_u64 v[128:129], v[130:131], 0, s[18:19]
	s_mov_b32 m0, s21
	s_nop 0
	global_load_lds_dwordx4 v[128:129], off
	s_barrier
	s_waitcnt lgkmcnt(0)
	s_setprio 1
	v_mfma_f32_16x16x32_bf16 v[124:127], v[132:135], v[156:159], v[124:127]
	v_mfma_f32_16x16x32_bf16 v[116:119], v[132:135], v[170:173], v[116:119]
	v_mfma_f32_16x16x32_bf16 v[112:115], v[140:143], v[170:173], v[112:115]
	v_mfma_f32_16x16x32_bf16 v[108:111], v[132:135], v[178:181], v[108:111]
	v_mfma_f32_16x16x32_bf16 v[104:107], v[140:143], v[178:181], v[104:107]
	v_mfma_f32_16x16x32_bf16 v[100:103], v[132:135], v[186:189], v[100:103]
	v_mfma_f32_16x16x32_bf16 v[96:99], v[140:143], v[186:189], v[96:99]
	v_mfma_f32_16x16x32_bf16 v[124:127], v[136:139], v[160:163], v[124:127]
	v_mfma_f32_16x16x32_bf16 v[120:123], v[140:143], v[156:159], v[120:123]
	v_mfma_f32_16x16x32_bf16 v[116:119], v[136:139], v[174:177], v[116:119]
	v_mfma_f32_16x16x32_bf16 v[112:115], v[152:155], v[174:177], v[112:115]
	v_mfma_f32_16x16x32_bf16 v[108:111], v[136:139], v[182:185], v[108:111]
	v_mfma_f32_16x16x32_bf16 v[104:107], v[152:155], v[182:185], v[104:107]
	v_mfma_f32_16x16x32_bf16 v[100:103], v[136:139], v[194:197], v[100:103]
	v_mfma_f32_16x16x32_bf16 v[96:99], v[152:155], v[194:197], v[96:99]
	v_mfma_f32_16x16x32_bf16 v[128:131], v[152:155], v[160:163], v[120:123]
	s_setprio 0
	s_barrier
	s_nop 0
	ds_read_b128 v[120:123], v166
	ds_read_b128 v[198:201], v166 offset:1024
	ds_read_b128 v[202:205], v166 offset:2048
	ds_read_b128 v[206:209], v166 offset:3072
	s_barrier
	s_waitcnt lgkmcnt(0)
	s_setprio 1
	v_mfma_f32_16x16x32_bf16 v[92:95], v[120:123], v[156:159], v[92:95]
	v_mfma_f32_16x16x32_bf16 v[88:91], v[202:205], v[156:159], v[88:91]
	v_mfma_f32_16x16x32_bf16 v[84:87], v[120:123], v[170:173], v[84:87]
	v_mfma_f32_16x16x32_bf16 v[76:79], v[120:123], v[178:181], v[76:79]
	v_mfma_f32_16x16x32_bf16 v[72:75], v[202:205], v[178:181], v[72:75]
	v_mfma_f32_16x16x32_bf16 v[64:67], v[202:205], v[186:189], v[64:67]
	v_mfma_f32_16x16x32_bf16 v[92:95], v[198:201], v[160:163], v[92:95]
	v_mfma_f32_16x16x32_bf16 v[88:91], v[206:209], v[160:163], v[88:91]
	v_mfma_f32_16x16x32_bf16 v[84:87], v[198:201], v[174:177], v[84:87]
	v_mfma_f32_16x16x32_bf16 v[80:83], v[202:205], v[170:173], v[80:83]
	v_mfma_f32_16x16x32_bf16 v[76:79], v[198:201], v[182:185], v[76:79]
	v_mfma_f32_16x16x32_bf16 v[72:75], v[206:209], v[182:185], v[72:75]
	v_mfma_f32_16x16x32_bf16 v[68:71], v[120:123], v[186:189], v[68:71]
	v_mfma_f32_16x16x32_bf16 v[64:67], v[206:209], v[194:197], v[64:67]
	v_mfma_f32_16x16x32_bf16 v[156:159], v[206:209], v[174:177], v[80:83]
	v_mfma_f32_16x16x32_bf16 v[160:163], v[198:201], v[194:197], v[68:71]
	s_setprio 0
	s_barrier
	s_nop 2
	ds_read_b128 v[68:71], v150 offset:16384
	ds_read_b128 v[80:83], v150 offset:17408
	ds_read_b128 v[170:173], v149 offset:16384
	ds_read_b128 v[174:177], v149 offset:17408
	ds_read_b128 v[178:181], v148 offset:16384
	ds_read_b128 v[182:185], v148 offset:17408
	ds_read_b128 v[186:189], v147 offset:16384
	ds_read_b128 v[194:197], v147 offset:17408
	s_waitcnt vmcnt(4)
	s_barrier
	s_waitcnt lgkmcnt(0)
	s_setprio 1
	v_mfma_f32_16x16x32_bf16 v[60:63], v[132:135], v[68:71], v[60:63]
	v_mfma_f32_16x16x32_bf16 v[52:55], v[132:135], v[170:173], v[52:55]
	v_mfma_f32_16x16x32_bf16 v[44:47], v[132:135], v[178:181], v[44:47]
	v_mfma_f32_16x16x32_bf16 v[36:39], v[132:135], v[186:189], v[36:39]
	v_mfma_f32_16x16x32_bf16 v[60:63], v[136:139], v[80:83], v[60:63]
	v_mfma_f32_16x16x32_bf16 v[56:59], v[140:143], v[68:71], v[56:59]
	v_mfma_f32_16x16x32_bf16 v[52:55], v[136:139], v[174:177], v[52:55]
	v_mfma_f32_16x16x32_bf16 v[48:51], v[140:143], v[170:173], v[48:51]
	v_mfma_f32_16x16x32_bf16 v[44:47], v[136:139], v[182:185], v[44:47]
	v_mfma_f32_16x16x32_bf16 v[40:43], v[140:143], v[178:181], v[40:43]
	v_mfma_f32_16x16x32_bf16 v[36:39], v[136:139], v[194:197], v[36:39]
	v_mfma_f32_16x16x32_bf16 v[32:35], v[140:143], v[186:189], v[32:35]
	v_mfma_f32_16x16x32_bf16 v[210:213], v[152:155], v[80:83], v[56:59]
	v_mfma_f32_16x16x32_bf16 v[214:217], v[152:155], v[174:177], v[48:51]
	v_mfma_f32_16x16x32_bf16 v[218:221], v[152:155], v[182:185], v[40:43]
	v_mfma_f32_16x16x32_bf16 v[132:135], v[152:155], v[194:197], v[32:35]
	s_setprio 0
	s_setprio 1
	v_mfma_f32_16x16x32_bf16 v[28:31], v[120:123], v[68:71], v[28:31]
	v_mfma_f32_16x16x32_bf16 v[20:23], v[120:123], v[170:173], v[20:23]
	v_mfma_f32_16x16x32_bf16 v[0:3], v[202:205], v[186:189], v[0:3]
	v_mfma_f32_16x16x32_bf16 v[28:31], v[198:201], v[80:83], v[28:31]
	v_mfma_f32_16x16x32_bf16 v[24:27], v[202:205], v[68:71], v[24:27]
	v_mfma_f32_16x16x32_bf16 v[20:23], v[198:201], v[174:177], v[20:23]
	v_mfma_f32_16x16x32_bf16 v[16:19], v[202:205], v[170:173], v[16:19]
	v_mfma_f32_16x16x32_bf16 v[12:15], v[120:123], v[178:181], v[12:15]
	v_mfma_f32_16x16x32_bf16 v[8:11], v[202:205], v[178:181], v[8:11]
	v_mfma_f32_16x16x32_bf16 v[4:7], v[120:123], v[186:189], v[4:7]
	v_mfma_f32_16x16x32_bf16 v[0:3], v[206:209], v[194:197], v[0:3]
	v_mfma_f32_16x16x32_bf16 v[136:139], v[206:209], v[80:83], v[24:27]
	v_mfma_f32_16x16x32_bf16 v[140:143], v[206:209], v[174:177], v[16:19]
	v_mfma_f32_16x16x32_bf16 v[152:155], v[198:201], v[182:185], v[12:15]
	v_mfma_f32_16x16x32_bf16 v[170:173], v[206:209], v[182:185], v[8:11]
	v_mfma_f32_16x16x32_bf16 v[174:177], v[198:201], v[194:197], v[4:7]
	s_setprio 0
	s_barrier
	ds_read_b128 v[178:181], v167
	ds_read_b128 v[182:185], v167 offset:1024
	ds_read_b128 v[186:189], v167 offset:2048
	ds_read_b128 v[164:167], v167 offset:3072
	ds_read_b128 v[16:19], v150 offset:32768
	ds_read_b128 v[24:27], v150 offset:33792
	ds_read_b128 v[32:35], v149 offset:32768
	ds_read_b128 v[40:43], v149 offset:33792
	ds_read_b128 v[194:197], v148 offset:32768
	ds_read_b128 v[198:201], v148 offset:33792
	ds_read_b128 v[202:205], v147 offset:32768
	ds_read_b128 v[206:209], v147 offset:33792
	s_waitcnt vmcnt(2)
	s_barrier
	s_waitcnt lgkmcnt(0)
	s_setprio 1
	v_mfma_f32_16x16x32_bf16 v[4:7], v[178:181], v[16:19], v[124:127]
	v_mfma_f32_16x16x32_bf16 v[120:123], v[182:185], v[24:27], v[4:7]
	v_mfma_f32_16x16x32_bf16 v[4:7], v[186:189], v[16:19], v[128:131]
	v_mfma_f32_16x16x32_bf16 v[124:127], v[164:167], v[24:27], v[4:7]
	v_mfma_f32_16x16x32_bf16 v[4:7], v[178:181], v[32:35], v[116:119]
	v_mfma_f32_16x16x32_bf16 v[116:119], v[182:185], v[40:43], v[4:7]
	v_mfma_f32_16x16x32_bf16 v[4:7], v[186:189], v[32:35], v[112:115]
	v_mfma_f32_16x16x32_bf16 v[112:115], v[164:167], v[40:43], v[4:7]
	v_mfma_f32_16x16x32_bf16 v[4:7], v[178:181], v[194:197], v[108:111]
	v_mfma_f32_16x16x32_bf16 v[108:111], v[182:185], v[198:201], v[4:7]
	v_mfma_f32_16x16x32_bf16 v[4:7], v[186:189], v[194:197], v[104:107]
	v_mfma_f32_16x16x32_bf16 v[12:15], v[164:167], v[198:201], v[4:7]
	v_mfma_f32_16x16x32_bf16 v[4:7], v[178:181], v[202:205], v[100:103]
	v_mfma_f32_16x16x32_bf16 v[8:11], v[182:185], v[206:209], v[4:7]
	v_mfma_f32_16x16x32_bf16 v[4:7], v[186:189], v[202:205], v[96:99]
	v_mfma_f32_16x16x32_bf16 v[4:7], v[164:167], v[206:209], v[4:7]
	s_setprio 0
	s_barrier
	ds_read_b128 v[128:131], v168
	ds_read_b128 v[222:225], v168 offset:1024
	ds_read_b128 v[226:229], v168 offset:2048
	ds_read_b128 v[230:233], v168 offset:3072
	s_waitcnt vmcnt(0)
	s_barrier
	s_waitcnt lgkmcnt(0)
	s_setprio 1
	v_mfma_f32_16x16x32_bf16 v[48:51], v[128:131], v[16:19], v[92:95]
	v_mfma_f32_16x16x32_bf16 v[16:19], v[226:229], v[16:19], v[88:91]
	v_mfma_f32_16x16x32_bf16 v[68:71], v[230:233], v[24:27], v[16:19]
	v_mfma_f32_16x16x32_bf16 v[16:19], v[128:131], v[32:35], v[84:87]
	v_mfma_f32_16x16x32_bf16 v[56:59], v[222:225], v[40:43], v[16:19]
	v_mfma_f32_16x16x32_bf16 v[16:19], v[226:229], v[32:35], v[156:159]
	v_mfma_f32_16x16x32_bf16 v[80:83], v[222:225], v[24:27], v[48:51]
	v_mfma_f32_16x16x32_bf16 v[48:51], v[230:233], v[40:43], v[16:19]
	v_mfma_f32_16x16x32_bf16 v[16:19], v[128:131], v[194:197], v[76:79]
	v_mfma_f32_16x16x32_bf16 v[40:43], v[222:225], v[198:201], v[16:19]
	v_mfma_f32_16x16x32_bf16 v[16:19], v[226:229], v[194:197], v[72:75]
	v_mfma_f32_16x16x32_bf16 v[32:35], v[230:233], v[198:201], v[16:19]
	v_mfma_f32_16x16x32_bf16 v[16:19], v[128:131], v[202:205], v[160:163]
	v_mfma_f32_16x16x32_bf16 v[24:27], v[222:225], v[206:209], v[16:19]
	v_mfma_f32_16x16x32_bf16 v[16:19], v[226:229], v[202:205], v[64:67]
	v_mfma_f32_16x16x32_bf16 v[16:19], v[230:233], v[206:209], v[16:19]
	s_setprio 0
	s_barrier
	ds_read_b128 v[64:67], v150 offset:49152
	ds_read_b128 v[156:159], v150 offset:50176
	ds_read_b128 v[160:163], v149 offset:49152
	ds_read_b128 v[194:197], v149 offset:50176
	ds_read_b128 v[198:201], v148 offset:49152
	ds_read_b128 v[148:151], v148 offset:50176
	ds_read_b128 v[202:205], v147 offset:49152
	ds_read_b128 v[206:209], v147 offset:50176
	s_barrier
	s_waitcnt lgkmcnt(0)
	s_setprio 1
	v_mfma_f32_16x16x32_bf16 v[60:63], v[178:181], v[64:67], v[60:63]
	v_mfma_f32_16x16x32_bf16 v[52:55], v[178:181], v[160:163], v[52:55]
	v_mfma_f32_16x16x32_bf16 v[44:47], v[178:181], v[198:201], v[44:47]
	v_mfma_f32_16x16x32_bf16 v[36:39], v[178:181], v[202:205], v[36:39]
	v_mfma_f32_16x16x32_bf16 v[104:107], v[182:185], v[156:159], v[60:63]
	v_mfma_f32_16x16x32_bf16 v[60:63], v[186:189], v[64:67], v[210:213]
	v_mfma_f32_16x16x32_bf16 v[96:99], v[182:185], v[194:197], v[52:55]
	v_mfma_f32_16x16x32_bf16 v[52:55], v[186:189], v[160:163], v[214:217]
	v_mfma_f32_16x16x32_bf16 v[88:91], v[182:185], v[148:151], v[44:47]
	v_mfma_f32_16x16x32_bf16 v[44:47], v[186:189], v[198:201], v[218:221]
	v_mfma_f32_16x16x32_bf16 v[72:75], v[182:185], v[206:209], v[36:39]
	v_mfma_f32_16x16x32_bf16 v[36:39], v[186:189], v[202:205], v[132:135]
	v_mfma_f32_16x16x32_bf16 v[100:103], v[164:167], v[156:159], v[60:63]
	v_mfma_f32_16x16x32_bf16 v[92:95], v[164:167], v[194:197], v[52:55]
	v_mfma_f32_16x16x32_bf16 v[84:87], v[164:167], v[148:151], v[44:47]
	v_mfma_f32_16x16x32_bf16 v[60:63], v[164:167], v[206:209], v[36:39]
	s_setprio 0
	s_setprio 1
	v_mfma_f32_16x16x32_bf16 v[20:23], v[128:131], v[160:163], v[20:23]
	v_mfma_f32_16x16x32_bf16 v[52:55], v[222:225], v[194:197], v[20:23]
	v_mfma_f32_16x16x32_bf16 v[20:23], v[226:229], v[160:163], v[140:143]
	v_mfma_f32_16x16x32_bf16 v[28:31], v[128:131], v[64:67], v[28:31]
	v_mfma_f32_16x16x32_bf16 v[44:47], v[230:233], v[194:197], v[20:23]
	v_mfma_f32_16x16x32_bf16 v[20:23], v[128:131], v[198:201], v[152:155]
	v_mfma_f32_16x16x32_bf16 v[76:79], v[222:225], v[156:159], v[28:31]
	v_mfma_f32_16x16x32_bf16 v[28:31], v[226:229], v[64:67], v[136:139]
	v_mfma_f32_16x16x32_bf16 v[36:39], v[222:225], v[148:151], v[20:23]
	v_mfma_f32_16x16x32_bf16 v[20:23], v[226:229], v[198:201], v[170:173]
	v_mfma_f32_16x16x32_bf16 v[64:67], v[230:233], v[156:159], v[28:31]
	v_mfma_f32_16x16x32_bf16 v[28:31], v[230:233], v[148:151], v[20:23]
	v_mfma_f32_16x16x32_bf16 v[20:23], v[128:131], v[202:205], v[174:177]
	v_mfma_f32_16x16x32_bf16 v[0:3], v[226:229], v[202:205], v[0:3]
	v_mfma_f32_16x16x32_bf16 v[20:23], v[222:225], v[206:209], v[20:23]
	v_mfma_f32_16x16x32_bf16 v[0:3], v[230:233], v[206:209], v[0:3]
	s_setprio 0
	v_readlane_b32 s30, v253, 16
	v_readlane_b32 s31, v253, 17
	s_andn2_b64 vcc, exec, s[30:31]
	s_barrier
	s_cbranch_vccnz .LBB0_999
	s_barrier
	s_branch .LBB0_999
